# K-loop diet: removed per-segment s_setprio flips, merged/dropped redundant waitcnts, removed s_nop after m0 writes by reordering
# speedup vs baseline: 1.0171x; 1.0171x over previous
; #define PG8_STAGE(bufoff, gbase, voff) do { _Pragma("unroll") for (int _i = 0; _i < 2; ++_i) \
;         __builtin_amdgcn_global_load_lds((const unsigned*)((const char*)(gbase) + (voff)[_i]), (LAS unsigned*)(lds + (bufoff) + ldsw + _i * 8192), 16, 0, 0); } while (0)
; #define PG8_LDA(dst, b, h) do { _Pragma("unroll") for (int m = 0; m < 4; ++m) _Pragma("unroll") for (int k = 0; k < 2; ++k) dst[m][k] = *(const LAS bf16x8*)(lds + PG8_SA(b, h) + aoff + m * 2048 + k * 1024); } while (0)
; #define PG8_LDB(dst, b, h) do { _Pragma("unroll") for (int n = 0; n < 2; ++n) _Pragma("unroll") for (int k = 0; k < 2; ++k) dst[n][k] = *(const LAS bf16x8*)(lds + PG8_SB(b, h) + boff + n * 2048 + k * 1024); } while (0)
; #define PG8_MMA(ai, bj, At, Bt) do { __builtin_amdgcn_s_setprio(1); _Pragma("unroll") for (int m = 0; m < 4; ++m) _Pragma("unroll") for (int n = 0; n < 2; ++n) _Pragma("unroll") for (int k = 0; k < 2; ++k) \
;         acc[ai][bj][m][n] = __builtin_amdgcn_mfma_f32_16x16x32_bf16(Bt[n][k], At[m][k], acc[ai][bj][m][n], 0, 0, 0); __builtin_amdgcn_s_setprio(0); } while (0)
; #define PG8_WAIT_V(n) asm volatile("s_waitcnt vmcnt(" #n ")" ::: "memory")
; #define PG8_WAIT_L(n) asm volatile("s_waitcnt lgkmcnt(" #n ")" ::: "memory")
; #define PG8_BAR __builtin_amdgcn_s_barrier()
; #define PG8_SCHED __builtin_amdgcn_sched_barrier(0)
; template <class Epi, class Sched, bool ALIGN_EPI>
; __device__ __forceinline__ void gemm_phase(LAS unsigned char* lds, const Gemm g, const Sched& S, const Epi& E) {
;     ...
;             const bool last = (t == nt - 2);
;             const char* a1 = cA + (size_t)(t + 1) * kstep;
;             const char* a2 = last ? nA : cA + (size_t)(t + 2) * kstep; const char* b2 = last ? nB : cB + (size_t)(t + 2) * kstep;
;             const char* a3 = a2 + kstep; const char* b3 = b2 + kstep;
;             PG8_LDB(B0, 0, 0); PG8_LDB(B1, 0, 1); PG8_SCHED; PG8_LDA(At, 0, 0); PG8_STAGE(PG8_SA(1, 1), a1 + hA, voffA);
;             PG8_WAIT_V(8); PG8_WAIT_L(0); PG8_BAR; PG8_MMA(0, 0, At, B0); PG8_MMA(0, 1, At, B1); PG8_BAR; PG8_SCHED;
;             PG8_LDA(At, 0, 1); PG8_STAGE(PG8_SB(0, 0), b2, voffB); PG8_STAGE(PG8_SB(0, 1), b2 + hB, voffB); PG8_STAGE(PG8_SA(0, 0), a2, voffA);
;             PG8_WAIT_V(8); PG8_WAIT_L(0); PG8_BAR; PG8_MMA(1, 0, At, B0); PG8_MMA(1, 1, At, B1); PG8_BAR; PG8_SCHED;
.LBB0_242:
	ds_read_b128 v[140:143], v137
	ds_read_b128 v[152:155], v137 offset:1024
	ds_read_b128 v[156:159], v137 offset:2048
	ds_read_b128 v[160:163], v137 offset:3072
	ds_read_b128 v[164:167], v138
	ds_read_b128 v[168:171], v138 offset:1024
	ds_read_b128 v[172:175], v138 offset:2048
	ds_read_b128 v[176:179], v138 offset:3072
	s_add_u32 s18, s66, 0xfff80080
	s_addc_u32 s19, s67, -1
	s_cmp_eq_u32 s72, 28
	s_cselect_b32 s71, vcc_lo, s19
	s_cselect_b32 s70, vcc_hi, s18
	s_cselect_b32 s69, s41, s45
	s_cselect_b32 s68, s87, s44
	v_lshl_add_u64 v[132:133], s[66:67], 0, v[128:129]
	s_add_i32 m0, s81, 0xc000
	ds_read_b128 v[192:195], v139
	ds_read_b128 v[196:199], v139 offset:1024
	ds_read_b128 v[200:203], v139 offset:2048
	ds_read_b128 v[204:207], v139 offset:3072
	ds_read_b128 v[208:211], v139 offset:4096
	ds_read_b128 v[212:215], v139 offset:5120
	ds_read_b128 v[216:219], v139 offset:6144
	ds_read_b128 v[222:225], v139 offset:7168
	global_load_lds_dwordx4 v[132:133], off
	s_add_i32 m0, s81, 0xe000
	v_lshl_add_u64 v[132:133], s[66:67], 0, v[130:131]
	global_load_lds_dwordx4 v[132:133], off
	s_waitcnt vmcnt(8) lgkmcnt(0)
	s_barrier
	v_mfma_f32_16x16x32_bf16 v[124:127], v[140:143], v[192:195], v[124:127]
	v_mfma_f32_16x16x32_bf16 v[120:123], v[156:159], v[192:195], v[120:123]
	v_mfma_f32_16x16x32_bf16 v[112:115], v[140:143], v[200:203], v[112:115]
	v_mfma_f32_16x16x32_bf16 v[104:107], v[156:159], v[200:203], v[104:107]
	v_mfma_f32_16x16x32_bf16 v[96:99], v[140:143], v[208:211], v[96:99]
	v_mfma_f32_16x16x32_bf16 v[88:91], v[156:159], v[208:211], v[88:91]
	v_mfma_f32_16x16x32_bf16 v[80:83], v[140:143], v[216:219], v[80:83]
	v_mfma_f32_16x16x32_bf16 v[72:75], v[156:159], v[216:219], v[72:75]
	v_mfma_f32_16x16x32_bf16 v[124:127], v[152:155], v[196:199], v[124:127]
	v_mfma_f32_16x16x32_bf16 v[120:123], v[160:163], v[196:199], v[120:123]
	v_mfma_f32_16x16x32_bf16 v[112:115], v[152:155], v[204:207], v[112:115]
	v_mfma_f32_16x16x32_bf16 v[104:107], v[160:163], v[204:207], v[104:107]
	v_mfma_f32_16x16x32_bf16 v[96:99], v[152:155], v[212:215], v[96:99]
	v_mfma_f32_16x16x32_bf16 v[88:91], v[160:163], v[212:215], v[88:91]
	v_mfma_f32_16x16x32_bf16 v[80:83], v[152:155], v[222:225], v[80:83]
	v_mfma_f32_16x16x32_bf16 v[72:75], v[160:163], v[222:225], v[72:75]
	v_mfma_f32_16x16x32_bf16 v[116:119], v[164:167], v[192:195], v[116:119]
	v_mfma_f32_16x16x32_bf16 v[108:111], v[172:175], v[192:195], v[108:111]
	v_mfma_f32_16x16x32_bf16 v[100:103], v[164:167], v[200:203], v[100:103]
	v_mfma_f32_16x16x32_bf16 v[92:95], v[172:175], v[200:203], v[92:95]
	v_mfma_f32_16x16x32_bf16 v[84:87], v[164:167], v[208:211], v[84:87]
	v_mfma_f32_16x16x32_bf16 v[76:79], v[172:175], v[208:211], v[76:79]
	v_mfma_f32_16x16x32_bf16 v[68:71], v[164:167], v[216:219], v[68:71]
	v_mfma_f32_16x16x32_bf16 v[64:67], v[172:175], v[216:219], v[64:67]
	v_mfma_f32_16x16x32_bf16 v[116:119], v[168:171], v[196:199], v[116:119]
	v_mfma_f32_16x16x32_bf16 v[108:111], v[176:179], v[196:199], v[108:111]
	v_mfma_f32_16x16x32_bf16 v[100:103], v[168:171], v[204:207], v[100:103]
	v_mfma_f32_16x16x32_bf16 v[92:95], v[176:179], v[204:207], v[92:95]
	v_mfma_f32_16x16x32_bf16 v[84:87], v[168:171], v[212:215], v[84:87]
	v_mfma_f32_16x16x32_bf16 v[76:79], v[176:179], v[212:215], v[76:79]
	v_mfma_f32_16x16x32_bf16 v[68:71], v[168:171], v[222:225], v[68:71]
	v_mfma_f32_16x16x32_bf16 v[64:67], v[176:179], v[222:225], v[64:67]
	s_barrier
	s_add_i32 s18, s92, s78
	v_lshl_add_u64 v[132:133], s[68:69], 0, v[144:145]
	s_mov_b32 m0, s18
	ds_read_b128 v[192:195], v139 offset:16384
	ds_read_b128 v[196:199], v139 offset:17408
	ds_read_b128 v[200:203], v139 offset:18432
	ds_read_b128 v[204:207], v139 offset:19456
	ds_read_b128 v[208:211], v139 offset:20480
	ds_read_b128 v[212:215], v139 offset:21504
	ds_read_b128 v[216:219], v139 offset:22528
	ds_read_b128 v[222:225], v139 offset:23552
	global_load_lds_dwordx4 v[132:133], off
	s_add_i32 m0, s18, 0x2000
	s_add_u32 s46, s68, 0x80000
	v_lshl_add_u64 v[226:227], s[68:69], 0, v[146:147]
	s_addc_u32 s47, s69, 0
	s_add_i32 s18, s93, s78
	global_load_lds_dwordx4 v[226:227], off
	v_lshl_add_u64 v[228:229], s[46:47], 0, v[144:145]
	s_mov_b32 m0, s18
	v_lshl_add_u64 v[230:231], s[70:71], 0, v[150:151]
	global_load_lds_dwordx4 v[228:229], off
	s_add_i32 m0, s18, 0x2000
	v_lshl_add_u64 v[228:229], s[46:47], 0, v[146:147]
	global_load_lds_dwordx4 v[228:229], off
	s_mov_b32 m0, s81
	v_lshl_add_u64 v[228:229], s[70:71], 0, v[148:149]
	global_load_lds_dwordx4 v[228:229], off
	s_mov_b32 m0, s82
	s_nop 0
	global_load_lds_dwordx4 v[230:231], off
	s_waitcnt vmcnt(8) lgkmcnt(0)
	s_barrier
; #define PG8_STAGE(bufoff, gbase, voff) do { _Pragma("unroll") for (int _i = 0; _i < 2; ++_i) \
;         __builtin_amdgcn_global_load_lds((const unsigned*)((const char*)(gbase) + (voff)[_i]), (LAS unsigned*)(lds + (bufoff) + ldsw + _i * 8192), 16, 0, 0); } while (0)
; #define PG8_LDA(dst, b, h) do { _Pragma("unroll") for (int m = 0; m < 4; ++m) _Pragma("unroll") for (int k = 0; k < 2; ++k) dst[m][k] = *(const LAS bf16x8*)(lds + PG8_SA(b, h) + aoff + m * 2048 + k * 1024); } while (0)
; #define PG8_LDB(dst, b, h) do { _Pragma("unroll") for (int n = 0; n < 2; ++n) _Pragma("unroll") for (int k = 0; k < 2; ++k) dst[n][k] = *(const LAS bf16x8*)(lds + PG8_SB(b, h) + boff + n * 2048 + k * 1024); } while (0)
; #define PG8_MMA(ai, bj, At, Bt) do { __builtin_amdgcn_s_setprio(1); _Pragma("unroll") for (int m = 0; m < 4; ++m) _Pragma("unroll") for (int n = 0; n < 2; ++n) _Pragma("unroll") for (int k = 0; k < 2; ++k) \
;         acc[ai][bj][m][n] = __builtin_amdgcn_mfma_f32_16x16x32_bf16(Bt[n][k], At[m][k], acc[ai][bj][m][n], 0, 0, 0); __builtin_amdgcn_s_setprio(0); } while (0)
; #define PG8_WAIT_V(n) asm volatile("s_waitcnt vmcnt(" #n ")" ::: "memory")
; #define PG8_WAIT_L(n) asm volatile("s_waitcnt lgkmcnt(" #n ")" ::: "memory")
; #define PG8_BAR __builtin_amdgcn_s_barrier()
; #define PG8_SCHED __builtin_amdgcn_sched_barrier(0)
; template <class Epi, class Sched, bool ALIGN_EPI>
; __device__ __forceinline__ void gemm_phase(LAS unsigned char* lds, const Gemm g, const Sched& S, const Epi& E) {
;     ...
;             PG8_WAIT_V(8); PG8_WAIT_L(0); PG8_BAR; PG8_MMA(1, 0, At, B0); PG8_MMA(1, 1, At, B1); PG8_BAR; PG8_SCHED;
;             PG8_LDB(B0, 1, 0); PG8_LDB(B1, 1, 1); PG8_SCHED; PG8_LDA(At, 1, 0); PG8_STAGE(PG8_SA(0, 1), a2 + hA, voffA);
;             PG8_WAIT_V(8); PG8_WAIT_L(0); PG8_BAR; PG8_MMA(0, 0, At, B0); PG8_MMA(0, 1, At, B1); PG8_BAR; PG8_SCHED;
	v_mfma_f32_16x16x32_bf16 v[60:63], v[140:143], v[192:195], v[60:63]
	v_mfma_f32_16x16x32_bf16 v[56:59], v[156:159], v[192:195], v[56:59]
	v_mfma_f32_16x16x32_bf16 v[52:55], v[140:143], v[200:203], v[52:55]
	v_mfma_f32_16x16x32_bf16 v[44:47], v[156:159], v[200:203], v[44:47]
	v_mfma_f32_16x16x32_bf16 v[36:39], v[140:143], v[208:211], v[36:39]
	v_mfma_f32_16x16x32_bf16 v[28:31], v[156:159], v[208:211], v[28:31]
	v_mfma_f32_16x16x32_bf16 v[20:23], v[140:143], v[216:219], v[20:23]
	v_mfma_f32_16x16x32_bf16 v[12:15], v[156:159], v[216:219], v[12:15]
	v_mfma_f32_16x16x32_bf16 v[60:63], v[152:155], v[196:199], v[60:63]
	v_mfma_f32_16x16x32_bf16 v[56:59], v[160:163], v[196:199], v[56:59]
	v_mfma_f32_16x16x32_bf16 v[52:55], v[152:155], v[204:207], v[52:55]
	v_mfma_f32_16x16x32_bf16 v[44:47], v[160:163], v[204:207], v[44:47]
	v_mfma_f32_16x16x32_bf16 v[36:39], v[152:155], v[212:215], v[36:39]
	v_mfma_f32_16x16x32_bf16 v[28:31], v[160:163], v[212:215], v[28:31]
	v_mfma_f32_16x16x32_bf16 v[20:23], v[152:155], v[222:225], v[20:23]
	v_mfma_f32_16x16x32_bf16 v[12:15], v[160:163], v[222:225], v[12:15]
	v_mfma_f32_16x16x32_bf16 v[48:51], v[164:167], v[192:195], v[48:51]
	v_mfma_f32_16x16x32_bf16 v[40:43], v[172:175], v[192:195], v[40:43]
	v_mfma_f32_16x16x32_bf16 v[32:35], v[164:167], v[200:203], v[32:35]
	v_mfma_f32_16x16x32_bf16 v[24:27], v[172:175], v[200:203], v[24:27]
	v_mfma_f32_16x16x32_bf16 v[16:19], v[164:167], v[208:211], v[16:19]
	v_mfma_f32_16x16x32_bf16 v[8:11], v[172:175], v[208:211], v[8:11]
	v_mfma_f32_16x16x32_bf16 v[4:7], v[164:167], v[216:219], v[4:7]
	v_mfma_f32_16x16x32_bf16 v[0:3], v[172:175], v[216:219], v[0:3]
	v_mfma_f32_16x16x32_bf16 v[48:51], v[168:171], v[196:199], v[48:51]
	v_mfma_f32_16x16x32_bf16 v[40:43], v[176:179], v[196:199], v[40:43]
	v_mfma_f32_16x16x32_bf16 v[32:35], v[168:171], v[204:207], v[32:35]
	v_mfma_f32_16x16x32_bf16 v[24:27], v[176:179], v[204:207], v[24:27]
	v_mfma_f32_16x16x32_bf16 v[16:19], v[168:171], v[212:215], v[16:19]
	v_mfma_f32_16x16x32_bf16 v[8:11], v[176:179], v[212:215], v[8:11]
	v_mfma_f32_16x16x32_bf16 v[4:7], v[168:171], v[222:225], v[4:7]
	v_mfma_f32_16x16x32_bf16 v[0:3], v[176:179], v[222:225], v[0:3]
	s_barrier
	s_add_i32 s18, 0, 0x18000
	s_add_i32 s19, 0, 0x1c000
	v_add_u32_e32 v160, s18, v135
	v_add_u32_e32 v176, s19, v135
	ds_read_b128 v[140:143], v160
	ds_read_b128 v[152:155], v160 offset:1024
	ds_read_b128 v[156:159], v160 offset:2048
	ds_read_b128 v[160:163], v160 offset:3072
	ds_read_b128 v[164:167], v176
	ds_read_b128 v[168:171], v176 offset:1024
	ds_read_b128 v[172:175], v176 offset:2048
	ds_read_b128 v[176:179], v176 offset:3072
	s_add_u32 s46, s70, 0x80000
	s_addc_u32 s47, s71, 0
	s_mov_b32 m0, s83
	v_lshl_add_u64 v[232:233], s[46:47], 0, v[148:149]
	ds_read_b128 v[192:195], v139 offset:32768
	ds_read_b128 v[196:199], v139 offset:33792
	ds_read_b128 v[200:203], v139 offset:34816
	ds_read_b128 v[204:207], v139 offset:35840
	ds_read_b128 v[208:211], v139 offset:36864
	ds_read_b128 v[212:215], v139 offset:37888
	ds_read_b128 v[216:219], v139 offset:38912
	ds_read_b128 v[222:225], v139 offset:39936
	global_load_lds_dwordx4 v[232:233], off
	s_mov_b32 m0, s84
	v_lshl_add_u64 v[232:233], s[46:47], 0, v[150:151]
	global_load_lds_dwordx4 v[232:233], off
	s_waitcnt vmcnt(8) lgkmcnt(0)
	s_barrier
	v_mfma_f32_16x16x32_bf16 v[124:127], v[140:143], v[192:195], v[124:127]
	v_mfma_f32_16x16x32_bf16 v[120:123], v[156:159], v[192:195], v[120:123]
	v_mfma_f32_16x16x32_bf16 v[112:115], v[140:143], v[200:203], v[112:115]
	v_mfma_f32_16x16x32_bf16 v[104:107], v[156:159], v[200:203], v[104:107]
	v_mfma_f32_16x16x32_bf16 v[96:99], v[140:143], v[208:211], v[96:99]
	v_mfma_f32_16x16x32_bf16 v[88:91], v[156:159], v[208:211], v[88:91]
	v_mfma_f32_16x16x32_bf16 v[80:83], v[140:143], v[216:219], v[80:83]
	v_mfma_f32_16x16x32_bf16 v[72:75], v[156:159], v[216:219], v[72:75]
	v_mfma_f32_16x16x32_bf16 v[124:127], v[152:155], v[196:199], v[124:127]
	v_mfma_f32_16x16x32_bf16 v[120:123], v[160:163], v[196:199], v[120:123]
	v_mfma_f32_16x16x32_bf16 v[112:115], v[152:155], v[204:207], v[112:115]
	v_mfma_f32_16x16x32_bf16 v[104:107], v[160:163], v[204:207], v[104:107]
	v_mfma_f32_16x16x32_bf16 v[96:99], v[152:155], v[212:215], v[96:99]
	v_mfma_f32_16x16x32_bf16 v[88:91], v[160:163], v[212:215], v[88:91]
	v_mfma_f32_16x16x32_bf16 v[80:83], v[152:155], v[222:225], v[80:83]
	v_mfma_f32_16x16x32_bf16 v[72:75], v[160:163], v[222:225], v[72:75]
	v_mfma_f32_16x16x32_bf16 v[116:119], v[164:167], v[192:195], v[116:119]
	v_mfma_f32_16x16x32_bf16 v[108:111], v[172:175], v[192:195], v[108:111]
	v_mfma_f32_16x16x32_bf16 v[100:103], v[164:167], v[200:203], v[100:103]
	v_mfma_f32_16x16x32_bf16 v[92:95], v[172:175], v[200:203], v[92:95]
	v_mfma_f32_16x16x32_bf16 v[84:87], v[164:167], v[208:211], v[84:87]
	v_mfma_f32_16x16x32_bf16 v[76:79], v[172:175], v[208:211], v[76:79]
	v_mfma_f32_16x16x32_bf16 v[68:71], v[164:167], v[216:219], v[68:71]
	v_mfma_f32_16x16x32_bf16 v[64:67], v[172:175], v[216:219], v[64:67]
	v_mfma_f32_16x16x32_bf16 v[116:119], v[168:171], v[196:199], v[116:119]
	v_mfma_f32_16x16x32_bf16 v[108:111], v[176:179], v[196:199], v[108:111]
	v_mfma_f32_16x16x32_bf16 v[100:103], v[168:171], v[204:207], v[100:103]
	v_mfma_f32_16x16x32_bf16 v[92:95], v[176:179], v[204:207], v[92:95]
	v_mfma_f32_16x16x32_bf16 v[84:87], v[168:171], v[212:215], v[84:87]
	v_mfma_f32_16x16x32_bf16 v[76:79], v[176:179], v[212:215], v[76:79]
	v_mfma_f32_16x16x32_bf16 v[68:71], v[168:171], v[222:225], v[68:71]
	v_mfma_f32_16x16x32_bf16 v[64:67], v[176:179], v[222:225], v[64:67]
	s_barrier
; #define PG8_STAGE(bufoff, gbase, voff) do { _Pragma("unroll") for (int _i = 0; _i < 2; ++_i) \
;         __builtin_amdgcn_global_load_lds((const unsigned*)((const char*)(gbase) + (voff)[_i]), (LAS unsigned*)(lds + (bufoff) + ldsw + _i * 8192), 16, 0, 0); } while (0)
; #define PG8_LDA(dst, b, h) do { _Pragma("unroll") for (int m = 0; m < 4; ++m) _Pragma("unroll") for (int k = 0; k < 2; ++k) dst[m][k] = *(const LAS bf16x8*)(lds + PG8_SA(b, h) + aoff + m * 2048 + k * 1024); } while (0)
; #define PG8_MMA(ai, bj, At, Bt) do { __builtin_amdgcn_s_setprio(1); _Pragma("unroll") for (int m = 0; m < 4; ++m) _Pragma("unroll") for (int n = 0; n < 2; ++n) _Pragma("unroll") for (int k = 0; k < 2; ++k) \
;         acc[ai][bj][m][n] = __builtin_amdgcn_mfma_f32_16x16x32_bf16(Bt[n][k], At[m][k], acc[ai][bj][m][n], 0, 0, 0); __builtin_amdgcn_s_setprio(0); } while (0)
; #define PG8_WAIT_V(n) asm volatile("s_waitcnt vmcnt(" #n ")" ::: "memory")
; #define PG8_WAIT_L(n) asm volatile("s_waitcnt lgkmcnt(" #n ")" ::: "memory")
; #define PG8_BAR __builtin_amdgcn_s_barrier()
; #define PG8_SCHED __builtin_amdgcn_sched_barrier(0)
; template <class Epi, class Sched, bool ALIGN_EPI>
; __device__ __forceinline__ void gemm_phase(LAS unsigned char* lds, const Gemm g, const Sched& S, const Epi& E) {
;     ...
;             PG8_LDA(At, 1, 1); PG8_STAGE(PG8_SB(1, 0), b3, voffB); PG8_STAGE(PG8_SB(1, 1), b3 + hB, voffB); PG8_STAGE(PG8_SA(1, 0), a3, voffA);
;             PG8_WAIT_V(8); PG8_WAIT_L(0); PG8_BAR; PG8_MMA(1, 0, At, B0); PG8_MMA(1, 1, At, B1); PG8_BAR; PG8_SCHED;
;         }
;         if constexpr (ALIGN_EPI) { if (wr == 0) PG8_BAR; }
	s_add_i32 s18, s18, s78
	v_lshl_add_u64 v[132:133], v[132:133], 0, s[24:25]
	s_mov_b32 m0, s18
	ds_read_b128 v[192:195], v139 offset:49152
	ds_read_b128 v[196:199], v139 offset:50176
	ds_read_b128 v[200:203], v139 offset:51200
	ds_read_b128 v[204:207], v139 offset:52224
	ds_read_b128 v[208:211], v139 offset:53248
	ds_read_b128 v[212:215], v139 offset:54272
	ds_read_b128 v[216:219], v139 offset:55296
	ds_read_b128 v[222:225], v139 offset:56320
	global_load_lds_dwordx4 v[132:133], off
	s_add_i32 m0, s18, 0x2000
	s_add_u32 s46, s68, 0x80080
	v_lshl_add_u64 v[132:133], v[226:227], 0, s[24:25]
	s_addc_u32 s47, s69, 0
	s_add_i32 s18, s19, s78
	global_load_lds_dwordx4 v[132:133], off
	s_mov_b32 m0, s18
	v_lshl_add_u64 v[132:133], s[46:47], 0, v[144:145]
	global_load_lds_dwordx4 v[132:133], off
	s_add_i32 m0, s18, 0x2000
	v_lshl_add_u64 v[132:133], s[46:47], 0, v[146:147]
	global_load_lds_dwordx4 v[132:133], off
	s_mov_b32 m0, s88
	v_lshl_add_u64 v[132:133], v[228:229], 0, s[24:25]
	global_load_lds_dwordx4 v[132:133], off
	s_mov_b32 m0, s89
	v_lshl_add_u64 v[132:133], v[230:231], 0, s[24:25]
	global_load_lds_dwordx4 v[132:133], off
	s_waitcnt vmcnt(8) lgkmcnt(0)
	s_barrier
	v_mfma_f32_16x16x32_bf16 v[60:63], v[140:143], v[192:195], v[60:63]
	v_mfma_f32_16x16x32_bf16 v[56:59], v[156:159], v[192:195], v[56:59]
	v_mfma_f32_16x16x32_bf16 v[52:55], v[140:143], v[200:203], v[52:55]
	v_mfma_f32_16x16x32_bf16 v[44:47], v[156:159], v[200:203], v[44:47]
	v_mfma_f32_16x16x32_bf16 v[36:39], v[140:143], v[208:211], v[36:39]
	v_mfma_f32_16x16x32_bf16 v[28:31], v[156:159], v[208:211], v[28:31]
	v_mfma_f32_16x16x32_bf16 v[20:23], v[140:143], v[216:219], v[20:23]
	v_mfma_f32_16x16x32_bf16 v[12:15], v[156:159], v[216:219], v[12:15]
	v_mfma_f32_16x16x32_bf16 v[60:63], v[152:155], v[196:199], v[60:63]
	v_mfma_f32_16x16x32_bf16 v[56:59], v[160:163], v[196:199], v[56:59]
	v_mfma_f32_16x16x32_bf16 v[52:55], v[152:155], v[204:207], v[52:55]
	v_mfma_f32_16x16x32_bf16 v[44:47], v[160:163], v[204:207], v[44:47]
	v_mfma_f32_16x16x32_bf16 v[36:39], v[152:155], v[212:215], v[36:39]
	v_mfma_f32_16x16x32_bf16 v[28:31], v[160:163], v[212:215], v[28:31]
	v_mfma_f32_16x16x32_bf16 v[20:23], v[152:155], v[222:225], v[20:23]
	v_mfma_f32_16x16x32_bf16 v[12:15], v[160:163], v[222:225], v[12:15]
	v_mfma_f32_16x16x32_bf16 v[48:51], v[164:167], v[192:195], v[48:51]
	v_mfma_f32_16x16x32_bf16 v[40:43], v[172:175], v[192:195], v[40:43]
	v_mfma_f32_16x16x32_bf16 v[32:35], v[164:167], v[200:203], v[32:35]
	v_mfma_f32_16x16x32_bf16 v[24:27], v[172:175], v[200:203], v[24:27]
	v_mfma_f32_16x16x32_bf16 v[16:19], v[164:167], v[208:211], v[16:19]
	v_mfma_f32_16x16x32_bf16 v[8:11], v[172:175], v[208:211], v[8:11]
	v_mfma_f32_16x16x32_bf16 v[4:7], v[164:167], v[216:219], v[4:7]
	v_mfma_f32_16x16x32_bf16 v[0:3], v[172:175], v[216:219], v[0:3]
	v_mfma_f32_16x16x32_bf16 v[48:51], v[168:171], v[196:199], v[48:51]
	v_mfma_f32_16x16x32_bf16 v[40:43], v[176:179], v[196:199], v[40:43]
	v_mfma_f32_16x16x32_bf16 v[32:35], v[168:171], v[204:207], v[32:35]
	v_mfma_f32_16x16x32_bf16 v[24:27], v[176:179], v[204:207], v[24:27]
	v_mfma_f32_16x16x32_bf16 v[16:19], v[168:171], v[212:215], v[16:19]
	v_mfma_f32_16x16x32_bf16 v[8:11], v[176:179], v[212:215], v[8:11]
	v_mfma_f32_16x16x32_bf16 v[4:7], v[168:171], v[222:225], v[4:7]
	v_mfma_f32_16x16x32_bf16 v[0:3], v[176:179], v[222:225], v[0:3]
	s_barrier
	s_add_i32 s72, s72, 2
	s_add_u32 s66, s66, 0x100
	s_addc_u32 s67, s67, 0
	s_add_u32 s44, s44, 0x100
	s_addc_u32 s45, s45, 0
	s_cmp_gt_u32 s72, 29
	s_cbranch_scc0 .LBB0_242
	s_and_b64 vcc, exec, s[26:27]
	s_cbranch_vccz .LBB0_245
	s_barrier

; #define PG8_STAGE(bufoff, gbase, voff) do { _Pragma("unroll") for (int _i = 0; _i < 2; ++_i) \
;         __builtin_amdgcn_global_load_lds((const unsigned*)((const char*)(gbase) + (voff)[_i]), (LAS unsigned*)(lds + (bufoff) + ldsw + _i * 8192), 16, 0, 0); } while (0)
; #define PG8_LDA(dst, b, h) do { _Pragma("unroll") for (int m = 0; m < 4; ++m) _Pragma("unroll") for (int k = 0; k < 2; ++k) dst[m][k] = *(const LAS bf16x8*)(lds + PG8_SA(b, h) + aoff + m * 2048 + k * 1024); } while (0)
; #define PG8_LDB(dst, b, h) do { _Pragma("unroll") for (int n = 0; n < 2; ++n) _Pragma("unroll") for (int k = 0; k < 2; ++k) dst[n][k] = *(const LAS bf16x8*)(lds + PG8_SB(b, h) + boff + n * 2048 + k * 1024); } while (0)
; #define PG8_MMA(ai, bj, At, Bt) do { __builtin_amdgcn_s_setprio(1); _Pragma("unroll") for (int m = 0; m < 4; ++m) _Pragma("unroll") for (int n = 0; n < 2; ++n) _Pragma("unroll") for (int k = 0; k < 2; ++k) \
;         acc[ai][bj][m][n] = __builtin_amdgcn_mfma_f32_16x16x32_bf16(Bt[n][k], At[m][k], acc[ai][bj][m][n], 0, 0, 0); __builtin_amdgcn_s_setprio(0); } while (0)
; #define PG8_WAIT_V(n) asm volatile("s_waitcnt vmcnt(" #n ")" ::: "memory")
; #define PG8_WAIT_L(n) asm volatile("s_waitcnt lgkmcnt(" #n ")" ::: "memory")
; #define PG8_BAR __builtin_amdgcn_s_barrier()
; #define PG8_SCHED __builtin_amdgcn_sched_barrier(0)
; template <class Epi, class Sched, bool ALIGN_EPI>
; __device__ __forceinline__ void gemm_phase(LAS unsigned char* lds, const Gemm g, const Sched& S, const Epi& E) {
;     ...
;             const bool last = (t == nt - 2);
;             const char* a1 = cA + (size_t)(t + 1) * kstep;
;             const char* a2 = last ? nA : cA + (size_t)(t + 2) * kstep; const char* b2 = last ? nB : cB + (size_t)(t + 2) * kstep;
;             const char* a3 = a2 + kstep; const char* b3 = b2 + kstep;
;             PG8_LDB(B0, 0, 0); PG8_LDB(B1, 0, 1); PG8_SCHED; PG8_LDA(At, 0, 0); PG8_STAGE(PG8_SA(1, 1), a1 + hA, voffA);
;             PG8_WAIT_V(8); PG8_WAIT_L(0); PG8_BAR; PG8_MMA(0, 0, At, B0); PG8_MMA(0, 1, At, B1); PG8_BAR; PG8_SCHED;
;             PG8_LDA(At, 0, 1); PG8_STAGE(PG8_SB(0, 0), b2, voffB); PG8_STAGE(PG8_SB(0, 1), b2 + hB, voffB); PG8_STAGE(PG8_SA(0, 0), a2, voffA);
;             PG8_WAIT_V(8); PG8_WAIT_L(0); PG8_BAR; PG8_MMA(1, 0, At, B0); PG8_MMA(1, 1, At, B1); PG8_BAR; PG8_SCHED;
.LBB0_261:
	ds_read_b128 v[128:131], v195
	ds_read_b128 v[132:135], v195 offset:1024
	ds_read_b128 v[136:139], v195 offset:2048
	ds_read_b128 v[140:143], v195 offset:3072
	ds_read_b128 v[162:165], v196
	ds_read_b128 v[166:169], v196 offset:1024
	ds_read_b128 v[170:173], v196 offset:2048
	ds_read_b128 v[174:177], v196 offset:3072
	s_add_u32 s6, s4, 0xfff80080
	s_addc_u32 s7, s5, -1
	s_cmp_eq_u32 s72, 28
	s_cselect_b32 s67, s93, s7
	s_cselect_b32 s66, s94, s6
	s_cselect_b32 s7, s43, s45
	s_cselect_b32 s6, s87, s44
	v_lshl_add_u64 v[178:179], s[4:5], 0, v[154:155]
	s_add_i32 m0, s70, 0xc000
	ds_read_b128 v[200:203], v197
	ds_read_b128 v[204:207], v197 offset:1024
	ds_read_b128 v[208:211], v197 offset:2048
	ds_read_b128 v[212:215], v197 offset:3072
	ds_read_b128 v[216:219], v197 offset:4096
	ds_read_b128 v[222:225], v197 offset:5120
	ds_read_b128 v[226:229], v197 offset:6144
	ds_read_b128 v[230:233], v197 offset:7168
	global_load_lds_dwordx4 v[178:179], off
	s_add_i32 m0, s70, 0xe000
	v_lshl_add_u64 v[178:179], s[4:5], 0, v[156:157]
	global_load_lds_dwordx4 v[178:179], off
	s_waitcnt vmcnt(8) lgkmcnt(0)
	s_barrier
	v_mfma_f32_16x16x32_bf16 v[124:127], v[128:131], v[200:203], v[124:127]
	v_mfma_f32_16x16x32_bf16 v[116:119], v[136:139], v[200:203], v[116:119]
	v_mfma_f32_16x16x32_bf16 v[108:111], v[128:131], v[208:211], v[108:111]
	v_mfma_f32_16x16x32_bf16 v[100:103], v[136:139], v[208:211], v[100:103]
	v_mfma_f32_16x16x32_bf16 v[92:95], v[128:131], v[216:219], v[92:95]
	v_mfma_f32_16x16x32_bf16 v[84:87], v[136:139], v[216:219], v[84:87]
	v_mfma_f32_16x16x32_bf16 v[76:79], v[128:131], v[226:229], v[76:79]
	v_mfma_f32_16x16x32_bf16 v[68:71], v[136:139], v[226:229], v[68:71]
	v_mfma_f32_16x16x32_bf16 v[124:127], v[132:135], v[204:207], v[124:127]
	v_mfma_f32_16x16x32_bf16 v[116:119], v[140:143], v[204:207], v[116:119]
	v_mfma_f32_16x16x32_bf16 v[108:111], v[132:135], v[212:215], v[108:111]
	v_mfma_f32_16x16x32_bf16 v[100:103], v[140:143], v[212:215], v[100:103]
	v_mfma_f32_16x16x32_bf16 v[92:95], v[132:135], v[222:225], v[92:95]
	v_mfma_f32_16x16x32_bf16 v[84:87], v[140:143], v[222:225], v[84:87]
	v_mfma_f32_16x16x32_bf16 v[76:79], v[132:135], v[230:233], v[76:79]
	v_mfma_f32_16x16x32_bf16 v[68:71], v[140:143], v[230:233], v[68:71]
	v_mfma_f32_16x16x32_bf16 v[120:123], v[162:165], v[200:203], v[120:123]
	v_mfma_f32_16x16x32_bf16 v[112:115], v[170:173], v[200:203], v[112:115]
	v_mfma_f32_16x16x32_bf16 v[104:107], v[162:165], v[208:211], v[104:107]
	v_mfma_f32_16x16x32_bf16 v[96:99], v[170:173], v[208:211], v[96:99]
	v_mfma_f32_16x16x32_bf16 v[88:91], v[162:165], v[216:219], v[88:91]
	v_mfma_f32_16x16x32_bf16 v[80:83], v[170:173], v[216:219], v[80:83]
	v_mfma_f32_16x16x32_bf16 v[72:75], v[162:165], v[226:229], v[72:75]
	v_mfma_f32_16x16x32_bf16 v[64:67], v[170:173], v[226:229], v[64:67]
	v_mfma_f32_16x16x32_bf16 v[120:123], v[166:169], v[204:207], v[120:123]
	v_mfma_f32_16x16x32_bf16 v[112:115], v[174:177], v[204:207], v[112:115]
	v_mfma_f32_16x16x32_bf16 v[104:107], v[166:169], v[212:215], v[104:107]
	v_mfma_f32_16x16x32_bf16 v[96:99], v[174:177], v[212:215], v[96:99]
	v_mfma_f32_16x16x32_bf16 v[88:91], v[166:169], v[222:225], v[88:91]
	v_mfma_f32_16x16x32_bf16 v[80:83], v[174:177], v[222:225], v[80:83]
	v_mfma_f32_16x16x32_bf16 v[72:75], v[166:169], v[230:233], v[72:75]
	v_mfma_f32_16x16x32_bf16 v[64:67], v[174:177], v[230:233], v[64:67]
	s_barrier
	s_add_i32 s18, s82, s41
	v_lshl_add_u64 v[178:179], s[6:7], 0, v[144:145]
	s_mov_b32 m0, s18
	ds_read_b128 v[200:203], v197 offset:16384
	ds_read_b128 v[204:207], v197 offset:17408
	ds_read_b128 v[208:211], v197 offset:18432
	ds_read_b128 v[212:215], v197 offset:19456
	ds_read_b128 v[216:219], v197 offset:20480
	ds_read_b128 v[222:225], v197 offset:21504
	ds_read_b128 v[226:229], v197 offset:22528
	ds_read_b128 v[230:233], v197 offset:23552
	global_load_lds_dwordx4 v[178:179], off
	s_add_i32 m0, s18, 0x2000
	s_add_u32 s46, s6, 0x80000
	v_lshl_add_u64 v[234:235], s[6:7], 0, v[146:147]
	s_addc_u32 s47, s7, 0
	s_add_i32 s18, s83, s41
	global_load_lds_dwordx4 v[234:235], off
	v_lshl_add_u64 v[236:237], s[46:47], 0, v[144:145]
	s_mov_b32 m0, s18
	v_lshl_add_u64 v[238:239], s[66:67], 0, v[150:151]
	global_load_lds_dwordx4 v[236:237], off
	s_add_i32 m0, s18, 0x2000
	v_lshl_add_u64 v[236:237], s[46:47], 0, v[146:147]
	global_load_lds_dwordx4 v[236:237], off
	s_mov_b32 m0, s70
	v_lshl_add_u64 v[236:237], s[66:67], 0, v[148:149]
	global_load_lds_dwordx4 v[236:237], off
	s_mov_b32 m0, s71
	s_nop 0
	global_load_lds_dwordx4 v[238:239], off
	s_waitcnt vmcnt(8) lgkmcnt(0)
	s_barrier
; #define PG8_STAGE(bufoff, gbase, voff) do { _Pragma("unroll") for (int _i = 0; _i < 2; ++_i) \
;         __builtin_amdgcn_global_load_lds((const unsigned*)((const char*)(gbase) + (voff)[_i]), (LAS unsigned*)(lds + (bufoff) + ldsw + _i * 8192), 16, 0, 0); } while (0)
; #define PG8_LDA(dst, b, h) do { _Pragma("unroll") for (int m = 0; m < 4; ++m) _Pragma("unroll") for (int k = 0; k < 2; ++k) dst[m][k] = *(const LAS bf16x8*)(lds + PG8_SA(b, h) + aoff + m * 2048 + k * 1024); } while (0)
; #define PG8_LDB(dst, b, h) do { _Pragma("unroll") for (int n = 0; n < 2; ++n) _Pragma("unroll") for (int k = 0; k < 2; ++k) dst[n][k] = *(const LAS bf16x8*)(lds + PG8_SB(b, h) + boff + n * 2048 + k * 1024); } while (0)
; #define PG8_MMA(ai, bj, At, Bt) do { __builtin_amdgcn_s_setprio(1); _Pragma("unroll") for (int m = 0; m < 4; ++m) _Pragma("unroll") for (int n = 0; n < 2; ++n) _Pragma("unroll") for (int k = 0; k < 2; ++k) \
;         acc[ai][bj][m][n] = __builtin_amdgcn_mfma_f32_16x16x32_bf16(Bt[n][k], At[m][k], acc[ai][bj][m][n], 0, 0, 0); __builtin_amdgcn_s_setprio(0); } while (0)
; #define PG8_WAIT_V(n) asm volatile("s_waitcnt vmcnt(" #n ")" ::: "memory")
; #define PG8_WAIT_L(n) asm volatile("s_waitcnt lgkmcnt(" #n ")" ::: "memory")
; #define PG8_BAR __builtin_amdgcn_s_barrier()
; #define PG8_SCHED __builtin_amdgcn_sched_barrier(0)
; template <class Epi, class Sched, bool ALIGN_EPI>
; __device__ __forceinline__ void gemm_phase(LAS unsigned char* lds, const Gemm g, const Sched& S, const Epi& E) {
;     ...
;             PG8_WAIT_V(8); PG8_WAIT_L(0); PG8_BAR; PG8_MMA(1, 0, At, B0); PG8_MMA(1, 1, At, B1); PG8_BAR; PG8_SCHED;
;             PG8_LDB(B0, 1, 0); PG8_LDB(B1, 1, 1); PG8_SCHED; PG8_LDA(At, 1, 0); PG8_STAGE(PG8_SA(0, 1), a2 + hA, voffA);
;             PG8_WAIT_V(8); PG8_WAIT_L(0); PG8_BAR; PG8_MMA(0, 0, At, B0); PG8_MMA(0, 1, At, B1); PG8_BAR; PG8_SCHED;
	v_mfma_f32_16x16x32_bf16 v[60:63], v[128:131], v[200:203], v[60:63]
	v_mfma_f32_16x16x32_bf16 v[52:55], v[136:139], v[200:203], v[52:55]
	v_mfma_f32_16x16x32_bf16 v[44:47], v[128:131], v[208:211], v[44:47]
	v_mfma_f32_16x16x32_bf16 v[36:39], v[136:139], v[208:211], v[36:39]
	v_mfma_f32_16x16x32_bf16 v[28:31], v[128:131], v[216:219], v[28:31]
	v_mfma_f32_16x16x32_bf16 v[20:23], v[136:139], v[216:219], v[20:23]
	v_mfma_f32_16x16x32_bf16 v[12:15], v[128:131], v[226:229], v[12:15]
	v_mfma_f32_16x16x32_bf16 v[4:7], v[136:139], v[226:229], v[4:7]
	v_mfma_f32_16x16x32_bf16 v[60:63], v[132:135], v[204:207], v[60:63]
	v_mfma_f32_16x16x32_bf16 v[52:55], v[140:143], v[204:207], v[52:55]
	v_mfma_f32_16x16x32_bf16 v[44:47], v[132:135], v[212:215], v[44:47]
	v_mfma_f32_16x16x32_bf16 v[36:39], v[140:143], v[212:215], v[36:39]
	v_mfma_f32_16x16x32_bf16 v[28:31], v[132:135], v[222:225], v[28:31]
	v_mfma_f32_16x16x32_bf16 v[20:23], v[140:143], v[222:225], v[20:23]
	v_mfma_f32_16x16x32_bf16 v[12:15], v[132:135], v[230:233], v[12:15]
	v_mfma_f32_16x16x32_bf16 v[4:7], v[140:143], v[230:233], v[4:7]
	v_mfma_f32_16x16x32_bf16 v[56:59], v[162:165], v[200:203], v[56:59]
	v_mfma_f32_16x16x32_bf16 v[48:51], v[170:173], v[200:203], v[48:51]
	v_mfma_f32_16x16x32_bf16 v[40:43], v[162:165], v[208:211], v[40:43]
	v_mfma_f32_16x16x32_bf16 v[32:35], v[170:173], v[208:211], v[32:35]
	v_mfma_f32_16x16x32_bf16 v[24:27], v[162:165], v[216:219], v[24:27]
	v_mfma_f32_16x16x32_bf16 v[16:19], v[170:173], v[216:219], v[16:19]
	v_mfma_f32_16x16x32_bf16 v[8:11], v[162:165], v[226:229], v[8:11]
	v_mfma_f32_16x16x32_bf16 v[0:3], v[170:173], v[226:229], v[0:3]
	v_mfma_f32_16x16x32_bf16 v[56:59], v[166:169], v[204:207], v[56:59]
	v_mfma_f32_16x16x32_bf16 v[48:51], v[174:177], v[204:207], v[48:51]
	v_mfma_f32_16x16x32_bf16 v[40:43], v[166:169], v[212:215], v[40:43]
	v_mfma_f32_16x16x32_bf16 v[32:35], v[174:177], v[212:215], v[32:35]
	v_mfma_f32_16x16x32_bf16 v[24:27], v[166:169], v[222:225], v[24:27]
	v_mfma_f32_16x16x32_bf16 v[16:19], v[174:177], v[222:225], v[16:19]
	v_mfma_f32_16x16x32_bf16 v[8:11], v[166:169], v[230:233], v[8:11]
	v_mfma_f32_16x16x32_bf16 v[0:3], v[174:177], v[230:233], v[0:3]
	s_barrier
	s_add_i32 s18, 0, 0x18000
	s_add_i32 s19, 0, 0x1c000
	v_add_u32_e32 v140, s18, v193
	v_add_u32_e32 v174, s19, v193
	ds_read_b128 v[128:131], v140
	ds_read_b128 v[132:135], v140 offset:1024
	ds_read_b128 v[136:139], v140 offset:2048
	ds_read_b128 v[140:143], v140 offset:3072
	ds_read_b128 v[162:165], v174
	ds_read_b128 v[166:169], v174 offset:1024
	ds_read_b128 v[170:173], v174 offset:2048
	ds_read_b128 v[174:177], v174 offset:3072
	s_add_u32 s46, s66, 0x80000
	s_addc_u32 s47, s67, 0
	s_mov_b32 m0, s76
	v_lshl_add_u64 v[240:241], s[46:47], 0, v[148:149]
	ds_read_b128 v[200:203], v197 offset:32768
	ds_read_b128 v[204:207], v197 offset:33792
	ds_read_b128 v[208:211], v197 offset:34816
	ds_read_b128 v[212:215], v197 offset:35840
	ds_read_b128 v[216:219], v197 offset:36864
	ds_read_b128 v[222:225], v197 offset:37888
	ds_read_b128 v[226:229], v197 offset:38912
	ds_read_b128 v[230:233], v197 offset:39936
	global_load_lds_dwordx4 v[240:241], off
	s_mov_b32 m0, s77
	v_lshl_add_u64 v[240:241], s[46:47], 0, v[150:151]
	global_load_lds_dwordx4 v[240:241], off
	s_waitcnt vmcnt(8) lgkmcnt(0)
	s_barrier
	v_mfma_f32_16x16x32_bf16 v[124:127], v[128:131], v[200:203], v[124:127]
	v_mfma_f32_16x16x32_bf16 v[116:119], v[136:139], v[200:203], v[116:119]
	v_mfma_f32_16x16x32_bf16 v[108:111], v[128:131], v[208:211], v[108:111]
	v_mfma_f32_16x16x32_bf16 v[100:103], v[136:139], v[208:211], v[100:103]
	v_mfma_f32_16x16x32_bf16 v[92:95], v[128:131], v[216:219], v[92:95]
	v_mfma_f32_16x16x32_bf16 v[84:87], v[136:139], v[216:219], v[84:87]
	v_mfma_f32_16x16x32_bf16 v[76:79], v[128:131], v[226:229], v[76:79]
	v_mfma_f32_16x16x32_bf16 v[68:71], v[136:139], v[226:229], v[68:71]
	v_mfma_f32_16x16x32_bf16 v[124:127], v[132:135], v[204:207], v[124:127]
	v_mfma_f32_16x16x32_bf16 v[116:119], v[140:143], v[204:207], v[116:119]
	v_mfma_f32_16x16x32_bf16 v[108:111], v[132:135], v[212:215], v[108:111]
	v_mfma_f32_16x16x32_bf16 v[100:103], v[140:143], v[212:215], v[100:103]
	v_mfma_f32_16x16x32_bf16 v[92:95], v[132:135], v[222:225], v[92:95]
	v_mfma_f32_16x16x32_bf16 v[84:87], v[140:143], v[222:225], v[84:87]
	v_mfma_f32_16x16x32_bf16 v[76:79], v[132:135], v[230:233], v[76:79]
	v_mfma_f32_16x16x32_bf16 v[68:71], v[140:143], v[230:233], v[68:71]
	v_mfma_f32_16x16x32_bf16 v[120:123], v[162:165], v[200:203], v[120:123]
	v_mfma_f32_16x16x32_bf16 v[112:115], v[170:173], v[200:203], v[112:115]
	v_mfma_f32_16x16x32_bf16 v[104:107], v[162:165], v[208:211], v[104:107]
	v_mfma_f32_16x16x32_bf16 v[96:99], v[170:173], v[208:211], v[96:99]
	v_mfma_f32_16x16x32_bf16 v[88:91], v[162:165], v[216:219], v[88:91]
	v_mfma_f32_16x16x32_bf16 v[80:83], v[170:173], v[216:219], v[80:83]
	v_mfma_f32_16x16x32_bf16 v[72:75], v[162:165], v[226:229], v[72:75]
	v_mfma_f32_16x16x32_bf16 v[64:67], v[170:173], v[226:229], v[64:67]
	v_mfma_f32_16x16x32_bf16 v[120:123], v[166:169], v[204:207], v[120:123]
	v_mfma_f32_16x16x32_bf16 v[112:115], v[174:177], v[204:207], v[112:115]
	v_mfma_f32_16x16x32_bf16 v[104:107], v[166:169], v[212:215], v[104:107]
	v_mfma_f32_16x16x32_bf16 v[96:99], v[174:177], v[212:215], v[96:99]
	v_mfma_f32_16x16x32_bf16 v[88:91], v[166:169], v[222:225], v[88:91]
	v_mfma_f32_16x16x32_bf16 v[80:83], v[174:177], v[222:225], v[80:83]
	v_mfma_f32_16x16x32_bf16 v[72:75], v[166:169], v[230:233], v[72:75]
	v_mfma_f32_16x16x32_bf16 v[64:67], v[174:177], v[230:233], v[64:67]
	s_barrier
; #define PG8_STAGE(bufoff, gbase, voff) do { _Pragma("unroll") for (int _i = 0; _i < 2; ++_i) \
;         __builtin_amdgcn_global_load_lds((const unsigned*)((const char*)(gbase) + (voff)[_i]), (LAS unsigned*)(lds + (bufoff) + ldsw + _i * 8192), 16, 0, 0); } while (0)
; #define PG8_LDA(dst, b, h) do { _Pragma("unroll") for (int m = 0; m < 4; ++m) _Pragma("unroll") for (int k = 0; k < 2; ++k) dst[m][k] = *(const LAS bf16x8*)(lds + PG8_SA(b, h) + aoff + m * 2048 + k * 1024); } while (0)
; #define PG8_MMA(ai, bj, At, Bt) do { __builtin_amdgcn_s_setprio(1); _Pragma("unroll") for (int m = 0; m < 4; ++m) _Pragma("unroll") for (int n = 0; n < 2; ++n) _Pragma("unroll") for (int k = 0; k < 2; ++k) \
;         acc[ai][bj][m][n] = __builtin_amdgcn_mfma_f32_16x16x32_bf16(Bt[n][k], At[m][k], acc[ai][bj][m][n], 0, 0, 0); __builtin_amdgcn_s_setprio(0); } while (0)
; #define PG8_WAIT_V(n) asm volatile("s_waitcnt vmcnt(" #n ")" ::: "memory")
; #define PG8_WAIT_L(n) asm volatile("s_waitcnt lgkmcnt(" #n ")" ::: "memory")
; #define PG8_BAR __builtin_amdgcn_s_barrier()
; #define PG8_SCHED __builtin_amdgcn_sched_barrier(0)
; template <class Epi, class Sched, bool ALIGN_EPI>
; __device__ __forceinline__ void gemm_phase(LAS unsigned char* lds, const Gemm g, const Sched& S, const Epi& E) {
;     ...
;             PG8_LDA(At, 1, 1); PG8_STAGE(PG8_SB(1, 0), b3, voffB); PG8_STAGE(PG8_SB(1, 1), b3 + hB, voffB); PG8_STAGE(PG8_SA(1, 0), a3, voffA);
;             PG8_WAIT_V(8); PG8_WAIT_L(0); PG8_BAR; PG8_MMA(1, 0, At, B0); PG8_MMA(1, 1, At, B1); PG8_BAR; PG8_SCHED;
;         }
;         if constexpr (ALIGN_EPI) { if (wr == 0) PG8_BAR; }
	s_add_i32 s18, s18, s41
	v_lshl_add_u64 v[178:179], v[178:179], 0, s[36:37]
	s_mov_b32 m0, s18
	ds_read_b128 v[200:203], v197 offset:49152
	ds_read_b128 v[204:207], v197 offset:50176
	ds_read_b128 v[208:211], v197 offset:51200
	ds_read_b128 v[212:215], v197 offset:52224
	ds_read_b128 v[216:219], v197 offset:53248
	ds_read_b128 v[222:225], v197 offset:54272
	ds_read_b128 v[226:229], v197 offset:55296
	ds_read_b128 v[230:233], v197 offset:56320
	global_load_lds_dwordx4 v[178:179], off
	s_add_i32 m0, s18, 0x2000
	s_add_u32 s6, s6, 0x80080
	v_lshl_add_u64 v[178:179], v[234:235], 0, s[36:37]
	s_addc_u32 s7, s7, 0
	s_add_i32 s18, s19, s41
	global_load_lds_dwordx4 v[178:179], off
	s_mov_b32 m0, s18
	v_lshl_add_u64 v[178:179], s[6:7], 0, v[144:145]
	global_load_lds_dwordx4 v[178:179], off
	s_add_i32 m0, s18, 0x2000
	v_lshl_add_u64 v[178:179], s[6:7], 0, v[146:147]
	global_load_lds_dwordx4 v[178:179], off
	s_mov_b32 m0, s78
	v_lshl_add_u64 v[178:179], v[236:237], 0, s[36:37]
	global_load_lds_dwordx4 v[178:179], off
	s_mov_b32 m0, s79
	v_lshl_add_u64 v[178:179], v[238:239], 0, s[36:37]
	global_load_lds_dwordx4 v[178:179], off
	s_waitcnt vmcnt(8) lgkmcnt(0)
	s_barrier
	v_mfma_f32_16x16x32_bf16 v[60:63], v[128:131], v[200:203], v[60:63]
	v_mfma_f32_16x16x32_bf16 v[52:55], v[136:139], v[200:203], v[52:55]
	v_mfma_f32_16x16x32_bf16 v[44:47], v[128:131], v[208:211], v[44:47]
	v_mfma_f32_16x16x32_bf16 v[36:39], v[136:139], v[208:211], v[36:39]
	v_mfma_f32_16x16x32_bf16 v[28:31], v[128:131], v[216:219], v[28:31]
	v_mfma_f32_16x16x32_bf16 v[20:23], v[136:139], v[216:219], v[20:23]
	v_mfma_f32_16x16x32_bf16 v[12:15], v[128:131], v[226:229], v[12:15]
	v_mfma_f32_16x16x32_bf16 v[4:7], v[136:139], v[226:229], v[4:7]
	v_mfma_f32_16x16x32_bf16 v[60:63], v[132:135], v[204:207], v[60:63]
	v_mfma_f32_16x16x32_bf16 v[52:55], v[140:143], v[204:207], v[52:55]
	v_mfma_f32_16x16x32_bf16 v[44:47], v[132:135], v[212:215], v[44:47]
	v_mfma_f32_16x16x32_bf16 v[36:39], v[140:143], v[212:215], v[36:39]
	v_mfma_f32_16x16x32_bf16 v[28:31], v[132:135], v[222:225], v[28:31]
	v_mfma_f32_16x16x32_bf16 v[20:23], v[140:143], v[222:225], v[20:23]
	v_mfma_f32_16x16x32_bf16 v[12:15], v[132:135], v[230:233], v[12:15]
	v_mfma_f32_16x16x32_bf16 v[4:7], v[140:143], v[230:233], v[4:7]
	v_mfma_f32_16x16x32_bf16 v[56:59], v[162:165], v[200:203], v[56:59]
	v_mfma_f32_16x16x32_bf16 v[48:51], v[170:173], v[200:203], v[48:51]
	v_mfma_f32_16x16x32_bf16 v[40:43], v[162:165], v[208:211], v[40:43]
	v_mfma_f32_16x16x32_bf16 v[32:35], v[170:173], v[208:211], v[32:35]
	v_mfma_f32_16x16x32_bf16 v[24:27], v[162:165], v[216:219], v[24:27]
	v_mfma_f32_16x16x32_bf16 v[16:19], v[170:173], v[216:219], v[16:19]
	v_mfma_f32_16x16x32_bf16 v[8:11], v[162:165], v[226:229], v[8:11]
	v_mfma_f32_16x16x32_bf16 v[0:3], v[170:173], v[226:229], v[0:3]
	v_mfma_f32_16x16x32_bf16 v[56:59], v[166:169], v[204:207], v[56:59]
	v_mfma_f32_16x16x32_bf16 v[48:51], v[174:177], v[204:207], v[48:51]
	v_mfma_f32_16x16x32_bf16 v[40:43], v[166:169], v[212:215], v[40:43]
	v_mfma_f32_16x16x32_bf16 v[32:35], v[174:177], v[212:215], v[32:35]
	v_mfma_f32_16x16x32_bf16 v[24:27], v[166:169], v[222:225], v[24:27]
	v_mfma_f32_16x16x32_bf16 v[16:19], v[174:177], v[222:225], v[16:19]
	v_mfma_f32_16x16x32_bf16 v[8:11], v[166:169], v[230:233], v[8:11]
	v_mfma_f32_16x16x32_bf16 v[0:3], v[174:177], v[230:233], v[0:3]
	s_barrier
	s_add_i32 s72, s72, 2
	s_add_u32 s4, s4, 0x100
	s_addc_u32 s5, s5, 0
	s_add_u32 s44, s44, 0x100
	s_addc_u32 s45, s45, 0
	s_cmp_gt_u32 s72, 29
	s_cbranch_scc0 .LBB0_261
	s_and_b64 vcc, exec, s[38:39]
	s_cbranch_vccz .LBB0_264
	s_barrier

; #define PG8_STAGE(bufoff, gbase, voff) do { _Pragma("unroll") for (int _i = 0; _i < 2; ++_i) \
;         __builtin_amdgcn_global_load_lds((const unsigned*)((const char*)(gbase) + (voff)[_i]), (LAS unsigned*)(lds + (bufoff) + ldsw + _i * 8192), 16, 0, 0); } while (0)
; #define PG8_LDA(dst, b, h) do { _Pragma("unroll") for (int m = 0; m < 4; ++m) _Pragma("unroll") for (int k = 0; k < 2; ++k) dst[m][k] = *(const LAS bf16x8*)(lds + PG8_SA(b, h) + aoff + m * 2048 + k * 1024); } while (0)
; #define PG8_LDB(dst, b, h) do { _Pragma("unroll") for (int n = 0; n < 2; ++n) _Pragma("unroll") for (int k = 0; k < 2; ++k) dst[n][k] = *(const LAS bf16x8*)(lds + PG8_SB(b, h) + boff + n * 2048 + k * 1024); } while (0)
; #define PG8_MMA(ai, bj, At, Bt) do { __builtin_amdgcn_s_setprio(1); _Pragma("unroll") for (int m = 0; m < 4; ++m) _Pragma("unroll") for (int n = 0; n < 2; ++n) _Pragma("unroll") for (int k = 0; k < 2; ++k) \
;         acc[ai][bj][m][n] = __builtin_amdgcn_mfma_f32_16x16x32_bf16(Bt[n][k], At[m][k], acc[ai][bj][m][n], 0, 0, 0); __builtin_amdgcn_s_setprio(0); } while (0)
; #define PG8_WAIT_V(n) asm volatile("s_waitcnt vmcnt(" #n ")" ::: "memory")
; #define PG8_WAIT_L(n) asm volatile("s_waitcnt lgkmcnt(" #n ")" ::: "memory")
; #define PG8_BAR __builtin_amdgcn_s_barrier()
; #define PG8_SCHED __builtin_amdgcn_sched_barrier(0)
; template <class Epi, class Sched, bool ALIGN_EPI>
; __device__ __forceinline__ void gemm_phase(LAS unsigned char* lds, const Gemm g, const Sched& S, const Epi& E) {
;     ...
;             const bool last = (t == nt - 2);
;             const char* a1 = cA + (size_t)(t + 1) * kstep;
;             const char* a2 = last ? nA : cA + (size_t)(t + 2) * kstep; const char* b2 = last ? nB : cB + (size_t)(t + 2) * kstep;
;             const char* a3 = a2 + kstep; const char* b3 = b2 + kstep;
;             PG8_LDB(B0, 0, 0); PG8_LDB(B1, 0, 1); PG8_SCHED; PG8_LDA(At, 0, 0); PG8_STAGE(PG8_SA(1, 1), a1 + hA, voffA);
;             PG8_WAIT_V(8); PG8_WAIT_L(0); PG8_BAR; PG8_MMA(0, 0, At, B0); PG8_MMA(0, 1, At, B1); PG8_BAR; PG8_SCHED;
;             PG8_LDA(At, 0, 1); PG8_STAGE(PG8_SB(0, 0), b2, voffB); PG8_STAGE(PG8_SB(0, 1), b2 + hB, voffB); PG8_STAGE(PG8_SA(0, 0), a2, voffA);
;             PG8_WAIT_V(8); PG8_WAIT_L(0); PG8_BAR; PG8_MMA(1, 0, At, B0); PG8_MMA(1, 1, At, B1); PG8_BAR; PG8_SCHED;
.LBB0_280:
	ds_read_b128 v[150:153], v148
	ds_read_b128 v[154:157], v148 offset:1024
	ds_read_b128 v[158:161], v148 offset:2048
	ds_read_b128 v[162:165], v148 offset:3072
	ds_read_b128 v[166:169], v149
	ds_read_b128 v[170:173], v149 offset:1024
	ds_read_b128 v[174:177], v149 offset:2048
	ds_read_b128 v[186:189], v149 offset:3072
	s_add_i32 s80, s42, 2
	s_add_u32 s18, s40, 0xf4000080
	s_addc_u32 s19, s41, -1
	s_cmp_lg_u32 s66, s42
	s_cselect_b32 s18, s18, 0
	s_cselect_b32 s19, s19, 0
	s_add_u32 s62, s38, s18
	s_addc_u32 s63, s39, s19
	s_add_u32 s42, s36, s18
	s_addc_u32 s43, s37, s19
	s_mov_b32 m0, s6
	v_lshl_add_u64 v[178:179], v[138:139], 0, s[40:41]
	ds_read_b128 v[190:193], v143
	ds_read_b128 v[194:197], v143 offset:1024
	ds_read_b128 v[198:201], v143 offset:2048
	ds_read_b128 v[202:205], v143 offset:3072
	ds_read_b128 v[206:209], v143 offset:4096
	ds_read_b128 v[210:213], v143 offset:5120
	ds_read_b128 v[214:217], v143 offset:6144
	ds_read_b128 v[222:225], v143 offset:7168
	global_load_lds_dwordx4 v[178:179], off
	s_mov_b32 m0, s44
	v_lshl_add_u64 v[178:179], v[140:141], 0, s[40:41]
	global_load_lds_dwordx4 v[178:179], off
	s_waitcnt vmcnt(8) lgkmcnt(0)
	s_barrier
	v_mfma_f32_16x16x32_bf16 v[124:127], v[150:153], v[190:193], v[124:127]
	v_mfma_f32_16x16x32_bf16 v[120:123], v[158:161], v[190:193], v[120:123]
	v_mfma_f32_16x16x32_bf16 v[108:111], v[150:153], v[198:201], v[108:111]
	v_mfma_f32_16x16x32_bf16 v[104:107], v[158:161], v[198:201], v[104:107]
	v_mfma_f32_16x16x32_bf16 v[92:95], v[150:153], v[206:209], v[92:95]
	v_mfma_f32_16x16x32_bf16 v[88:91], v[158:161], v[206:209], v[88:91]
	v_mfma_f32_16x16x32_bf16 v[76:79], v[150:153], v[214:217], v[76:79]
	v_mfma_f32_16x16x32_bf16 v[72:75], v[158:161], v[214:217], v[72:75]
	v_mfma_f32_16x16x32_bf16 v[124:127], v[154:157], v[194:197], v[124:127]
	v_mfma_f32_16x16x32_bf16 v[120:123], v[162:165], v[194:197], v[120:123]
	v_mfma_f32_16x16x32_bf16 v[108:111], v[154:157], v[202:205], v[108:111]
	v_mfma_f32_16x16x32_bf16 v[104:107], v[162:165], v[202:205], v[104:107]
	v_mfma_f32_16x16x32_bf16 v[92:95], v[154:157], v[210:213], v[92:95]
	v_mfma_f32_16x16x32_bf16 v[88:91], v[162:165], v[210:213], v[88:91]
	v_mfma_f32_16x16x32_bf16 v[76:79], v[154:157], v[222:225], v[76:79]
	v_mfma_f32_16x16x32_bf16 v[72:75], v[162:165], v[222:225], v[72:75]
	v_mfma_f32_16x16x32_bf16 v[116:119], v[166:169], v[190:193], v[116:119]
	v_mfma_f32_16x16x32_bf16 v[112:115], v[174:177], v[190:193], v[112:115]
	v_mfma_f32_16x16x32_bf16 v[100:103], v[166:169], v[198:201], v[100:103]
	v_mfma_f32_16x16x32_bf16 v[96:99], v[174:177], v[198:201], v[96:99]
	v_mfma_f32_16x16x32_bf16 v[84:87], v[166:169], v[206:209], v[84:87]
	v_mfma_f32_16x16x32_bf16 v[80:83], v[174:177], v[206:209], v[80:83]
	v_mfma_f32_16x16x32_bf16 v[68:71], v[166:169], v[214:217], v[68:71]
	v_mfma_f32_16x16x32_bf16 v[64:67], v[174:177], v[214:217], v[64:67]
	v_mfma_f32_16x16x32_bf16 v[116:119], v[170:173], v[194:197], v[116:119]
	v_mfma_f32_16x16x32_bf16 v[112:115], v[186:189], v[194:197], v[112:115]
	v_mfma_f32_16x16x32_bf16 v[100:103], v[170:173], v[202:205], v[100:103]
	v_mfma_f32_16x16x32_bf16 v[96:99], v[186:189], v[202:205], v[96:99]
	v_mfma_f32_16x16x32_bf16 v[84:87], v[170:173], v[210:213], v[84:87]
	v_mfma_f32_16x16x32_bf16 v[80:83], v[186:189], v[210:213], v[80:83]
	v_mfma_f32_16x16x32_bf16 v[68:71], v[170:173], v[222:225], v[68:71]
	v_mfma_f32_16x16x32_bf16 v[64:67], v[186:189], v[222:225], v[64:67]
	s_barrier
	s_mov_b32 m0, s45
	v_lshl_add_u64 v[178:179], s[42:43], 0, v[144:145]
	s_add_u32 s82, s42, 0x80000
	ds_read_b128 v[190:193], v143 offset:16384
	ds_read_b128 v[194:197], v143 offset:17408
	ds_read_b128 v[198:201], v143 offset:18432
	ds_read_b128 v[202:205], v143 offset:19456
	ds_read_b128 v[206:209], v143 offset:20480
	ds_read_b128 v[210:213], v143 offset:21504
	ds_read_b128 v[214:217], v143 offset:22528
	ds_read_b128 v[222:225], v143 offset:23552
	global_load_lds_dwordx4 v[178:179], off
	v_lshl_add_u64 v[218:219], s[42:43], 0, v[146:147]
	s_mov_b32 m0, s46
	s_addc_u32 s83, s43, 0
	global_load_lds_dwordx4 v[218:219], off
	v_lshl_add_u64 v[226:227], s[82:83], 0, v[144:145]
	s_mov_b32 m0, s47
	v_lshl_add_u64 v[228:229], s[62:63], 0, v[130:131]
	global_load_lds_dwordx4 v[226:227], off
	s_mov_b32 m0, s72
	v_lshl_add_u64 v[226:227], s[82:83], 0, v[146:147]
	global_load_lds_dwordx4 v[226:227], off
	s_mov_b32 m0, s27
	v_lshl_add_u64 v[226:227], s[62:63], 0, v[128:129]
	global_load_lds_dwordx4 v[226:227], off
	s_mov_b32 m0, s75
	s_nop 0
	global_load_lds_dwordx4 v[228:229], off
	s_waitcnt vmcnt(8) lgkmcnt(0)
	s_barrier
; #define PG8_STAGE(bufoff, gbase, voff) do { _Pragma("unroll") for (int _i = 0; _i < 2; ++_i) \
;         __builtin_amdgcn_global_load_lds((const unsigned*)((const char*)(gbase) + (voff)[_i]), (LAS unsigned*)(lds + (bufoff) + ldsw + _i * 8192), 16, 0, 0); } while (0)
; #define PG8_LDA(dst, b, h) do { _Pragma("unroll") for (int m = 0; m < 4; ++m) _Pragma("unroll") for (int k = 0; k < 2; ++k) dst[m][k] = *(const LAS bf16x8*)(lds + PG8_SA(b, h) + aoff + m * 2048 + k * 1024); } while (0)
; #define PG8_LDB(dst, b, h) do { _Pragma("unroll") for (int n = 0; n < 2; ++n) _Pragma("unroll") for (int k = 0; k < 2; ++k) dst[n][k] = *(const LAS bf16x8*)(lds + PG8_SB(b, h) + boff + n * 2048 + k * 1024); } while (0)
; #define PG8_MMA(ai, bj, At, Bt) do { __builtin_amdgcn_s_setprio(1); _Pragma("unroll") for (int m = 0; m < 4; ++m) _Pragma("unroll") for (int n = 0; n < 2; ++n) _Pragma("unroll") for (int k = 0; k < 2; ++k) \
;         acc[ai][bj][m][n] = __builtin_amdgcn_mfma_f32_16x16x32_bf16(Bt[n][k], At[m][k], acc[ai][bj][m][n], 0, 0, 0); __builtin_amdgcn_s_setprio(0); } while (0)
; #define PG8_WAIT_V(n) asm volatile("s_waitcnt vmcnt(" #n ")" ::: "memory")
; #define PG8_WAIT_L(n) asm volatile("s_waitcnt lgkmcnt(" #n ")" ::: "memory")
; #define PG8_BAR __builtin_amdgcn_s_barrier()
; #define PG8_SCHED __builtin_amdgcn_sched_barrier(0)
; template <class Epi, class Sched, bool ALIGN_EPI>
; __device__ __forceinline__ void gemm_phase(LAS unsigned char* lds, const Gemm g, const Sched& S, const Epi& E) {
;     ...
;             PG8_WAIT_V(8); PG8_WAIT_L(0); PG8_BAR; PG8_MMA(1, 0, At, B0); PG8_MMA(1, 1, At, B1); PG8_BAR; PG8_SCHED;
;             PG8_LDB(B0, 1, 0); PG8_LDB(B1, 1, 1); PG8_SCHED; PG8_LDA(At, 1, 0); PG8_STAGE(PG8_SA(0, 1), a2 + hA, voffA);
;             PG8_WAIT_V(8); PG8_WAIT_L(0); PG8_BAR; PG8_MMA(0, 0, At, B0); PG8_MMA(0, 1, At, B1); PG8_BAR; PG8_SCHED;
	v_mfma_f32_16x16x32_bf16 v[60:63], v[150:153], v[190:193], v[60:63]
	v_mfma_f32_16x16x32_bf16 v[56:59], v[158:161], v[190:193], v[56:59]
	v_mfma_f32_16x16x32_bf16 v[44:47], v[150:153], v[198:201], v[44:47]
	v_mfma_f32_16x16x32_bf16 v[40:43], v[158:161], v[198:201], v[40:43]
	v_mfma_f32_16x16x32_bf16 v[28:31], v[150:153], v[206:209], v[28:31]
	v_mfma_f32_16x16x32_bf16 v[24:27], v[158:161], v[206:209], v[24:27]
	v_mfma_f32_16x16x32_bf16 v[12:15], v[150:153], v[214:217], v[12:15]
	v_mfma_f32_16x16x32_bf16 v[8:11], v[158:161], v[214:217], v[8:11]
	v_mfma_f32_16x16x32_bf16 v[60:63], v[154:157], v[194:197], v[60:63]
	v_mfma_f32_16x16x32_bf16 v[56:59], v[162:165], v[194:197], v[56:59]
	v_mfma_f32_16x16x32_bf16 v[44:47], v[154:157], v[202:205], v[44:47]
	v_mfma_f32_16x16x32_bf16 v[40:43], v[162:165], v[202:205], v[40:43]
	v_mfma_f32_16x16x32_bf16 v[28:31], v[154:157], v[210:213], v[28:31]
	v_mfma_f32_16x16x32_bf16 v[24:27], v[162:165], v[210:213], v[24:27]
	v_mfma_f32_16x16x32_bf16 v[12:15], v[154:157], v[222:225], v[12:15]
	v_mfma_f32_16x16x32_bf16 v[8:11], v[162:165], v[222:225], v[8:11]
	v_mfma_f32_16x16x32_bf16 v[52:55], v[166:169], v[190:193], v[52:55]
	v_mfma_f32_16x16x32_bf16 v[48:51], v[174:177], v[190:193], v[48:51]
	v_mfma_f32_16x16x32_bf16 v[36:39], v[166:169], v[198:201], v[36:39]
	v_mfma_f32_16x16x32_bf16 v[32:35], v[174:177], v[198:201], v[32:35]
	v_mfma_f32_16x16x32_bf16 v[20:23], v[166:169], v[206:209], v[20:23]
	v_mfma_f32_16x16x32_bf16 v[16:19], v[174:177], v[206:209], v[16:19]
	v_mfma_f32_16x16x32_bf16 v[4:7], v[166:169], v[214:217], v[4:7]
	v_mfma_f32_16x16x32_bf16 v[0:3], v[174:177], v[214:217], v[0:3]
	v_mfma_f32_16x16x32_bf16 v[52:55], v[170:173], v[194:197], v[52:55]
	v_mfma_f32_16x16x32_bf16 v[48:51], v[186:189], v[194:197], v[48:51]
	v_mfma_f32_16x16x32_bf16 v[36:39], v[170:173], v[202:205], v[36:39]
	v_mfma_f32_16x16x32_bf16 v[32:35], v[186:189], v[202:205], v[32:35]
	v_mfma_f32_16x16x32_bf16 v[20:23], v[170:173], v[210:213], v[20:23]
	v_mfma_f32_16x16x32_bf16 v[16:19], v[186:189], v[210:213], v[16:19]
	v_mfma_f32_16x16x32_bf16 v[4:7], v[170:173], v[222:225], v[4:7]
	v_mfma_f32_16x16x32_bf16 v[0:3], v[186:189], v[222:225], v[0:3]
	s_barrier
	s_add_i32 s18, 0, 0x18000
	s_add_i32 s19, 0, 0x1c000
	v_add_u32_e32 v162, s18, v142
	v_add_u32_e32 v185, s19, v142
	ds_read_b128 v[150:153], v162
	ds_read_b128 v[154:157], v162 offset:1024
	ds_read_b128 v[158:161], v162 offset:2048
	ds_read_b128 v[162:165], v162 offset:3072
	ds_read_b128 v[166:169], v185
	ds_read_b128 v[170:173], v185 offset:1024
	ds_read_b128 v[174:177], v185 offset:2048
	ds_read_b128 v[186:189], v185 offset:3072
	s_add_u32 s62, s62, 0x100000
	s_addc_u32 s63, s63, 0
	s_mov_b32 m0, s76
	v_lshl_add_u64 v[230:231], s[62:63], 0, v[128:129]
	ds_read_b128 v[190:193], v143 offset:32768
	ds_read_b128 v[194:197], v143 offset:33792
	ds_read_b128 v[198:201], v143 offset:34816
	ds_read_b128 v[202:205], v143 offset:35840
	ds_read_b128 v[206:209], v143 offset:36864
	ds_read_b128 v[210:213], v143 offset:37888
	ds_read_b128 v[214:217], v143 offset:38912
	ds_read_b128 v[222:225], v143 offset:39936
	global_load_lds_dwordx4 v[230:231], off
	s_mov_b32 m0, s77
	v_lshl_add_u64 v[230:231], s[62:63], 0, v[130:131]
	global_load_lds_dwordx4 v[230:231], off
	s_waitcnt vmcnt(8) lgkmcnt(0)
	s_barrier
	v_mfma_f32_16x16x32_bf16 v[124:127], v[150:153], v[190:193], v[124:127]
	v_mfma_f32_16x16x32_bf16 v[120:123], v[158:161], v[190:193], v[120:123]
	v_mfma_f32_16x16x32_bf16 v[108:111], v[150:153], v[198:201], v[108:111]
	v_mfma_f32_16x16x32_bf16 v[104:107], v[158:161], v[198:201], v[104:107]
	v_mfma_f32_16x16x32_bf16 v[92:95], v[150:153], v[206:209], v[92:95]
	v_mfma_f32_16x16x32_bf16 v[88:91], v[158:161], v[206:209], v[88:91]
	v_mfma_f32_16x16x32_bf16 v[76:79], v[150:153], v[214:217], v[76:79]
	v_mfma_f32_16x16x32_bf16 v[72:75], v[158:161], v[214:217], v[72:75]
	v_mfma_f32_16x16x32_bf16 v[124:127], v[154:157], v[194:197], v[124:127]
	v_mfma_f32_16x16x32_bf16 v[120:123], v[162:165], v[194:197], v[120:123]
	v_mfma_f32_16x16x32_bf16 v[108:111], v[154:157], v[202:205], v[108:111]
	v_mfma_f32_16x16x32_bf16 v[104:107], v[162:165], v[202:205], v[104:107]
	v_mfma_f32_16x16x32_bf16 v[92:95], v[154:157], v[210:213], v[92:95]
	v_mfma_f32_16x16x32_bf16 v[88:91], v[162:165], v[210:213], v[88:91]
	v_mfma_f32_16x16x32_bf16 v[76:79], v[154:157], v[222:225], v[76:79]
	v_mfma_f32_16x16x32_bf16 v[72:75], v[162:165], v[222:225], v[72:75]
	v_mfma_f32_16x16x32_bf16 v[116:119], v[166:169], v[190:193], v[116:119]
	v_mfma_f32_16x16x32_bf16 v[112:115], v[174:177], v[190:193], v[112:115]
	v_mfma_f32_16x16x32_bf16 v[100:103], v[166:169], v[198:201], v[100:103]
	v_mfma_f32_16x16x32_bf16 v[96:99], v[174:177], v[198:201], v[96:99]
	v_mfma_f32_16x16x32_bf16 v[84:87], v[166:169], v[206:209], v[84:87]
	v_mfma_f32_16x16x32_bf16 v[80:83], v[174:177], v[206:209], v[80:83]
	v_mfma_f32_16x16x32_bf16 v[68:71], v[166:169], v[214:217], v[68:71]
	v_mfma_f32_16x16x32_bf16 v[64:67], v[174:177], v[214:217], v[64:67]
	v_mfma_f32_16x16x32_bf16 v[116:119], v[170:173], v[194:197], v[116:119]
	v_mfma_f32_16x16x32_bf16 v[112:115], v[186:189], v[194:197], v[112:115]
	v_mfma_f32_16x16x32_bf16 v[100:103], v[170:173], v[202:205], v[100:103]
	v_mfma_f32_16x16x32_bf16 v[96:99], v[186:189], v[202:205], v[96:99]
	v_mfma_f32_16x16x32_bf16 v[84:87], v[170:173], v[210:213], v[84:87]
	v_mfma_f32_16x16x32_bf16 v[80:83], v[186:189], v[210:213], v[80:83]
	v_mfma_f32_16x16x32_bf16 v[68:71], v[170:173], v[222:225], v[68:71]
	v_mfma_f32_16x16x32_bf16 v[64:67], v[186:189], v[222:225], v[64:67]
	s_barrier
; #define PG8_STAGE(bufoff, gbase, voff) do { _Pragma("unroll") for (int _i = 0; _i < 2; ++_i) \
;         __builtin_amdgcn_global_load_lds((const unsigned*)((const char*)(gbase) + (voff)[_i]), (LAS unsigned*)(lds + (bufoff) + ldsw + _i * 8192), 16, 0, 0); } while (0)
; #define PG8_LDA(dst, b, h) do { _Pragma("unroll") for (int m = 0; m < 4; ++m) _Pragma("unroll") for (int k = 0; k < 2; ++k) dst[m][k] = *(const LAS bf16x8*)(lds + PG8_SA(b, h) + aoff + m * 2048 + k * 1024); } while (0)
; #define PG8_MMA(ai, bj, At, Bt) do { __builtin_amdgcn_s_setprio(1); _Pragma("unroll") for (int m = 0; m < 4; ++m) _Pragma("unroll") for (int n = 0; n < 2; ++n) _Pragma("unroll") for (int k = 0; k < 2; ++k) \
;         acc[ai][bj][m][n] = __builtin_amdgcn_mfma_f32_16x16x32_bf16(Bt[n][k], At[m][k], acc[ai][bj][m][n], 0, 0, 0); __builtin_amdgcn_s_setprio(0); } while (0)
; #define PG8_WAIT_V(n) asm volatile("s_waitcnt vmcnt(" #n ")" ::: "memory")
; #define PG8_WAIT_L(n) asm volatile("s_waitcnt lgkmcnt(" #n ")" ::: "memory")
; #define PG8_BAR __builtin_amdgcn_s_barrier()
; #define PG8_SCHED __builtin_amdgcn_sched_barrier(0)
; template <class Epi, class Sched, bool ALIGN_EPI>
; __device__ __forceinline__ void gemm_phase(LAS unsigned char* lds, const Gemm g, const Sched& S, const Epi& E) {
;     ...
;             PG8_LDA(At, 1, 1); PG8_STAGE(PG8_SB(1, 0), b3, voffB); PG8_STAGE(PG8_SB(1, 1), b3 + hB, voffB); PG8_STAGE(PG8_SA(1, 0), a3, voffA);
;             PG8_WAIT_V(8); PG8_WAIT_L(0); PG8_BAR; PG8_MMA(1, 0, At, B0); PG8_MMA(1, 1, At, B1); PG8_BAR; PG8_SCHED;
;         }
	s_add_i32 s18, s18, s11
	v_lshl_add_u64 v[178:179], v[178:179], 0, s[24:25]
	s_mov_b32 m0, s18
	ds_read_b128 v[190:193], v143 offset:49152
	ds_read_b128 v[194:197], v143 offset:50176
	ds_read_b128 v[198:201], v143 offset:51200
	ds_read_b128 v[202:205], v143 offset:52224
	ds_read_b128 v[206:209], v143 offset:53248
	ds_read_b128 v[210:213], v143 offset:54272
	ds_read_b128 v[214:217], v143 offset:55296
	ds_read_b128 v[222:225], v143 offset:56320
	global_load_lds_dwordx4 v[178:179], off
	s_add_i32 m0, s18, 0x2000
	s_add_u32 s42, s42, 0x80080
	v_lshl_add_u64 v[178:179], v[218:219], 0, s[24:25]
	s_addc_u32 s43, s43, 0
	s_add_i32 s18, s19, s11
	global_load_lds_dwordx4 v[178:179], off
	s_mov_b32 m0, s18
	v_lshl_add_u64 v[178:179], s[42:43], 0, v[144:145]
	global_load_lds_dwordx4 v[178:179], off
	s_add_i32 m0, s18, 0x2000
	v_lshl_add_u64 v[178:179], s[42:43], 0, v[146:147]
	global_load_lds_dwordx4 v[178:179], off
	s_mov_b32 m0, s78
	v_lshl_add_u64 v[178:179], v[226:227], 0, s[24:25]
	global_load_lds_dwordx4 v[178:179], off
	s_mov_b32 m0, s79
	v_lshl_add_u64 v[178:179], v[228:229], 0, s[24:25]
	global_load_lds_dwordx4 v[178:179], off
	s_waitcnt vmcnt(8) lgkmcnt(0)
	s_barrier
	v_mfma_f32_16x16x32_bf16 v[60:63], v[150:153], v[190:193], v[60:63]
	v_mfma_f32_16x16x32_bf16 v[56:59], v[158:161], v[190:193], v[56:59]
	v_mfma_f32_16x16x32_bf16 v[44:47], v[150:153], v[198:201], v[44:47]
	v_mfma_f32_16x16x32_bf16 v[40:43], v[158:161], v[198:201], v[40:43]
	v_mfma_f32_16x16x32_bf16 v[28:31], v[150:153], v[206:209], v[28:31]
	v_mfma_f32_16x16x32_bf16 v[24:27], v[158:161], v[206:209], v[24:27]
	v_mfma_f32_16x16x32_bf16 v[12:15], v[150:153], v[214:217], v[12:15]
	v_mfma_f32_16x16x32_bf16 v[8:11], v[158:161], v[214:217], v[8:11]
	v_mfma_f32_16x16x32_bf16 v[60:63], v[154:157], v[194:197], v[60:63]
	v_mfma_f32_16x16x32_bf16 v[56:59], v[162:165], v[194:197], v[56:59]
	v_mfma_f32_16x16x32_bf16 v[44:47], v[154:157], v[202:205], v[44:47]
	v_mfma_f32_16x16x32_bf16 v[40:43], v[162:165], v[202:205], v[40:43]
	v_mfma_f32_16x16x32_bf16 v[28:31], v[154:157], v[210:213], v[28:31]
	v_mfma_f32_16x16x32_bf16 v[24:27], v[162:165], v[210:213], v[24:27]
	v_mfma_f32_16x16x32_bf16 v[12:15], v[154:157], v[222:225], v[12:15]
	v_mfma_f32_16x16x32_bf16 v[8:11], v[162:165], v[222:225], v[8:11]
	v_mfma_f32_16x16x32_bf16 v[52:55], v[166:169], v[190:193], v[52:55]
	v_mfma_f32_16x16x32_bf16 v[48:51], v[174:177], v[190:193], v[48:51]
	v_mfma_f32_16x16x32_bf16 v[36:39], v[166:169], v[198:201], v[36:39]
	v_mfma_f32_16x16x32_bf16 v[32:35], v[174:177], v[198:201], v[32:35]
	v_mfma_f32_16x16x32_bf16 v[20:23], v[166:169], v[206:209], v[20:23]
	v_mfma_f32_16x16x32_bf16 v[16:19], v[174:177], v[206:209], v[16:19]
	v_mfma_f32_16x16x32_bf16 v[4:7], v[166:169], v[214:217], v[4:7]
	v_mfma_f32_16x16x32_bf16 v[0:3], v[174:177], v[214:217], v[0:3]
	v_mfma_f32_16x16x32_bf16 v[52:55], v[170:173], v[194:197], v[52:55]
	v_mfma_f32_16x16x32_bf16 v[48:51], v[186:189], v[194:197], v[48:51]
	v_mfma_f32_16x16x32_bf16 v[36:39], v[170:173], v[202:205], v[36:39]
	v_mfma_f32_16x16x32_bf16 v[32:35], v[186:189], v[202:205], v[32:35]
	v_mfma_f32_16x16x32_bf16 v[20:23], v[170:173], v[210:213], v[20:23]
	v_mfma_f32_16x16x32_bf16 v[16:19], v[186:189], v[210:213], v[16:19]
	v_mfma_f32_16x16x32_bf16 v[4:7], v[170:173], v[222:225], v[4:7]
	v_mfma_f32_16x16x32_bf16 v[0:3], v[186:189], v[222:225], v[0:3]
	s_barrier
	s_add_u32 s40, s40, 0x100
	s_addc_u32 s41, s41, 0
	s_cmp_ge_i32 s80, s65
	s_mov_b32 s42, s80
	s_cbranch_scc0 .LBB0_280

; #define PG8_STAGE(bufoff, gbase, voff) do { _Pragma("unroll") for (int _i = 0; _i < 2; ++_i) \
;         __builtin_amdgcn_global_load_lds((const unsigned*)((const char*)(gbase) + (voff)[_i]), (LAS unsigned*)(lds + (bufoff) + ldsw + _i * 8192), 16, 0, 0); } while (0)
; #define PG8_LDA(dst, b, h) do { _Pragma("unroll") for (int m = 0; m < 4; ++m) _Pragma("unroll") for (int k = 0; k < 2; ++k) dst[m][k] = *(const LAS bf16x8*)(lds + PG8_SA(b, h) + aoff + m * 2048 + k * 1024); } while (0)
; #define PG8_LDB(dst, b, h) do { _Pragma("unroll") for (int n = 0; n < 2; ++n) _Pragma("unroll") for (int k = 0; k < 2; ++k) dst[n][k] = *(const LAS bf16x8*)(lds + PG8_SB(b, h) + boff + n * 2048 + k * 1024); } while (0)
; #define PG8_MMA(ai, bj, At, Bt) do { __builtin_amdgcn_s_setprio(1); _Pragma("unroll") for (int m = 0; m < 4; ++m) _Pragma("unroll") for (int n = 0; n < 2; ++n) _Pragma("unroll") for (int k = 0; k < 2; ++k) \
;         acc[ai][bj][m][n] = __builtin_amdgcn_mfma_f32_16x16x32_bf16(Bt[n][k], At[m][k], acc[ai][bj][m][n], 0, 0, 0); __builtin_amdgcn_s_setprio(0); } while (0)
; #define PG8_WAIT_V(n) asm volatile("s_waitcnt vmcnt(" #n ")" ::: "memory")
; #define PG8_WAIT_L(n) asm volatile("s_waitcnt lgkmcnt(" #n ")" ::: "memory")
; #define PG8_BAR __builtin_amdgcn_s_barrier()
; #define PG8_SCHED __builtin_amdgcn_sched_barrier(0)
; template <class Epi, class Sched, bool ALIGN_EPI>
; __device__ __forceinline__ void gemm_phase(LAS unsigned char* lds, const Gemm g, const Sched& S, const Epi& E) {
;     ...
;             const bool last = (t == nt - 2);
;             const char* a1 = cA + (size_t)(t + 1) * kstep;
;             const char* a2 = last ? nA : cA + (size_t)(t + 2) * kstep; const char* b2 = last ? nB : cB + (size_t)(t + 2) * kstep;
;             const char* a3 = a2 + kstep; const char* b3 = b2 + kstep;
;             PG8_LDB(B0, 0, 0); PG8_LDB(B1, 0, 1); PG8_SCHED; PG8_LDA(At, 0, 0); PG8_STAGE(PG8_SA(1, 1), a1 + hA, voffA);
;             PG8_WAIT_V(8); PG8_WAIT_L(0); PG8_BAR; PG8_MMA(0, 0, At, B0); PG8_MMA(0, 1, At, B1); PG8_BAR; PG8_SCHED;
;             PG8_LDA(At, 0, 1); PG8_STAGE(PG8_SB(0, 0), b2, voffB); PG8_STAGE(PG8_SB(0, 1), b2 + hB, voffB); PG8_STAGE(PG8_SA(0, 0), a2, voffA);
;             PG8_WAIT_V(8); PG8_WAIT_L(0); PG8_BAR; PG8_MMA(1, 0, At, B0); PG8_MMA(1, 1, At, B1); PG8_BAR; PG8_SCHED;
.LBB0_361:
	ds_read_b128 v[144:147], v151
	ds_read_b128 v[156:159], v151 offset:1024
	ds_read_b128 v[160:163], v151 offset:2048
	ds_read_b128 v[164:167], v151 offset:3072
	ds_read_b128 v[168:171], v152
	ds_read_b128 v[172:175], v152 offset:1024
	ds_read_b128 v[176:179], v152 offset:2048
	ds_read_b128 v[180:183], v152 offset:3072
	s_add_u32 s18, s42, 0xffea0080
	s_addc_u32 s19, s43, -1
	s_cmpk_eq_i32 s84, 0x54
	s_cselect_b32 s63, s81, s19
	s_cselect_b32 s62, s82, s18
	s_cselect_b32 s61, s37, s45
	s_cselect_b32 s60, s83, s44
	v_lshl_add_u64 v[216:217], s[42:43], 0, v[136:137]
	s_add_i32 m0, s66, 0xc000
	ds_read_b128 v[184:187], v153
	ds_read_b128 v[188:191], v153 offset:1024
	ds_read_b128 v[192:195], v153 offset:2048
	ds_read_b128 v[196:199], v153 offset:3072
	ds_read_b128 v[200:203], v153 offset:4096
	ds_read_b128 v[204:207], v153 offset:5120
	ds_read_b128 v[208:211], v153 offset:6144
	ds_read_b128 v[212:215], v153 offset:7168
	global_load_lds_dwordx4 v[216:217], off
	s_add_i32 m0, s66, 0xe000
	v_lshl_add_u64 v[216:217], s[42:43], 0, v[138:139]
	global_load_lds_dwordx4 v[216:217], off
	s_waitcnt vmcnt(8) lgkmcnt(0)
	s_barrier
	v_mfma_f32_16x16x32_bf16 v[124:127], v[144:147], v[184:187], v[124:127]
	v_mfma_f32_16x16x32_bf16 v[120:123], v[160:163], v[184:187], v[120:123]
	v_mfma_f32_16x16x32_bf16 v[108:111], v[144:147], v[192:195], v[108:111]
	v_mfma_f32_16x16x32_bf16 v[104:107], v[160:163], v[192:195], v[104:107]
	v_mfma_f32_16x16x32_bf16 v[92:95], v[144:147], v[200:203], v[92:95]
	v_mfma_f32_16x16x32_bf16 v[88:91], v[160:163], v[200:203], v[88:91]
	v_mfma_f32_16x16x32_bf16 v[76:79], v[144:147], v[208:211], v[76:79]
	v_mfma_f32_16x16x32_bf16 v[72:75], v[160:163], v[208:211], v[72:75]
	v_mfma_f32_16x16x32_bf16 v[124:127], v[156:159], v[188:191], v[124:127]
	v_mfma_f32_16x16x32_bf16 v[120:123], v[164:167], v[188:191], v[120:123]
	v_mfma_f32_16x16x32_bf16 v[108:111], v[156:159], v[196:199], v[108:111]
	v_mfma_f32_16x16x32_bf16 v[104:107], v[164:167], v[196:199], v[104:107]
	v_mfma_f32_16x16x32_bf16 v[92:95], v[156:159], v[204:207], v[92:95]
	v_mfma_f32_16x16x32_bf16 v[88:91], v[164:167], v[204:207], v[88:91]
	v_mfma_f32_16x16x32_bf16 v[76:79], v[156:159], v[212:215], v[76:79]
	v_mfma_f32_16x16x32_bf16 v[72:75], v[164:167], v[212:215], v[72:75]
	v_mfma_f32_16x16x32_bf16 v[116:119], v[168:171], v[184:187], v[116:119]
	v_mfma_f32_16x16x32_bf16 v[112:115], v[176:179], v[184:187], v[112:115]
	v_mfma_f32_16x16x32_bf16 v[100:103], v[168:171], v[192:195], v[100:103]
	v_mfma_f32_16x16x32_bf16 v[96:99], v[176:179], v[192:195], v[96:99]
	v_mfma_f32_16x16x32_bf16 v[84:87], v[168:171], v[200:203], v[84:87]
	v_mfma_f32_16x16x32_bf16 v[80:83], v[176:179], v[200:203], v[80:83]
	v_mfma_f32_16x16x32_bf16 v[68:71], v[168:171], v[208:211], v[68:71]
	v_mfma_f32_16x16x32_bf16 v[64:67], v[176:179], v[208:211], v[64:67]
	v_mfma_f32_16x16x32_bf16 v[116:119], v[172:175], v[188:191], v[116:119]
	v_mfma_f32_16x16x32_bf16 v[112:115], v[180:183], v[188:191], v[112:115]
	v_mfma_f32_16x16x32_bf16 v[100:103], v[172:175], v[196:199], v[100:103]
	v_mfma_f32_16x16x32_bf16 v[96:99], v[180:183], v[196:199], v[96:99]
	v_mfma_f32_16x16x32_bf16 v[84:87], v[172:175], v[204:207], v[84:87]
	v_mfma_f32_16x16x32_bf16 v[80:83], v[180:183], v[204:207], v[80:83]
	v_mfma_f32_16x16x32_bf16 v[68:71], v[172:175], v[212:215], v[68:71]
	v_mfma_f32_16x16x32_bf16 v[64:67], v[180:183], v[212:215], v[64:67]
	s_barrier
	s_add_i32 s18, s76, s65
	v_lshl_add_u64 v[216:217], s[60:61], 0, v[130:131]
	s_mov_b32 m0, s18
	ds_read_b128 v[184:187], v153 offset:16384
	ds_read_b128 v[188:191], v153 offset:17408
	ds_read_b128 v[192:195], v153 offset:18432
	ds_read_b128 v[196:199], v153 offset:19456
	ds_read_b128 v[200:203], v153 offset:20480
	ds_read_b128 v[204:207], v153 offset:21504
	ds_read_b128 v[208:211], v153 offset:22528
	ds_read_b128 v[212:215], v153 offset:23552
	global_load_lds_dwordx4 v[216:217], off
	s_add_i32 m0, s18, 0x2000
	s_add_u32 s46, s60, 0x160000
	v_lshl_add_u64 v[218:219], s[60:61], 0, v[134:135]
	s_addc_u32 s47, s61, 0
	s_add_i32 s18, s77, s65
	global_load_lds_dwordx4 v[218:219], off
	v_lshl_add_u64 v[222:223], s[46:47], 0, v[130:131]
	s_mov_b32 m0, s18
	v_lshl_add_u64 v[224:225], s[62:63], 0, v[132:133]
	global_load_lds_dwordx4 v[222:223], off
	s_add_i32 m0, s18, 0x2000
	v_lshl_add_u64 v[222:223], s[46:47], 0, v[134:135]
	global_load_lds_dwordx4 v[222:223], off
	s_mov_b32 m0, s66
	v_lshl_add_u64 v[222:223], s[62:63], 0, v[128:129]
	global_load_lds_dwordx4 v[222:223], off
	s_mov_b32 m0, s67
	s_nop 0
	global_load_lds_dwordx4 v[224:225], off
	s_waitcnt vmcnt(8) lgkmcnt(0)
	s_barrier
; #define PG8_STAGE(bufoff, gbase, voff) do { _Pragma("unroll") for (int _i = 0; _i < 2; ++_i) \
;         __builtin_amdgcn_global_load_lds((const unsigned*)((const char*)(gbase) + (voff)[_i]), (LAS unsigned*)(lds + (bufoff) + ldsw + _i * 8192), 16, 0, 0); } while (0)
; #define PG8_LDA(dst, b, h) do { _Pragma("unroll") for (int m = 0; m < 4; ++m) _Pragma("unroll") for (int k = 0; k < 2; ++k) dst[m][k] = *(const LAS bf16x8*)(lds + PG8_SA(b, h) + aoff + m * 2048 + k * 1024); } while (0)
; #define PG8_LDB(dst, b, h) do { _Pragma("unroll") for (int n = 0; n < 2; ++n) _Pragma("unroll") for (int k = 0; k < 2; ++k) dst[n][k] = *(const LAS bf16x8*)(lds + PG8_SB(b, h) + boff + n * 2048 + k * 1024); } while (0)
; #define PG8_MMA(ai, bj, At, Bt) do { __builtin_amdgcn_s_setprio(1); _Pragma("unroll") for (int m = 0; m < 4; ++m) _Pragma("unroll") for (int n = 0; n < 2; ++n) _Pragma("unroll") for (int k = 0; k < 2; ++k) \
;         acc[ai][bj][m][n] = __builtin_amdgcn_mfma_f32_16x16x32_bf16(Bt[n][k], At[m][k], acc[ai][bj][m][n], 0, 0, 0); __builtin_amdgcn_s_setprio(0); } while (0)
; #define PG8_WAIT_V(n) asm volatile("s_waitcnt vmcnt(" #n ")" ::: "memory")
; #define PG8_WAIT_L(n) asm volatile("s_waitcnt lgkmcnt(" #n ")" ::: "memory")
; #define PG8_BAR __builtin_amdgcn_s_barrier()
; #define PG8_SCHED __builtin_amdgcn_sched_barrier(0)
; template <class Epi, class Sched, bool ALIGN_EPI>
; __device__ __forceinline__ void gemm_phase(LAS unsigned char* lds, const Gemm g, const Sched& S, const Epi& E) {
;     ...
;             PG8_WAIT_V(8); PG8_WAIT_L(0); PG8_BAR; PG8_MMA(1, 0, At, B0); PG8_MMA(1, 1, At, B1); PG8_BAR; PG8_SCHED;
;             PG8_LDB(B0, 1, 0); PG8_LDB(B1, 1, 1); PG8_SCHED; PG8_LDA(At, 1, 0); PG8_STAGE(PG8_SA(0, 1), a2 + hA, voffA);
;             PG8_WAIT_V(8); PG8_WAIT_L(0); PG8_BAR; PG8_MMA(0, 0, At, B0); PG8_MMA(0, 1, At, B1); PG8_BAR; PG8_SCHED;
	v_mfma_f32_16x16x32_bf16 v[60:63], v[144:147], v[184:187], v[60:63]
	v_mfma_f32_16x16x32_bf16 v[56:59], v[160:163], v[184:187], v[56:59]
	v_mfma_f32_16x16x32_bf16 v[44:47], v[144:147], v[192:195], v[44:47]
	v_mfma_f32_16x16x32_bf16 v[40:43], v[160:163], v[192:195], v[40:43]
	v_mfma_f32_16x16x32_bf16 v[28:31], v[144:147], v[200:203], v[28:31]
	v_mfma_f32_16x16x32_bf16 v[24:27], v[160:163], v[200:203], v[24:27]
	v_mfma_f32_16x16x32_bf16 v[12:15], v[144:147], v[208:211], v[12:15]
	v_mfma_f32_16x16x32_bf16 v[8:11], v[160:163], v[208:211], v[8:11]
	v_mfma_f32_16x16x32_bf16 v[60:63], v[156:159], v[188:191], v[60:63]
	v_mfma_f32_16x16x32_bf16 v[56:59], v[164:167], v[188:191], v[56:59]
	v_mfma_f32_16x16x32_bf16 v[44:47], v[156:159], v[196:199], v[44:47]
	v_mfma_f32_16x16x32_bf16 v[40:43], v[164:167], v[196:199], v[40:43]
	v_mfma_f32_16x16x32_bf16 v[28:31], v[156:159], v[204:207], v[28:31]
	v_mfma_f32_16x16x32_bf16 v[24:27], v[164:167], v[204:207], v[24:27]
	v_mfma_f32_16x16x32_bf16 v[12:15], v[156:159], v[212:215], v[12:15]
	v_mfma_f32_16x16x32_bf16 v[8:11], v[164:167], v[212:215], v[8:11]
	v_mfma_f32_16x16x32_bf16 v[52:55], v[168:171], v[184:187], v[52:55]
	v_mfma_f32_16x16x32_bf16 v[48:51], v[176:179], v[184:187], v[48:51]
	v_mfma_f32_16x16x32_bf16 v[36:39], v[168:171], v[192:195], v[36:39]
	v_mfma_f32_16x16x32_bf16 v[32:35], v[176:179], v[192:195], v[32:35]
	v_mfma_f32_16x16x32_bf16 v[20:23], v[168:171], v[200:203], v[20:23]
	v_mfma_f32_16x16x32_bf16 v[16:19], v[176:179], v[200:203], v[16:19]
	v_mfma_f32_16x16x32_bf16 v[4:7], v[168:171], v[208:211], v[4:7]
	v_mfma_f32_16x16x32_bf16 v[0:3], v[176:179], v[208:211], v[0:3]
	v_mfma_f32_16x16x32_bf16 v[52:55], v[172:175], v[188:191], v[52:55]
	v_mfma_f32_16x16x32_bf16 v[48:51], v[180:183], v[188:191], v[48:51]
	v_mfma_f32_16x16x32_bf16 v[36:39], v[172:175], v[196:199], v[36:39]
	v_mfma_f32_16x16x32_bf16 v[32:35], v[180:183], v[196:199], v[32:35]
	v_mfma_f32_16x16x32_bf16 v[20:23], v[172:175], v[204:207], v[20:23]
	v_mfma_f32_16x16x32_bf16 v[16:19], v[180:183], v[204:207], v[16:19]
	v_mfma_f32_16x16x32_bf16 v[4:7], v[172:175], v[212:215], v[4:7]
	v_mfma_f32_16x16x32_bf16 v[0:3], v[180:183], v[212:215], v[0:3]
	s_barrier
	s_add_i32 s18, 0, 0x18000
	v_add_u32_e32 v155, s18, v149
	s_add_i32 s19, 0, 0x1c000
	ds_read_b128 v[144:147], v155
	ds_read_b128 v[156:159], v155 offset:1024
	ds_read_b128 v[160:163], v155 offset:2048
	ds_read_b128 v[164:167], v155 offset:3072
	v_add_u32_e32 v155, s19, v149
	ds_read_b128 v[168:171], v155
	ds_read_b128 v[172:175], v155 offset:1024
	ds_read_b128 v[176:179], v155 offset:2048
	ds_read_b128 v[180:183], v155 offset:3072
	s_add_u32 s46, s62, 0x160000
	s_addc_u32 s47, s63, 0
	s_mov_b32 m0, s68
	v_lshl_add_u64 v[226:227], s[46:47], 0, v[128:129]
	ds_read_b128 v[184:187], v153 offset:32768
	ds_read_b128 v[188:191], v153 offset:33792
	ds_read_b128 v[192:195], v153 offset:34816
	ds_read_b128 v[196:199], v153 offset:35840
	ds_read_b128 v[200:203], v153 offset:36864
	ds_read_b128 v[204:207], v153 offset:37888
	ds_read_b128 v[208:211], v153 offset:38912
	ds_read_b128 v[212:215], v153 offset:39936
	global_load_lds_dwordx4 v[226:227], off
	s_mov_b32 m0, s69
	v_lshl_add_u64 v[226:227], s[46:47], 0, v[132:133]
	global_load_lds_dwordx4 v[226:227], off
	s_waitcnt vmcnt(8) lgkmcnt(0)
	s_barrier
	v_mfma_f32_16x16x32_bf16 v[124:127], v[144:147], v[184:187], v[124:127]
	v_mfma_f32_16x16x32_bf16 v[120:123], v[160:163], v[184:187], v[120:123]
	v_mfma_f32_16x16x32_bf16 v[108:111], v[144:147], v[192:195], v[108:111]
	v_mfma_f32_16x16x32_bf16 v[104:107], v[160:163], v[192:195], v[104:107]
	v_mfma_f32_16x16x32_bf16 v[92:95], v[144:147], v[200:203], v[92:95]
	v_mfma_f32_16x16x32_bf16 v[88:91], v[160:163], v[200:203], v[88:91]
	v_mfma_f32_16x16x32_bf16 v[76:79], v[144:147], v[208:211], v[76:79]
	v_mfma_f32_16x16x32_bf16 v[72:75], v[160:163], v[208:211], v[72:75]
	v_mfma_f32_16x16x32_bf16 v[124:127], v[156:159], v[188:191], v[124:127]
	v_mfma_f32_16x16x32_bf16 v[120:123], v[164:167], v[188:191], v[120:123]
	v_mfma_f32_16x16x32_bf16 v[108:111], v[156:159], v[196:199], v[108:111]
	v_mfma_f32_16x16x32_bf16 v[104:107], v[164:167], v[196:199], v[104:107]
	v_mfma_f32_16x16x32_bf16 v[92:95], v[156:159], v[204:207], v[92:95]
	v_mfma_f32_16x16x32_bf16 v[88:91], v[164:167], v[204:207], v[88:91]
	v_mfma_f32_16x16x32_bf16 v[76:79], v[156:159], v[212:215], v[76:79]
	v_mfma_f32_16x16x32_bf16 v[72:75], v[164:167], v[212:215], v[72:75]
	v_mfma_f32_16x16x32_bf16 v[116:119], v[168:171], v[184:187], v[116:119]
	v_mfma_f32_16x16x32_bf16 v[112:115], v[176:179], v[184:187], v[112:115]
	v_mfma_f32_16x16x32_bf16 v[100:103], v[168:171], v[192:195], v[100:103]
	v_mfma_f32_16x16x32_bf16 v[96:99], v[176:179], v[192:195], v[96:99]
	v_mfma_f32_16x16x32_bf16 v[84:87], v[168:171], v[200:203], v[84:87]
	v_mfma_f32_16x16x32_bf16 v[80:83], v[176:179], v[200:203], v[80:83]
	v_mfma_f32_16x16x32_bf16 v[68:71], v[168:171], v[208:211], v[68:71]
	v_mfma_f32_16x16x32_bf16 v[64:67], v[176:179], v[208:211], v[64:67]
	v_mfma_f32_16x16x32_bf16 v[116:119], v[172:175], v[188:191], v[116:119]
	v_mfma_f32_16x16x32_bf16 v[112:115], v[180:183], v[188:191], v[112:115]
	v_mfma_f32_16x16x32_bf16 v[100:103], v[172:175], v[196:199], v[100:103]
	v_mfma_f32_16x16x32_bf16 v[96:99], v[180:183], v[196:199], v[96:99]
	v_mfma_f32_16x16x32_bf16 v[84:87], v[172:175], v[204:207], v[84:87]
	v_mfma_f32_16x16x32_bf16 v[80:83], v[180:183], v[204:207], v[80:83]
	v_mfma_f32_16x16x32_bf16 v[68:71], v[172:175], v[212:215], v[68:71]
	v_mfma_f32_16x16x32_bf16 v[64:67], v[180:183], v[212:215], v[64:67]
	s_barrier
; #define PG8_STAGE(bufoff, gbase, voff) do { _Pragma("unroll") for (int _i = 0; _i < 2; ++_i) \
;         __builtin_amdgcn_global_load_lds((const unsigned*)((const char*)(gbase) + (voff)[_i]), (LAS unsigned*)(lds + (bufoff) + ldsw + _i * 8192), 16, 0, 0); } while (0)
; #define PG8_LDA(dst, b, h) do { _Pragma("unroll") for (int m = 0; m < 4; ++m) _Pragma("unroll") for (int k = 0; k < 2; ++k) dst[m][k] = *(const LAS bf16x8*)(lds + PG8_SA(b, h) + aoff + m * 2048 + k * 1024); } while (0)
; #define PG8_MMA(ai, bj, At, Bt) do { __builtin_amdgcn_s_setprio(1); _Pragma("unroll") for (int m = 0; m < 4; ++m) _Pragma("unroll") for (int n = 0; n < 2; ++n) _Pragma("unroll") for (int k = 0; k < 2; ++k) \
;         acc[ai][bj][m][n] = __builtin_amdgcn_mfma_f32_16x16x32_bf16(Bt[n][k], At[m][k], acc[ai][bj][m][n], 0, 0, 0); __builtin_amdgcn_s_setprio(0); } while (0)
; #define PG8_WAIT_V(n) asm volatile("s_waitcnt vmcnt(" #n ")" ::: "memory")
; #define PG8_WAIT_L(n) asm volatile("s_waitcnt lgkmcnt(" #n ")" ::: "memory")
; #define PG8_BAR __builtin_amdgcn_s_barrier()
; #define PG8_SCHED __builtin_amdgcn_sched_barrier(0)
; template <class Epi, class Sched, bool ALIGN_EPI>
; __device__ __forceinline__ void gemm_phase(LAS unsigned char* lds, const Gemm g, const Sched& S, const Epi& E) {
;     ...
;             PG8_LDA(At, 1, 1); PG8_STAGE(PG8_SB(1, 0), b3, voffB); PG8_STAGE(PG8_SB(1, 1), b3 + hB, voffB); PG8_STAGE(PG8_SA(1, 0), a3, voffA);
;             PG8_WAIT_V(8); PG8_WAIT_L(0); PG8_BAR; PG8_MMA(1, 0, At, B0); PG8_MMA(1, 1, At, B1); PG8_BAR; PG8_SCHED;
;         }
;         if constexpr (ALIGN_EPI) { if (wr == 0) PG8_BAR; }
	s_add_i32 s18, s18, s65
	v_lshl_add_u64 v[216:217], v[216:217], 0, s[24:25]
	s_mov_b32 m0, s18
	ds_read_b128 v[184:187], v153 offset:49152
	ds_read_b128 v[188:191], v153 offset:50176
	ds_read_b128 v[192:195], v153 offset:51200
	ds_read_b128 v[196:199], v153 offset:52224
	ds_read_b128 v[200:203], v153 offset:53248
	ds_read_b128 v[204:207], v153 offset:54272
	ds_read_b128 v[208:211], v153 offset:55296
	ds_read_b128 v[212:215], v153 offset:56320
	global_load_lds_dwordx4 v[216:217], off
	s_add_i32 m0, s18, 0x2000
	s_add_u32 s46, s60, 0x160080
	v_lshl_add_u64 v[216:217], v[218:219], 0, s[24:25]
	s_addc_u32 s47, s61, 0
	s_add_i32 s18, s19, s65
	global_load_lds_dwordx4 v[216:217], off
	s_mov_b32 m0, s18
	v_lshl_add_u64 v[216:217], s[46:47], 0, v[130:131]
	global_load_lds_dwordx4 v[216:217], off
	s_add_i32 m0, s18, 0x2000
	v_lshl_add_u64 v[216:217], s[46:47], 0, v[134:135]
	global_load_lds_dwordx4 v[216:217], off
	s_mov_b32 m0, s71
	v_lshl_add_u64 v[216:217], v[222:223], 0, s[24:25]
	global_load_lds_dwordx4 v[216:217], off
	s_mov_b32 m0, s72
	v_lshl_add_u64 v[216:217], v[224:225], 0, s[24:25]
	global_load_lds_dwordx4 v[216:217], off
	s_waitcnt vmcnt(8) lgkmcnt(0)
	s_barrier
	v_mfma_f32_16x16x32_bf16 v[60:63], v[144:147], v[184:187], v[60:63]
	v_mfma_f32_16x16x32_bf16 v[56:59], v[160:163], v[184:187], v[56:59]
	v_mfma_f32_16x16x32_bf16 v[44:47], v[144:147], v[192:195], v[44:47]
	v_mfma_f32_16x16x32_bf16 v[40:43], v[160:163], v[192:195], v[40:43]
	v_mfma_f32_16x16x32_bf16 v[28:31], v[144:147], v[200:203], v[28:31]
	v_mfma_f32_16x16x32_bf16 v[24:27], v[160:163], v[200:203], v[24:27]
	v_mfma_f32_16x16x32_bf16 v[12:15], v[144:147], v[208:211], v[12:15]
	v_mfma_f32_16x16x32_bf16 v[8:11], v[160:163], v[208:211], v[8:11]
	v_mfma_f32_16x16x32_bf16 v[60:63], v[156:159], v[188:191], v[60:63]
	v_mfma_f32_16x16x32_bf16 v[56:59], v[164:167], v[188:191], v[56:59]
	v_mfma_f32_16x16x32_bf16 v[44:47], v[156:159], v[196:199], v[44:47]
	v_mfma_f32_16x16x32_bf16 v[40:43], v[164:167], v[196:199], v[40:43]
	v_mfma_f32_16x16x32_bf16 v[28:31], v[156:159], v[204:207], v[28:31]
	v_mfma_f32_16x16x32_bf16 v[24:27], v[164:167], v[204:207], v[24:27]
	v_mfma_f32_16x16x32_bf16 v[12:15], v[156:159], v[212:215], v[12:15]
	v_mfma_f32_16x16x32_bf16 v[8:11], v[164:167], v[212:215], v[8:11]
	v_mfma_f32_16x16x32_bf16 v[52:55], v[168:171], v[184:187], v[52:55]
	v_mfma_f32_16x16x32_bf16 v[48:51], v[176:179], v[184:187], v[48:51]
	v_mfma_f32_16x16x32_bf16 v[36:39], v[168:171], v[192:195], v[36:39]
	v_mfma_f32_16x16x32_bf16 v[32:35], v[176:179], v[192:195], v[32:35]
	v_mfma_f32_16x16x32_bf16 v[20:23], v[168:171], v[200:203], v[20:23]
	v_mfma_f32_16x16x32_bf16 v[16:19], v[176:179], v[200:203], v[16:19]
	v_mfma_f32_16x16x32_bf16 v[4:7], v[168:171], v[208:211], v[4:7]
	v_mfma_f32_16x16x32_bf16 v[0:3], v[176:179], v[208:211], v[0:3]
	v_mfma_f32_16x16x32_bf16 v[52:55], v[172:175], v[188:191], v[52:55]
	v_mfma_f32_16x16x32_bf16 v[48:51], v[180:183], v[188:191], v[48:51]
	v_mfma_f32_16x16x32_bf16 v[36:39], v[172:175], v[196:199], v[36:39]
	v_mfma_f32_16x16x32_bf16 v[32:35], v[180:183], v[196:199], v[32:35]
	v_mfma_f32_16x16x32_bf16 v[20:23], v[172:175], v[204:207], v[20:23]
	v_mfma_f32_16x16x32_bf16 v[16:19], v[180:183], v[204:207], v[16:19]
	v_mfma_f32_16x16x32_bf16 v[4:7], v[172:175], v[212:215], v[4:7]
	v_mfma_f32_16x16x32_bf16 v[0:3], v[180:183], v[212:215], v[0:3]
	s_barrier
	s_add_i32 s84, s84, 2
	s_add_u32 s42, s42, 0x100
	s_addc_u32 s43, s43, 0
	s_add_u32 s44, s44, 0x100
	s_addc_u32 s45, s45, 0
	s_cmpk_gt_u32 s84, 0x55
	s_cbranch_scc0 .LBB0_361
	s_and_b64 vcc, exec, s[26:27]
	s_cbranch_vccz .LBB0_364
	s_barrier

; #define PG8_STAGE(bufoff, gbase, voff) do { _Pragma("unroll") for (int _i = 0; _i < 2; ++_i) \
;         __builtin_amdgcn_global_load_lds((const unsigned*)((const char*)(gbase) + (voff)[_i]), (LAS unsigned*)(lds + (bufoff) + ldsw + _i * 8192), 16, 0, 0); } while (0)
; #define PG8_LDA(dst, b, h) do { _Pragma("unroll") for (int m = 0; m < 4; ++m) _Pragma("unroll") for (int k = 0; k < 2; ++k) dst[m][k] = *(const LAS bf16x8*)(lds + PG8_SA(b, h) + aoff + m * 2048 + k * 1024); } while (0)
; #define PG8_LDB(dst, b, h) do { _Pragma("unroll") for (int n = 0; n < 2; ++n) _Pragma("unroll") for (int k = 0; k < 2; ++k) dst[n][k] = *(const LAS bf16x8*)(lds + PG8_SB(b, h) + boff + n * 2048 + k * 1024); } while (0)
; #define PG8_MMA(ai, bj, At, Bt) do { __builtin_amdgcn_s_setprio(1); _Pragma("unroll") for (int m = 0; m < 4; ++m) _Pragma("unroll") for (int n = 0; n < 2; ++n) _Pragma("unroll") for (int k = 0; k < 2; ++k) \
;         acc[ai][bj][m][n] = __builtin_amdgcn_mfma_f32_16x16x32_bf16(Bt[n][k], At[m][k], acc[ai][bj][m][n], 0, 0, 0); __builtin_amdgcn_s_setprio(0); } while (0)
; #define PG8_WAIT_V(n) asm volatile("s_waitcnt vmcnt(" #n ")" ::: "memory")
; #define PG8_WAIT_L(n) asm volatile("s_waitcnt lgkmcnt(" #n ")" ::: "memory")
; #define PG8_BAR __builtin_amdgcn_s_barrier()
; #define PG8_SCHED __builtin_amdgcn_sched_barrier(0)
; template <class Epi, class Sched, bool ALIGN_EPI>
; __device__ __forceinline__ void gemm_phase(LAS unsigned char* lds, const Gemm g, const Sched& S, const Epi& E) {
;     ...
;             const bool last = (t == nt - 2);
;             const char* a1 = cA + (size_t)(t + 1) * kstep;
;             const char* a2 = last ? nA : cA + (size_t)(t + 2) * kstep; const char* b2 = last ? nB : cB + (size_t)(t + 2) * kstep;
;             const char* a3 = a2 + kstep; const char* b3 = b2 + kstep;
;             PG8_LDB(B0, 0, 0); PG8_LDB(B1, 0, 1); PG8_SCHED; PG8_LDA(At, 0, 0); PG8_STAGE(PG8_SA(1, 1), a1 + hA, voffA);
;             PG8_WAIT_V(8); PG8_WAIT_L(0); PG8_BAR; PG8_MMA(0, 0, At, B0); PG8_MMA(0, 1, At, B1); PG8_BAR; PG8_SCHED;
;             PG8_LDA(At, 0, 1); PG8_STAGE(PG8_SB(0, 0), b2, voffB); PG8_STAGE(PG8_SB(0, 1), b2 + hB, voffB); PG8_STAGE(PG8_SA(0, 0), a2, voffA);
;             PG8_WAIT_V(8); PG8_WAIT_L(0); PG8_BAR; PG8_MMA(1, 0, At, B0); PG8_MMA(1, 1, At, B1); PG8_BAR; PG8_SCHED;
.LBB0_466:
	ds_read_b128 v[128:131], v173
	ds_read_b128 v[132:135], v173 offset:1024
	ds_read_b128 v[160:163], v173 offset:2048
	ds_read_b128 v[168:171], v173 offset:3072
	ds_read_b128 v[176:179], v175
	s_waitcnt lgkmcnt(0)
	ds_read_b128 v[182:185], v175 offset:1024
	ds_read_b128 v[186:189], v175 offset:2048
	ds_read_b128 v[190:193], v175 offset:3072
	s_add_u32 s18, s6, 0xfff80080
	s_addc_u32 s19, s7, -1
	s_cmp_eq_u32 s46, 28
	s_cselect_b32 s83, vcc_lo, s19
	s_cselect_b32 s82, vcc_hi, s18
	s_cselect_b32 s81, s75, s45
	s_cselect_b32 s80, s87, s44
	v_lshl_add_u64 v[156:157], s[6:7], 0, v[148:149]
	s_add_i32 m0, s61, 0xc000
	ds_read_b128 v[194:197], v181
	ds_read_b128 v[198:201], v181 offset:1024
	ds_read_b128 v[202:205], v181 offset:2048
	ds_read_b128 v[206:209], v181 offset:3072
	ds_read_b128 v[210:213], v181 offset:4096
	ds_read_b128 v[214:217], v181 offset:5120
	ds_read_b128 v[224:227], v181 offset:6144
	ds_read_b128 v[228:231], v181 offset:7168
	global_load_lds_dwordx4 v[156:157], off
	s_add_i32 m0, s61, 0xe000
	v_lshl_add_u64 v[156:157], s[6:7], 0, v[150:151]
	global_load_lds_dwordx4 v[156:157], off
	s_waitcnt vmcnt(8) lgkmcnt(0)
	s_barrier
	v_mfma_f32_16x16x32_bf16 v[124:127], v[128:131], v[194:197], v[124:127]
	v_mfma_f32_16x16x32_bf16 v[116:119], v[160:163], v[194:197], v[116:119]
	v_mfma_f32_16x16x32_bf16 v[108:111], v[128:131], v[202:205], v[108:111]
	v_mfma_f32_16x16x32_bf16 v[100:103], v[160:163], v[202:205], v[100:103]
	v_mfma_f32_16x16x32_bf16 v[92:95], v[128:131], v[210:213], v[92:95]
	v_mfma_f32_16x16x32_bf16 v[84:87], v[160:163], v[210:213], v[84:87]
	v_mfma_f32_16x16x32_bf16 v[76:79], v[128:131], v[224:227], v[76:79]
	v_mfma_f32_16x16x32_bf16 v[68:71], v[160:163], v[224:227], v[68:71]
	v_mfma_f32_16x16x32_bf16 v[124:127], v[132:135], v[198:201], v[124:127]
	v_mfma_f32_16x16x32_bf16 v[116:119], v[168:171], v[198:201], v[116:119]
	v_mfma_f32_16x16x32_bf16 v[108:111], v[132:135], v[206:209], v[108:111]
	v_mfma_f32_16x16x32_bf16 v[100:103], v[168:171], v[206:209], v[100:103]
	v_mfma_f32_16x16x32_bf16 v[92:95], v[132:135], v[214:217], v[92:95]
	v_mfma_f32_16x16x32_bf16 v[84:87], v[168:171], v[214:217], v[84:87]
	v_mfma_f32_16x16x32_bf16 v[76:79], v[132:135], v[228:231], v[76:79]
	v_mfma_f32_16x16x32_bf16 v[68:71], v[168:171], v[228:231], v[68:71]
	v_mfma_f32_16x16x32_bf16 v[120:123], v[176:179], v[194:197], v[120:123]
	v_mfma_f32_16x16x32_bf16 v[112:115], v[186:189], v[194:197], v[112:115]
	v_mfma_f32_16x16x32_bf16 v[104:107], v[176:179], v[202:205], v[104:107]
	v_mfma_f32_16x16x32_bf16 v[96:99], v[186:189], v[202:205], v[96:99]
	v_mfma_f32_16x16x32_bf16 v[88:91], v[176:179], v[210:213], v[88:91]
	v_mfma_f32_16x16x32_bf16 v[80:83], v[186:189], v[210:213], v[80:83]
	v_mfma_f32_16x16x32_bf16 v[72:75], v[176:179], v[224:227], v[72:75]
	v_mfma_f32_16x16x32_bf16 v[64:67], v[186:189], v[224:227], v[64:67]
	v_mfma_f32_16x16x32_bf16 v[120:123], v[182:185], v[198:201], v[120:123]
	v_mfma_f32_16x16x32_bf16 v[112:115], v[190:193], v[198:201], v[112:115]
	v_mfma_f32_16x16x32_bf16 v[104:107], v[182:185], v[206:209], v[104:107]
	v_mfma_f32_16x16x32_bf16 v[96:99], v[190:193], v[206:209], v[96:99]
	v_mfma_f32_16x16x32_bf16 v[88:91], v[182:185], v[214:217], v[88:91]
	v_mfma_f32_16x16x32_bf16 v[80:83], v[190:193], v[214:217], v[80:83]
	v_mfma_f32_16x16x32_bf16 v[72:75], v[182:185], v[228:231], v[72:75]
	v_mfma_f32_16x16x32_bf16 v[64:67], v[190:193], v[228:231], v[64:67]
	s_barrier
	s_add_i32 s18, s92, s59
	v_lshl_add_u64 v[156:157], s[80:81], 0, v[138:139]
	s_mov_b32 m0, s18
	ds_read_b128 v[194:197], v181 offset:16384
	ds_read_b128 v[198:201], v181 offset:17408
	ds_read_b128 v[202:205], v181 offset:18432
	ds_read_b128 v[206:209], v181 offset:19456
	ds_read_b128 v[210:213], v181 offset:20480
	ds_read_b128 v[214:217], v181 offset:21504
	ds_read_b128 v[224:227], v181 offset:22528
	ds_read_b128 v[228:231], v181 offset:23552
	global_load_lds_dwordx4 v[156:157], off
	s_add_i32 m0, s18, 0x2000
	s_add_u32 s18, s80, 0x80000
	v_lshl_add_u64 v[218:219], s[80:81], 0, v[142:143]
	s_addc_u32 s19, s81, 0
	s_add_i32 s47, s93, s59
	global_load_lds_dwordx4 v[218:219], off
	v_lshl_add_u64 v[232:233], s[18:19], 0, v[138:139]
	s_mov_b32 m0, s47
	v_lshl_add_u64 v[234:235], s[82:83], 0, v[140:141]
	global_load_lds_dwordx4 v[232:233], off
	s_add_i32 m0, s47, 0x2000
	v_lshl_add_u64 v[232:233], s[18:19], 0, v[142:143]
	global_load_lds_dwordx4 v[232:233], off
	s_mov_b32 m0, s61
	v_lshl_add_u64 v[232:233], s[82:83], 0, v[136:137]
	global_load_lds_dwordx4 v[232:233], off
	s_mov_b32 m0, s63
	s_nop 0
	global_load_lds_dwordx4 v[234:235], off
	s_waitcnt vmcnt(8) lgkmcnt(0)
	s_barrier
; #define PG8_STAGE(bufoff, gbase, voff) do { _Pragma("unroll") for (int _i = 0; _i < 2; ++_i) \
;         __builtin_amdgcn_global_load_lds((const unsigned*)((const char*)(gbase) + (voff)[_i]), (LAS unsigned*)(lds + (bufoff) + ldsw + _i * 8192), 16, 0, 0); } while (0)
; #define PG8_LDA(dst, b, h) do { _Pragma("unroll") for (int m = 0; m < 4; ++m) _Pragma("unroll") for (int k = 0; k < 2; ++k) dst[m][k] = *(const LAS bf16x8*)(lds + PG8_SA(b, h) + aoff + m * 2048 + k * 1024); } while (0)
; #define PG8_LDB(dst, b, h) do { _Pragma("unroll") for (int n = 0; n < 2; ++n) _Pragma("unroll") for (int k = 0; k < 2; ++k) dst[n][k] = *(const LAS bf16x8*)(lds + PG8_SB(b, h) + boff + n * 2048 + k * 1024); } while (0)
; #define PG8_MMA(ai, bj, At, Bt) do { __builtin_amdgcn_s_setprio(1); _Pragma("unroll") for (int m = 0; m < 4; ++m) _Pragma("unroll") for (int n = 0; n < 2; ++n) _Pragma("unroll") for (int k = 0; k < 2; ++k) \
;         acc[ai][bj][m][n] = __builtin_amdgcn_mfma_f32_16x16x32_bf16(Bt[n][k], At[m][k], acc[ai][bj][m][n], 0, 0, 0); __builtin_amdgcn_s_setprio(0); } while (0)
; #define PG8_WAIT_V(n) asm volatile("s_waitcnt vmcnt(" #n ")" ::: "memory")
; #define PG8_WAIT_L(n) asm volatile("s_waitcnt lgkmcnt(" #n ")" ::: "memory")
; #define PG8_BAR __builtin_amdgcn_s_barrier()
; #define PG8_SCHED __builtin_amdgcn_sched_barrier(0)
; template <class Epi, class Sched, bool ALIGN_EPI>
; __device__ __forceinline__ void gemm_phase(LAS unsigned char* lds, const Gemm g, const Sched& S, const Epi& E) {
;     ...
;             PG8_WAIT_V(8); PG8_WAIT_L(0); PG8_BAR; PG8_MMA(1, 0, At, B0); PG8_MMA(1, 1, At, B1); PG8_BAR; PG8_SCHED;
;             PG8_LDB(B0, 1, 0); PG8_LDB(B1, 1, 1); PG8_SCHED; PG8_LDA(At, 1, 0); PG8_STAGE(PG8_SA(0, 1), a2 + hA, voffA);
;             PG8_WAIT_V(8); PG8_WAIT_L(0); PG8_BAR; PG8_MMA(0, 0, At, B0); PG8_MMA(0, 1, At, B1); PG8_BAR; PG8_SCHED;
	v_mfma_f32_16x16x32_bf16 v[60:63], v[128:131], v[194:197], v[60:63]
	v_mfma_f32_16x16x32_bf16 v[52:55], v[160:163], v[194:197], v[52:55]
	v_mfma_f32_16x16x32_bf16 v[44:47], v[128:131], v[202:205], v[44:47]
	v_mfma_f32_16x16x32_bf16 v[36:39], v[160:163], v[202:205], v[36:39]
	v_mfma_f32_16x16x32_bf16 v[28:31], v[128:131], v[210:213], v[28:31]
	v_mfma_f32_16x16x32_bf16 v[20:23], v[160:163], v[210:213], v[20:23]
	v_mfma_f32_16x16x32_bf16 v[12:15], v[128:131], v[224:227], v[12:15]
	v_mfma_f32_16x16x32_bf16 v[4:7], v[160:163], v[224:227], v[4:7]
	v_mfma_f32_16x16x32_bf16 v[60:63], v[132:135], v[198:201], v[60:63]
	v_mfma_f32_16x16x32_bf16 v[52:55], v[168:171], v[198:201], v[52:55]
	v_mfma_f32_16x16x32_bf16 v[44:47], v[132:135], v[206:209], v[44:47]
	v_mfma_f32_16x16x32_bf16 v[36:39], v[168:171], v[206:209], v[36:39]
	v_mfma_f32_16x16x32_bf16 v[28:31], v[132:135], v[214:217], v[28:31]
	v_mfma_f32_16x16x32_bf16 v[20:23], v[168:171], v[214:217], v[20:23]
	v_mfma_f32_16x16x32_bf16 v[12:15], v[132:135], v[228:231], v[12:15]
	v_mfma_f32_16x16x32_bf16 v[4:7], v[168:171], v[228:231], v[4:7]
	v_mfma_f32_16x16x32_bf16 v[56:59], v[176:179], v[194:197], v[56:59]
	v_mfma_f32_16x16x32_bf16 v[48:51], v[186:189], v[194:197], v[48:51]
	v_mfma_f32_16x16x32_bf16 v[40:43], v[176:179], v[202:205], v[40:43]
	v_mfma_f32_16x16x32_bf16 v[32:35], v[186:189], v[202:205], v[32:35]
	v_mfma_f32_16x16x32_bf16 v[24:27], v[176:179], v[210:213], v[24:27]
	v_mfma_f32_16x16x32_bf16 v[16:19], v[186:189], v[210:213], v[16:19]
	v_mfma_f32_16x16x32_bf16 v[8:11], v[176:179], v[224:227], v[8:11]
	v_mfma_f32_16x16x32_bf16 v[0:3], v[186:189], v[224:227], v[0:3]
	v_mfma_f32_16x16x32_bf16 v[56:59], v[182:185], v[198:201], v[56:59]
	v_mfma_f32_16x16x32_bf16 v[48:51], v[190:193], v[198:201], v[48:51]
	v_mfma_f32_16x16x32_bf16 v[40:43], v[182:185], v[206:209], v[40:43]
	v_mfma_f32_16x16x32_bf16 v[32:35], v[190:193], v[206:209], v[32:35]
	v_mfma_f32_16x16x32_bf16 v[24:27], v[182:185], v[214:217], v[24:27]
	v_mfma_f32_16x16x32_bf16 v[16:19], v[190:193], v[214:217], v[16:19]
	v_mfma_f32_16x16x32_bf16 v[8:11], v[182:185], v[228:231], v[8:11]
	v_mfma_f32_16x16x32_bf16 v[0:3], v[190:193], v[228:231], v[0:3]
	s_barrier
	s_add_i32 s47, 0, 0x18000
	v_add_u32_e32 v145, s47, v165
	s_add_i32 s33, 0, 0x1c000
	ds_read_b128 v[128:131], v145
	ds_read_b128 v[132:135], v145 offset:1024
	ds_read_b128 v[160:163], v145 offset:2048
	ds_read_b128 v[168:171], v145 offset:3072
	v_add_u32_e32 v145, s33, v165
	ds_read_b128 v[176:179], v145
	ds_read_b128 v[182:185], v145 offset:1024
	ds_read_b128 v[186:189], v145 offset:2048
	ds_read_b128 v[190:193], v145 offset:3072
	s_add_u32 s18, s82, 0x80000
	s_addc_u32 s19, s83, 0
	s_mov_b32 m0, s65
	v_lshl_add_u64 v[236:237], s[18:19], 0, v[136:137]
	ds_read_b128 v[194:197], v181 offset:32768
	ds_read_b128 v[198:201], v181 offset:33792
	ds_read_b128 v[202:205], v181 offset:34816
	ds_read_b128 v[206:209], v181 offset:35840
	ds_read_b128 v[210:213], v181 offset:36864
	ds_read_b128 v[214:217], v181 offset:37888
	ds_read_b128 v[224:227], v181 offset:38912
	ds_read_b128 v[228:231], v181 offset:39936
	global_load_lds_dwordx4 v[236:237], off
	s_mov_b32 m0, s67
	v_lshl_add_u64 v[236:237], s[18:19], 0, v[140:141]
	global_load_lds_dwordx4 v[236:237], off
	s_waitcnt vmcnt(8) lgkmcnt(0)
	s_barrier
	v_mfma_f32_16x16x32_bf16 v[124:127], v[128:131], v[194:197], v[124:127]
	v_mfma_f32_16x16x32_bf16 v[116:119], v[160:163], v[194:197], v[116:119]
	v_mfma_f32_16x16x32_bf16 v[108:111], v[128:131], v[202:205], v[108:111]
	v_mfma_f32_16x16x32_bf16 v[100:103], v[160:163], v[202:205], v[100:103]
	v_mfma_f32_16x16x32_bf16 v[92:95], v[128:131], v[210:213], v[92:95]
	v_mfma_f32_16x16x32_bf16 v[84:87], v[160:163], v[210:213], v[84:87]
	v_mfma_f32_16x16x32_bf16 v[76:79], v[128:131], v[224:227], v[76:79]
	v_mfma_f32_16x16x32_bf16 v[68:71], v[160:163], v[224:227], v[68:71]
	v_mfma_f32_16x16x32_bf16 v[124:127], v[132:135], v[198:201], v[124:127]
	v_mfma_f32_16x16x32_bf16 v[116:119], v[168:171], v[198:201], v[116:119]
	v_mfma_f32_16x16x32_bf16 v[108:111], v[132:135], v[206:209], v[108:111]
	v_mfma_f32_16x16x32_bf16 v[100:103], v[168:171], v[206:209], v[100:103]
	v_mfma_f32_16x16x32_bf16 v[92:95], v[132:135], v[214:217], v[92:95]
	v_mfma_f32_16x16x32_bf16 v[84:87], v[168:171], v[214:217], v[84:87]
	v_mfma_f32_16x16x32_bf16 v[76:79], v[132:135], v[228:231], v[76:79]
	v_mfma_f32_16x16x32_bf16 v[68:71], v[168:171], v[228:231], v[68:71]
	v_mfma_f32_16x16x32_bf16 v[120:123], v[176:179], v[194:197], v[120:123]
	v_mfma_f32_16x16x32_bf16 v[112:115], v[186:189], v[194:197], v[112:115]
	v_mfma_f32_16x16x32_bf16 v[104:107], v[176:179], v[202:205], v[104:107]
	v_mfma_f32_16x16x32_bf16 v[96:99], v[186:189], v[202:205], v[96:99]
	v_mfma_f32_16x16x32_bf16 v[88:91], v[176:179], v[210:213], v[88:91]
	v_mfma_f32_16x16x32_bf16 v[80:83], v[186:189], v[210:213], v[80:83]
	v_mfma_f32_16x16x32_bf16 v[72:75], v[176:179], v[224:227], v[72:75]
	v_mfma_f32_16x16x32_bf16 v[64:67], v[186:189], v[224:227], v[64:67]
	v_mfma_f32_16x16x32_bf16 v[120:123], v[182:185], v[198:201], v[120:123]
	v_mfma_f32_16x16x32_bf16 v[112:115], v[190:193], v[198:201], v[112:115]
	v_mfma_f32_16x16x32_bf16 v[104:107], v[182:185], v[206:209], v[104:107]
	v_mfma_f32_16x16x32_bf16 v[96:99], v[190:193], v[206:209], v[96:99]
	v_mfma_f32_16x16x32_bf16 v[88:91], v[182:185], v[214:217], v[88:91]
	v_mfma_f32_16x16x32_bf16 v[80:83], v[190:193], v[214:217], v[80:83]
	v_mfma_f32_16x16x32_bf16 v[72:75], v[182:185], v[228:231], v[72:75]
	v_mfma_f32_16x16x32_bf16 v[64:67], v[190:193], v[228:231], v[64:67]
	s_barrier
; #define PG8_STAGE(bufoff, gbase, voff) do { _Pragma("unroll") for (int _i = 0; _i < 2; ++_i) \
;         __builtin_amdgcn_global_load_lds((const unsigned*)((const char*)(gbase) + (voff)[_i]), (LAS unsigned*)(lds + (bufoff) + ldsw + _i * 8192), 16, 0, 0); } while (0)
; #define PG8_LDA(dst, b, h) do { _Pragma("unroll") for (int m = 0; m < 4; ++m) _Pragma("unroll") for (int k = 0; k < 2; ++k) dst[m][k] = *(const LAS bf16x8*)(lds + PG8_SA(b, h) + aoff + m * 2048 + k * 1024); } while (0)
; #define PG8_MMA(ai, bj, At, Bt) do { __builtin_amdgcn_s_setprio(1); _Pragma("unroll") for (int m = 0; m < 4; ++m) _Pragma("unroll") for (int n = 0; n < 2; ++n) _Pragma("unroll") for (int k = 0; k < 2; ++k) \
;         acc[ai][bj][m][n] = __builtin_amdgcn_mfma_f32_16x16x32_bf16(Bt[n][k], At[m][k], acc[ai][bj][m][n], 0, 0, 0); __builtin_amdgcn_s_setprio(0); } while (0)
; #define PG8_WAIT_V(n) asm volatile("s_waitcnt vmcnt(" #n ")" ::: "memory")
; #define PG8_WAIT_L(n) asm volatile("s_waitcnt lgkmcnt(" #n ")" ::: "memory")
; #define PG8_BAR __builtin_amdgcn_s_barrier()
; #define PG8_SCHED __builtin_amdgcn_sched_barrier(0)
; template <class Epi, class Sched, bool ALIGN_EPI>
; __device__ __forceinline__ void gemm_phase(LAS unsigned char* lds, const Gemm g, const Sched& S, const Epi& E) {
;     ...
;             PG8_LDA(At, 1, 1); PG8_STAGE(PG8_SB(1, 0), b3, voffB); PG8_STAGE(PG8_SB(1, 1), b3 + hB, voffB); PG8_STAGE(PG8_SA(1, 0), a3, voffA);
;             PG8_WAIT_V(8); PG8_WAIT_L(0); PG8_BAR; PG8_MMA(1, 0, At, B0); PG8_MMA(1, 1, At, B1); PG8_BAR; PG8_SCHED;
;         }
;         if constexpr (ALIGN_EPI) { if (wr == 0) PG8_BAR; }
	s_add_i32 s18, s47, s59
	v_lshl_add_u64 v[156:157], v[156:157], 0, s[40:41]
	s_mov_b32 m0, s18
	ds_read_b128 v[194:197], v181 offset:49152
	ds_read_b128 v[198:201], v181 offset:50176
	ds_read_b128 v[202:205], v181 offset:51200
	ds_read_b128 v[206:209], v181 offset:52224
	ds_read_b128 v[210:213], v181 offset:53248
	ds_read_b128 v[214:217], v181 offset:54272
	ds_read_b128 v[224:227], v181 offset:55296
	ds_read_b128 v[228:231], v181 offset:56320
	global_load_lds_dwordx4 v[156:157], off
	s_add_i32 m0, s18, 0x2000
	s_add_u32 s18, s80, 0x80080
	v_lshl_add_u64 v[156:157], v[218:219], 0, s[40:41]
	s_addc_u32 s19, s81, 0
	s_add_i32 s33, s33, s59
	global_load_lds_dwordx4 v[156:157], off
	s_mov_b32 m0, s33
	v_lshl_add_u64 v[156:157], s[18:19], 0, v[138:139]
	global_load_lds_dwordx4 v[156:157], off
	s_add_i32 m0, s33, 0x2000
	v_lshl_add_u64 v[156:157], s[18:19], 0, v[142:143]
	global_load_lds_dwordx4 v[156:157], off
	s_mov_b32 m0, s69
	v_lshl_add_u64 v[156:157], v[232:233], 0, s[40:41]
	global_load_lds_dwordx4 v[156:157], off
	s_mov_b32 m0, s71
	v_lshl_add_u64 v[156:157], v[234:235], 0, s[40:41]
	global_load_lds_dwordx4 v[156:157], off
	s_waitcnt vmcnt(8) lgkmcnt(0)
	s_barrier
	v_mfma_f32_16x16x32_bf16 v[60:63], v[128:131], v[194:197], v[60:63]
	v_mfma_f32_16x16x32_bf16 v[52:55], v[160:163], v[194:197], v[52:55]
	v_mfma_f32_16x16x32_bf16 v[44:47], v[128:131], v[202:205], v[44:47]
	v_mfma_f32_16x16x32_bf16 v[36:39], v[160:163], v[202:205], v[36:39]
	v_mfma_f32_16x16x32_bf16 v[28:31], v[128:131], v[210:213], v[28:31]
	v_mfma_f32_16x16x32_bf16 v[20:23], v[160:163], v[210:213], v[20:23]
	v_mfma_f32_16x16x32_bf16 v[12:15], v[128:131], v[224:227], v[12:15]
	v_mfma_f32_16x16x32_bf16 v[4:7], v[160:163], v[224:227], v[4:7]
	v_mfma_f32_16x16x32_bf16 v[60:63], v[132:135], v[198:201], v[60:63]
	v_mfma_f32_16x16x32_bf16 v[52:55], v[168:171], v[198:201], v[52:55]
	v_mfma_f32_16x16x32_bf16 v[44:47], v[132:135], v[206:209], v[44:47]
	v_mfma_f32_16x16x32_bf16 v[36:39], v[168:171], v[206:209], v[36:39]
	v_mfma_f32_16x16x32_bf16 v[28:31], v[132:135], v[214:217], v[28:31]
	v_mfma_f32_16x16x32_bf16 v[20:23], v[168:171], v[214:217], v[20:23]
	v_mfma_f32_16x16x32_bf16 v[12:15], v[132:135], v[228:231], v[12:15]
	v_mfma_f32_16x16x32_bf16 v[4:7], v[168:171], v[228:231], v[4:7]
	v_mfma_f32_16x16x32_bf16 v[56:59], v[176:179], v[194:197], v[56:59]
	v_mfma_f32_16x16x32_bf16 v[48:51], v[186:189], v[194:197], v[48:51]
	v_mfma_f32_16x16x32_bf16 v[40:43], v[176:179], v[202:205], v[40:43]
	v_mfma_f32_16x16x32_bf16 v[32:35], v[186:189], v[202:205], v[32:35]
	v_mfma_f32_16x16x32_bf16 v[24:27], v[176:179], v[210:213], v[24:27]
	v_mfma_f32_16x16x32_bf16 v[16:19], v[186:189], v[210:213], v[16:19]
	v_mfma_f32_16x16x32_bf16 v[8:11], v[176:179], v[224:227], v[8:11]
	v_mfma_f32_16x16x32_bf16 v[0:3], v[186:189], v[224:227], v[0:3]
	v_mfma_f32_16x16x32_bf16 v[56:59], v[182:185], v[198:201], v[56:59]
	v_mfma_f32_16x16x32_bf16 v[48:51], v[190:193], v[198:201], v[48:51]
	v_mfma_f32_16x16x32_bf16 v[40:43], v[182:185], v[206:209], v[40:43]
	v_mfma_f32_16x16x32_bf16 v[32:35], v[190:193], v[206:209], v[32:35]
	v_mfma_f32_16x16x32_bf16 v[24:27], v[182:185], v[214:217], v[24:27]
	v_mfma_f32_16x16x32_bf16 v[16:19], v[190:193], v[214:217], v[16:19]
	v_mfma_f32_16x16x32_bf16 v[8:11], v[182:185], v[228:231], v[8:11]
	v_mfma_f32_16x16x32_bf16 v[0:3], v[190:193], v[228:231], v[0:3]
	s_barrier
	s_add_i32 s46, s46, 2
	s_add_u32 s6, s6, 0x100
	s_addc_u32 s7, s7, 0
	s_add_u32 s44, s44, 0x100
	s_addc_u32 s45, s45, 0
	s_cmp_gt_u32 s46, 29
	s_cbranch_scc0 .LBB0_466
	s_and_b64 vcc, exec, s[42:43]
	s_cbranch_vccz .LBB0_469
	s_barrier

; #define PG8_STAGE(bufoff, gbase, voff) do { _Pragma("unroll") for (int _i = 0; _i < 2; ++_i) \
;         __builtin_amdgcn_global_load_lds((const unsigned*)((const char*)(gbase) + (voff)[_i]), (LAS unsigned*)(lds + (bufoff) + ldsw + _i * 8192), 16, 0, 0); } while (0)
; #define PG8_LDA(dst, b, h) do { _Pragma("unroll") for (int m = 0; m < 4; ++m) _Pragma("unroll") for (int k = 0; k < 2; ++k) dst[m][k] = *(const LAS bf16x8*)(lds + PG8_SA(b, h) + aoff + m * 2048 + k * 1024); } while (0)
; #define PG8_LDB(dst, b, h) do { _Pragma("unroll") for (int n = 0; n < 2; ++n) _Pragma("unroll") for (int k = 0; k < 2; ++k) dst[n][k] = *(const LAS bf16x8*)(lds + PG8_SB(b, h) + boff + n * 2048 + k * 1024); } while (0)
; #define PG8_MMA(ai, bj, At, Bt) do { __builtin_amdgcn_s_setprio(1); _Pragma("unroll") for (int m = 0; m < 4; ++m) _Pragma("unroll") for (int n = 0; n < 2; ++n) _Pragma("unroll") for (int k = 0; k < 2; ++k) \
;         acc[ai][bj][m][n] = __builtin_amdgcn_mfma_f32_16x16x32_bf16(Bt[n][k], At[m][k], acc[ai][bj][m][n], 0, 0, 0); __builtin_amdgcn_s_setprio(0); } while (0)
; #define PG8_WAIT_V(n) asm volatile("s_waitcnt vmcnt(" #n ")" ::: "memory")
; #define PG8_WAIT_L(n) asm volatile("s_waitcnt lgkmcnt(" #n ")" ::: "memory")
; #define PG8_BAR __builtin_amdgcn_s_barrier()
; #define PG8_SCHED __builtin_amdgcn_sched_barrier(0)
; template <class Epi, class Sched, bool ALIGN_EPI>
; __device__ __forceinline__ void gemm_phase(LAS unsigned char* lds, const Gemm g, const Sched& S, const Epi& E) {
;     ...
;             const bool last = (t == nt - 2);
;             const char* a1 = cA + (size_t)(t + 1) * kstep;
;             const char* a2 = last ? nA : cA + (size_t)(t + 2) * kstep; const char* b2 = last ? nB : cB + (size_t)(t + 2) * kstep;
;             const char* a3 = a2 + kstep; const char* b3 = b2 + kstep;
;             PG8_LDB(B0, 0, 0); PG8_LDB(B1, 0, 1); PG8_SCHED; PG8_LDA(At, 0, 0); PG8_STAGE(PG8_SA(1, 1), a1 + hA, voffA);
;             PG8_WAIT_V(8); PG8_WAIT_L(0); PG8_BAR; PG8_MMA(0, 0, At, B0); PG8_MMA(0, 1, At, B1); PG8_BAR; PG8_SCHED;
;             PG8_LDA(At, 0, 1); PG8_STAGE(PG8_SB(0, 0), b2, voffB); PG8_STAGE(PG8_SB(0, 1), b2 + hB, voffB); PG8_STAGE(PG8_SA(0, 0), a2, voffA);
;             PG8_WAIT_V(8); PG8_WAIT_L(0); PG8_BAR; PG8_MMA(1, 0, At, B0); PG8_MMA(1, 1, At, B1); PG8_BAR; PG8_SCHED;
.LBB0_845:
	ds_read_b128 v[144:147], v151
	ds_read_b128 v[156:159], v151 offset:1024
	ds_read_b128 v[160:163], v151 offset:2048
	ds_read_b128 v[164:167], v151 offset:3072
	ds_read_b128 v[168:171], v152
	ds_read_b128 v[172:175], v152 offset:1024
	ds_read_b128 v[176:179], v152 offset:2048
	ds_read_b128 v[180:183], v152 offset:3072
	s_add_u32 s18, s58, 0xfff80080
	s_addc_u32 s19, s59, -1
	s_cmp_eq_u32 s46, 28
	s_cselect_b32 s63, s81, s19
	s_cselect_b32 s62, s82, s18
	s_cselect_b32 s61, s41, s45
	s_cselect_b32 s60, s83, s44
	v_lshl_add_u64 v[216:217], s[58:59], 0, v[136:137]
	s_add_i32 m0, s66, 0xc000
	ds_read_b128 v[184:187], v153
	ds_read_b128 v[188:191], v153 offset:1024
	ds_read_b128 v[192:195], v153 offset:2048
	ds_read_b128 v[196:199], v153 offset:3072
	ds_read_b128 v[200:203], v153 offset:4096
	ds_read_b128 v[204:207], v153 offset:5120
	ds_read_b128 v[208:211], v153 offset:6144
	ds_read_b128 v[212:215], v153 offset:7168
	global_load_lds_dwordx4 v[216:217], off
	s_add_i32 m0, s66, 0xe000
	v_lshl_add_u64 v[216:217], s[58:59], 0, v[138:139]
	global_load_lds_dwordx4 v[216:217], off
	s_waitcnt vmcnt(8) lgkmcnt(0)
	s_barrier
	v_mfma_f32_16x16x32_bf16 v[124:127], v[144:147], v[184:187], v[124:127]
	v_mfma_f32_16x16x32_bf16 v[120:123], v[160:163], v[184:187], v[120:123]
	v_mfma_f32_16x16x32_bf16 v[108:111], v[144:147], v[192:195], v[108:111]
	v_mfma_f32_16x16x32_bf16 v[104:107], v[160:163], v[192:195], v[104:107]
	v_mfma_f32_16x16x32_bf16 v[92:95], v[144:147], v[200:203], v[92:95]
	v_mfma_f32_16x16x32_bf16 v[88:91], v[160:163], v[200:203], v[88:91]
	v_mfma_f32_16x16x32_bf16 v[76:79], v[144:147], v[208:211], v[76:79]
	v_mfma_f32_16x16x32_bf16 v[72:75], v[160:163], v[208:211], v[72:75]
	v_mfma_f32_16x16x32_bf16 v[124:127], v[156:159], v[188:191], v[124:127]
	v_mfma_f32_16x16x32_bf16 v[120:123], v[164:167], v[188:191], v[120:123]
	v_mfma_f32_16x16x32_bf16 v[108:111], v[156:159], v[196:199], v[108:111]
	v_mfma_f32_16x16x32_bf16 v[104:107], v[164:167], v[196:199], v[104:107]
	v_mfma_f32_16x16x32_bf16 v[92:95], v[156:159], v[204:207], v[92:95]
	v_mfma_f32_16x16x32_bf16 v[88:91], v[164:167], v[204:207], v[88:91]
	v_mfma_f32_16x16x32_bf16 v[76:79], v[156:159], v[212:215], v[76:79]
	v_mfma_f32_16x16x32_bf16 v[72:75], v[164:167], v[212:215], v[72:75]
	v_mfma_f32_16x16x32_bf16 v[116:119], v[168:171], v[184:187], v[116:119]
	v_mfma_f32_16x16x32_bf16 v[112:115], v[176:179], v[184:187], v[112:115]
	v_mfma_f32_16x16x32_bf16 v[100:103], v[168:171], v[192:195], v[100:103]
	v_mfma_f32_16x16x32_bf16 v[96:99], v[176:179], v[192:195], v[96:99]
	v_mfma_f32_16x16x32_bf16 v[84:87], v[168:171], v[200:203], v[84:87]
	v_mfma_f32_16x16x32_bf16 v[80:83], v[176:179], v[200:203], v[80:83]
	v_mfma_f32_16x16x32_bf16 v[68:71], v[168:171], v[208:211], v[68:71]
	v_mfma_f32_16x16x32_bf16 v[64:67], v[176:179], v[208:211], v[64:67]
	v_mfma_f32_16x16x32_bf16 v[116:119], v[172:175], v[188:191], v[116:119]
	v_mfma_f32_16x16x32_bf16 v[112:115], v[180:183], v[188:191], v[112:115]
	v_mfma_f32_16x16x32_bf16 v[100:103], v[172:175], v[196:199], v[100:103]
	v_mfma_f32_16x16x32_bf16 v[96:99], v[180:183], v[196:199], v[96:99]
	v_mfma_f32_16x16x32_bf16 v[84:87], v[172:175], v[204:207], v[84:87]
	v_mfma_f32_16x16x32_bf16 v[80:83], v[180:183], v[204:207], v[80:83]
	v_mfma_f32_16x16x32_bf16 v[68:71], v[172:175], v[212:215], v[68:71]
	v_mfma_f32_16x16x32_bf16 v[64:67], v[180:183], v[212:215], v[64:67]
	s_barrier
	s_add_i32 s18, s76, s65
	v_lshl_add_u64 v[216:217], s[60:61], 0, v[130:131]
	s_mov_b32 m0, s18
	ds_read_b128 v[184:187], v153 offset:16384
	ds_read_b128 v[188:191], v153 offset:17408
	ds_read_b128 v[192:195], v153 offset:18432
	ds_read_b128 v[196:199], v153 offset:19456
	ds_read_b128 v[200:203], v153 offset:20480
	ds_read_b128 v[204:207], v153 offset:21504
	ds_read_b128 v[208:211], v153 offset:22528
	ds_read_b128 v[212:215], v153 offset:23552
	global_load_lds_dwordx4 v[216:217], off
	s_add_i32 m0, s18, 0x2000
	s_add_u32 s18, s60, 0x80000
	v_lshl_add_u64 v[218:219], s[60:61], 0, v[134:135]
	s_addc_u32 s19, s61, 0
	s_add_i32 s33, s77, s65
	global_load_lds_dwordx4 v[218:219], off
	v_lshl_add_u64 v[222:223], s[18:19], 0, v[130:131]
	s_mov_b32 m0, s33
	v_lshl_add_u64 v[224:225], s[62:63], 0, v[132:133]
	global_load_lds_dwordx4 v[222:223], off
	s_add_i32 m0, s33, 0x2000
	v_lshl_add_u64 v[222:223], s[18:19], 0, v[134:135]
	global_load_lds_dwordx4 v[222:223], off
	s_mov_b32 m0, s66
	v_lshl_add_u64 v[222:223], s[62:63], 0, v[128:129]
	global_load_lds_dwordx4 v[222:223], off
	s_mov_b32 m0, s67
	s_nop 0
	global_load_lds_dwordx4 v[224:225], off
	s_waitcnt vmcnt(8) lgkmcnt(0)
	s_barrier
; #define PG8_STAGE(bufoff, gbase, voff) do { _Pragma("unroll") for (int _i = 0; _i < 2; ++_i) \
;         __builtin_amdgcn_global_load_lds((const unsigned*)((const char*)(gbase) + (voff)[_i]), (LAS unsigned*)(lds + (bufoff) + ldsw + _i * 8192), 16, 0, 0); } while (0)
; #define PG8_LDA(dst, b, h) do { _Pragma("unroll") for (int m = 0; m < 4; ++m) _Pragma("unroll") for (int k = 0; k < 2; ++k) dst[m][k] = *(const LAS bf16x8*)(lds + PG8_SA(b, h) + aoff + m * 2048 + k * 1024); } while (0)
; #define PG8_LDB(dst, b, h) do { _Pragma("unroll") for (int n = 0; n < 2; ++n) _Pragma("unroll") for (int k = 0; k < 2; ++k) dst[n][k] = *(const LAS bf16x8*)(lds + PG8_SB(b, h) + boff + n * 2048 + k * 1024); } while (0)
; #define PG8_MMA(ai, bj, At, Bt) do { __builtin_amdgcn_s_setprio(1); _Pragma("unroll") for (int m = 0; m < 4; ++m) _Pragma("unroll") for (int n = 0; n < 2; ++n) _Pragma("unroll") for (int k = 0; k < 2; ++k) \
;         acc[ai][bj][m][n] = __builtin_amdgcn_mfma_f32_16x16x32_bf16(Bt[n][k], At[m][k], acc[ai][bj][m][n], 0, 0, 0); __builtin_amdgcn_s_setprio(0); } while (0)
; #define PG8_WAIT_V(n) asm volatile("s_waitcnt vmcnt(" #n ")" ::: "memory")
; #define PG8_WAIT_L(n) asm volatile("s_waitcnt lgkmcnt(" #n ")" ::: "memory")
; #define PG8_BAR __builtin_amdgcn_s_barrier()
; #define PG8_SCHED __builtin_amdgcn_sched_barrier(0)
; template <class Epi, class Sched, bool ALIGN_EPI>
; __device__ __forceinline__ void gemm_phase(LAS unsigned char* lds, const Gemm g, const Sched& S, const Epi& E) {
;     ...
;             PG8_WAIT_V(8); PG8_WAIT_L(0); PG8_BAR; PG8_MMA(1, 0, At, B0); PG8_MMA(1, 1, At, B1); PG8_BAR; PG8_SCHED;
;             PG8_LDB(B0, 1, 0); PG8_LDB(B1, 1, 1); PG8_SCHED; PG8_LDA(At, 1, 0); PG8_STAGE(PG8_SA(0, 1), a2 + hA, voffA);
;             PG8_WAIT_V(8); PG8_WAIT_L(0); PG8_BAR; PG8_MMA(0, 0, At, B0); PG8_MMA(0, 1, At, B1); PG8_BAR; PG8_SCHED;
	v_mfma_f32_16x16x32_bf16 v[60:63], v[144:147], v[184:187], v[60:63]
	v_mfma_f32_16x16x32_bf16 v[56:59], v[160:163], v[184:187], v[56:59]
	v_mfma_f32_16x16x32_bf16 v[44:47], v[144:147], v[192:195], v[44:47]
	v_mfma_f32_16x16x32_bf16 v[40:43], v[160:163], v[192:195], v[40:43]
	v_mfma_f32_16x16x32_bf16 v[28:31], v[144:147], v[200:203], v[28:31]
	v_mfma_f32_16x16x32_bf16 v[24:27], v[160:163], v[200:203], v[24:27]
	v_mfma_f32_16x16x32_bf16 v[12:15], v[144:147], v[208:211], v[12:15]
	v_mfma_f32_16x16x32_bf16 v[8:11], v[160:163], v[208:211], v[8:11]
	v_mfma_f32_16x16x32_bf16 v[60:63], v[156:159], v[188:191], v[60:63]
	v_mfma_f32_16x16x32_bf16 v[56:59], v[164:167], v[188:191], v[56:59]
	v_mfma_f32_16x16x32_bf16 v[44:47], v[156:159], v[196:199], v[44:47]
	v_mfma_f32_16x16x32_bf16 v[40:43], v[164:167], v[196:199], v[40:43]
	v_mfma_f32_16x16x32_bf16 v[28:31], v[156:159], v[204:207], v[28:31]
	v_mfma_f32_16x16x32_bf16 v[24:27], v[164:167], v[204:207], v[24:27]
	v_mfma_f32_16x16x32_bf16 v[12:15], v[156:159], v[212:215], v[12:15]
	v_mfma_f32_16x16x32_bf16 v[8:11], v[164:167], v[212:215], v[8:11]
	v_mfma_f32_16x16x32_bf16 v[52:55], v[168:171], v[184:187], v[52:55]
	v_mfma_f32_16x16x32_bf16 v[48:51], v[176:179], v[184:187], v[48:51]
	v_mfma_f32_16x16x32_bf16 v[36:39], v[168:171], v[192:195], v[36:39]
	v_mfma_f32_16x16x32_bf16 v[32:35], v[176:179], v[192:195], v[32:35]
	v_mfma_f32_16x16x32_bf16 v[20:23], v[168:171], v[200:203], v[20:23]
	v_mfma_f32_16x16x32_bf16 v[16:19], v[176:179], v[200:203], v[16:19]
	v_mfma_f32_16x16x32_bf16 v[4:7], v[168:171], v[208:211], v[4:7]
	v_mfma_f32_16x16x32_bf16 v[0:3], v[176:179], v[208:211], v[0:3]
	v_mfma_f32_16x16x32_bf16 v[52:55], v[172:175], v[188:191], v[52:55]
	v_mfma_f32_16x16x32_bf16 v[48:51], v[180:183], v[188:191], v[48:51]
	v_mfma_f32_16x16x32_bf16 v[36:39], v[172:175], v[196:199], v[36:39]
	v_mfma_f32_16x16x32_bf16 v[32:35], v[180:183], v[196:199], v[32:35]
	v_mfma_f32_16x16x32_bf16 v[20:23], v[172:175], v[204:207], v[20:23]
	v_mfma_f32_16x16x32_bf16 v[16:19], v[180:183], v[204:207], v[16:19]
	v_mfma_f32_16x16x32_bf16 v[4:7], v[172:175], v[212:215], v[4:7]
	v_mfma_f32_16x16x32_bf16 v[0:3], v[180:183], v[212:215], v[0:3]
	s_barrier
	s_add_i32 s33, 0, 0x18000
	v_add_u32_e32 v155, s33, v149
	s_add_i32 s47, 0, 0x1c000
	ds_read_b128 v[144:147], v155
	ds_read_b128 v[156:159], v155 offset:1024
	ds_read_b128 v[160:163], v155 offset:2048
	ds_read_b128 v[164:167], v155 offset:3072
	v_add_u32_e32 v155, s47, v149
	ds_read_b128 v[168:171], v155
	ds_read_b128 v[172:175], v155 offset:1024
	ds_read_b128 v[176:179], v155 offset:2048
	ds_read_b128 v[180:183], v155 offset:3072
	s_add_u32 s18, s62, 0x80000
	s_addc_u32 s19, s63, 0
	s_mov_b32 m0, s68
	v_lshl_add_u64 v[226:227], s[18:19], 0, v[128:129]
	ds_read_b128 v[184:187], v153 offset:32768
	ds_read_b128 v[188:191], v153 offset:33792
	ds_read_b128 v[192:195], v153 offset:34816
	ds_read_b128 v[196:199], v153 offset:35840
	ds_read_b128 v[200:203], v153 offset:36864
	ds_read_b128 v[204:207], v153 offset:37888
	ds_read_b128 v[208:211], v153 offset:38912
	ds_read_b128 v[212:215], v153 offset:39936
	global_load_lds_dwordx4 v[226:227], off
	s_mov_b32 m0, s69
	v_lshl_add_u64 v[226:227], s[18:19], 0, v[132:133]
	global_load_lds_dwordx4 v[226:227], off
	s_waitcnt vmcnt(8) lgkmcnt(0)
	s_barrier
	v_mfma_f32_16x16x32_bf16 v[124:127], v[144:147], v[184:187], v[124:127]
	v_mfma_f32_16x16x32_bf16 v[120:123], v[160:163], v[184:187], v[120:123]
	v_mfma_f32_16x16x32_bf16 v[108:111], v[144:147], v[192:195], v[108:111]
	v_mfma_f32_16x16x32_bf16 v[104:107], v[160:163], v[192:195], v[104:107]
	v_mfma_f32_16x16x32_bf16 v[92:95], v[144:147], v[200:203], v[92:95]
	v_mfma_f32_16x16x32_bf16 v[88:91], v[160:163], v[200:203], v[88:91]
	v_mfma_f32_16x16x32_bf16 v[76:79], v[144:147], v[208:211], v[76:79]
	v_mfma_f32_16x16x32_bf16 v[72:75], v[160:163], v[208:211], v[72:75]
	v_mfma_f32_16x16x32_bf16 v[124:127], v[156:159], v[188:191], v[124:127]
	v_mfma_f32_16x16x32_bf16 v[120:123], v[164:167], v[188:191], v[120:123]
	v_mfma_f32_16x16x32_bf16 v[108:111], v[156:159], v[196:199], v[108:111]
	v_mfma_f32_16x16x32_bf16 v[104:107], v[164:167], v[196:199], v[104:107]
	v_mfma_f32_16x16x32_bf16 v[92:95], v[156:159], v[204:207], v[92:95]
	v_mfma_f32_16x16x32_bf16 v[88:91], v[164:167], v[204:207], v[88:91]
	v_mfma_f32_16x16x32_bf16 v[76:79], v[156:159], v[212:215], v[76:79]
	v_mfma_f32_16x16x32_bf16 v[72:75], v[164:167], v[212:215], v[72:75]
	v_mfma_f32_16x16x32_bf16 v[116:119], v[168:171], v[184:187], v[116:119]
	v_mfma_f32_16x16x32_bf16 v[112:115], v[176:179], v[184:187], v[112:115]
	v_mfma_f32_16x16x32_bf16 v[100:103], v[168:171], v[192:195], v[100:103]
	v_mfma_f32_16x16x32_bf16 v[96:99], v[176:179], v[192:195], v[96:99]
	v_mfma_f32_16x16x32_bf16 v[84:87], v[168:171], v[200:203], v[84:87]
	v_mfma_f32_16x16x32_bf16 v[80:83], v[176:179], v[200:203], v[80:83]
	v_mfma_f32_16x16x32_bf16 v[68:71], v[168:171], v[208:211], v[68:71]
	v_mfma_f32_16x16x32_bf16 v[64:67], v[176:179], v[208:211], v[64:67]
	v_mfma_f32_16x16x32_bf16 v[116:119], v[172:175], v[188:191], v[116:119]
	v_mfma_f32_16x16x32_bf16 v[112:115], v[180:183], v[188:191], v[112:115]
	v_mfma_f32_16x16x32_bf16 v[100:103], v[172:175], v[196:199], v[100:103]
	v_mfma_f32_16x16x32_bf16 v[96:99], v[180:183], v[196:199], v[96:99]
	v_mfma_f32_16x16x32_bf16 v[84:87], v[172:175], v[204:207], v[84:87]
	v_mfma_f32_16x16x32_bf16 v[80:83], v[180:183], v[204:207], v[80:83]
	v_mfma_f32_16x16x32_bf16 v[68:71], v[172:175], v[212:215], v[68:71]
	v_mfma_f32_16x16x32_bf16 v[64:67], v[180:183], v[212:215], v[64:67]
	s_barrier
; #define PG8_STAGE(bufoff, gbase, voff) do { _Pragma("unroll") for (int _i = 0; _i < 2; ++_i) \
;         __builtin_amdgcn_global_load_lds((const unsigned*)((const char*)(gbase) + (voff)[_i]), (LAS unsigned*)(lds + (bufoff) + ldsw + _i * 8192), 16, 0, 0); } while (0)
; #define PG8_LDA(dst, b, h) do { _Pragma("unroll") for (int m = 0; m < 4; ++m) _Pragma("unroll") for (int k = 0; k < 2; ++k) dst[m][k] = *(const LAS bf16x8*)(lds + PG8_SA(b, h) + aoff + m * 2048 + k * 1024); } while (0)
; #define PG8_MMA(ai, bj, At, Bt) do { __builtin_amdgcn_s_setprio(1); _Pragma("unroll") for (int m = 0; m < 4; ++m) _Pragma("unroll") for (int n = 0; n < 2; ++n) _Pragma("unroll") for (int k = 0; k < 2; ++k) \
;         acc[ai][bj][m][n] = __builtin_amdgcn_mfma_f32_16x16x32_bf16(Bt[n][k], At[m][k], acc[ai][bj][m][n], 0, 0, 0); __builtin_amdgcn_s_setprio(0); } while (0)
; #define PG8_WAIT_V(n) asm volatile("s_waitcnt vmcnt(" #n ")" ::: "memory")
; #define PG8_WAIT_L(n) asm volatile("s_waitcnt lgkmcnt(" #n ")" ::: "memory")
; #define PG8_BAR __builtin_amdgcn_s_barrier()
; #define PG8_SCHED __builtin_amdgcn_sched_barrier(0)
; template <class Epi, class Sched, bool ALIGN_EPI>
; __device__ __forceinline__ void gemm_phase(LAS unsigned char* lds, const Gemm g, const Sched& S, const Epi& E) {
;     ...
;             PG8_LDA(At, 1, 1); PG8_STAGE(PG8_SB(1, 0), b3, voffB); PG8_STAGE(PG8_SB(1, 1), b3 + hB, voffB); PG8_STAGE(PG8_SA(1, 0), a3, voffA);
;             PG8_WAIT_V(8); PG8_WAIT_L(0); PG8_BAR; PG8_MMA(1, 0, At, B0); PG8_MMA(1, 1, At, B1); PG8_BAR; PG8_SCHED;
;         }
;         if constexpr (ALIGN_EPI) { if (wr == 0) PG8_BAR; }
	s_add_i32 s18, s33, s65
	v_lshl_add_u64 v[216:217], v[216:217], 0, s[26:27]
	s_mov_b32 m0, s18
	ds_read_b128 v[184:187], v153 offset:49152
	ds_read_b128 v[188:191], v153 offset:50176
	ds_read_b128 v[192:195], v153 offset:51200
	ds_read_b128 v[196:199], v153 offset:52224
	ds_read_b128 v[200:203], v153 offset:53248
	ds_read_b128 v[204:207], v153 offset:54272
	ds_read_b128 v[208:211], v153 offset:55296
	ds_read_b128 v[212:215], v153 offset:56320
	global_load_lds_dwordx4 v[216:217], off
	s_add_i32 m0, s18, 0x2000
	s_add_u32 s18, s60, 0x80080
	v_lshl_add_u64 v[216:217], v[218:219], 0, s[26:27]
	s_addc_u32 s19, s61, 0
	s_add_i32 s33, s47, s65
	global_load_lds_dwordx4 v[216:217], off
	s_mov_b32 m0, s33
	v_lshl_add_u64 v[216:217], s[18:19], 0, v[130:131]
	global_load_lds_dwordx4 v[216:217], off
	s_add_i32 m0, s33, 0x2000
	v_lshl_add_u64 v[216:217], s[18:19], 0, v[134:135]
	global_load_lds_dwordx4 v[216:217], off
	s_mov_b32 m0, s71
	v_lshl_add_u64 v[216:217], v[222:223], 0, s[26:27]
	global_load_lds_dwordx4 v[216:217], off
	s_mov_b32 m0, s72
	v_lshl_add_u64 v[216:217], v[224:225], 0, s[26:27]
	global_load_lds_dwordx4 v[216:217], off
	s_waitcnt vmcnt(8) lgkmcnt(0)
	s_barrier
	v_mfma_f32_16x16x32_bf16 v[60:63], v[144:147], v[184:187], v[60:63]
	v_mfma_f32_16x16x32_bf16 v[56:59], v[160:163], v[184:187], v[56:59]
	v_mfma_f32_16x16x32_bf16 v[44:47], v[144:147], v[192:195], v[44:47]
	v_mfma_f32_16x16x32_bf16 v[40:43], v[160:163], v[192:195], v[40:43]
	v_mfma_f32_16x16x32_bf16 v[28:31], v[144:147], v[200:203], v[28:31]
	v_mfma_f32_16x16x32_bf16 v[24:27], v[160:163], v[200:203], v[24:27]
	v_mfma_f32_16x16x32_bf16 v[12:15], v[144:147], v[208:211], v[12:15]
	v_mfma_f32_16x16x32_bf16 v[8:11], v[160:163], v[208:211], v[8:11]
	v_mfma_f32_16x16x32_bf16 v[60:63], v[156:159], v[188:191], v[60:63]
	v_mfma_f32_16x16x32_bf16 v[56:59], v[164:167], v[188:191], v[56:59]
	v_mfma_f32_16x16x32_bf16 v[44:47], v[156:159], v[196:199], v[44:47]
	v_mfma_f32_16x16x32_bf16 v[40:43], v[164:167], v[196:199], v[40:43]
	v_mfma_f32_16x16x32_bf16 v[28:31], v[156:159], v[204:207], v[28:31]
	v_mfma_f32_16x16x32_bf16 v[24:27], v[164:167], v[204:207], v[24:27]
	v_mfma_f32_16x16x32_bf16 v[12:15], v[156:159], v[212:215], v[12:15]
	v_mfma_f32_16x16x32_bf16 v[8:11], v[164:167], v[212:215], v[8:11]
	v_mfma_f32_16x16x32_bf16 v[52:55], v[168:171], v[184:187], v[52:55]
	v_mfma_f32_16x16x32_bf16 v[48:51], v[176:179], v[184:187], v[48:51]
	v_mfma_f32_16x16x32_bf16 v[36:39], v[168:171], v[192:195], v[36:39]
	v_mfma_f32_16x16x32_bf16 v[32:35], v[176:179], v[192:195], v[32:35]
	v_mfma_f32_16x16x32_bf16 v[20:23], v[168:171], v[200:203], v[20:23]
	v_mfma_f32_16x16x32_bf16 v[16:19], v[176:179], v[200:203], v[16:19]
	v_mfma_f32_16x16x32_bf16 v[4:7], v[168:171], v[208:211], v[4:7]
	v_mfma_f32_16x16x32_bf16 v[0:3], v[176:179], v[208:211], v[0:3]
	v_mfma_f32_16x16x32_bf16 v[52:55], v[172:175], v[188:191], v[52:55]
	v_mfma_f32_16x16x32_bf16 v[48:51], v[180:183], v[188:191], v[48:51]
	v_mfma_f32_16x16x32_bf16 v[36:39], v[172:175], v[196:199], v[36:39]
	v_mfma_f32_16x16x32_bf16 v[32:35], v[180:183], v[196:199], v[32:35]
	v_mfma_f32_16x16x32_bf16 v[20:23], v[172:175], v[204:207], v[20:23]
	v_mfma_f32_16x16x32_bf16 v[16:19], v[180:183], v[204:207], v[16:19]
	v_mfma_f32_16x16x32_bf16 v[4:7], v[172:175], v[212:215], v[4:7]
	v_mfma_f32_16x16x32_bf16 v[0:3], v[180:183], v[212:215], v[0:3]
	s_barrier
	s_add_i32 s46, s46, 2
	s_add_u32 s58, s58, 0x100
	s_addc_u32 s59, s59, 0
	s_add_u32 s44, s44, 0x100
	s_addc_u32 s45, s45, 0
	s_cmp_gt_u32 s46, 29
	s_cbranch_scc0 .LBB0_845
	s_and_b64 vcc, exec, s[38:39]
	s_cbranch_vccz .LBB0_848
	s_barrier

; #define PG8_STAGE(bufoff, gbase, voff) do { _Pragma("unroll") for (int _i = 0; _i < 2; ++_i) \
;         __builtin_amdgcn_global_load_lds((const unsigned*)((const char*)(gbase) + (voff)[_i]), (LAS unsigned*)(lds + (bufoff) + ldsw + _i * 8192), 16, 0, 0); } while (0)
; #define PG8_LDA(dst, b, h) do { _Pragma("unroll") for (int m = 0; m < 4; ++m) _Pragma("unroll") for (int k = 0; k < 2; ++k) dst[m][k] = *(const LAS bf16x8*)(lds + PG8_SA(b, h) + aoff + m * 2048 + k * 1024); } while (0)
; #define PG8_LDB(dst, b, h) do { _Pragma("unroll") for (int n = 0; n < 2; ++n) _Pragma("unroll") for (int k = 0; k < 2; ++k) dst[n][k] = *(const LAS bf16x8*)(lds + PG8_SB(b, h) + boff + n * 2048 + k * 1024); } while (0)
; #define PG8_MMA(ai, bj, At, Bt) do { __builtin_amdgcn_s_setprio(1); _Pragma("unroll") for (int m = 0; m < 4; ++m) _Pragma("unroll") for (int n = 0; n < 2; ++n) _Pragma("unroll") for (int k = 0; k < 2; ++k) \
;         acc[ai][bj][m][n] = __builtin_amdgcn_mfma_f32_16x16x32_bf16(Bt[n][k], At[m][k], acc[ai][bj][m][n], 0, 0, 0); __builtin_amdgcn_s_setprio(0); } while (0)
; #define PG8_WAIT_V(n) asm volatile("s_waitcnt vmcnt(" #n ")" ::: "memory")
; #define PG8_WAIT_L(n) asm volatile("s_waitcnt lgkmcnt(" #n ")" ::: "memory")
; #define PG8_BAR __builtin_amdgcn_s_barrier()
; #define PG8_SCHED __builtin_amdgcn_sched_barrier(0)
; template <class Epi, class Sched, bool ALIGN_EPI>
; __device__ __forceinline__ void gemm_phase(LAS unsigned char* lds, const Gemm g, const Sched& S, const Epi& E) {
;     ...
;             const bool last = (t == nt - 2);
;             const char* a1 = cA + (size_t)(t + 1) * kstep;
;             const char* a2 = last ? nA : cA + (size_t)(t + 2) * kstep; const char* b2 = last ? nB : cB + (size_t)(t + 2) * kstep;
;             const char* a3 = a2 + kstep; const char* b3 = b2 + kstep;
;             PG8_LDB(B0, 0, 0); PG8_LDB(B1, 0, 1); PG8_SCHED; PG8_LDA(At, 0, 0); PG8_STAGE(PG8_SA(1, 1), a1 + hA, voffA);
;             PG8_WAIT_V(8); PG8_WAIT_L(0); PG8_BAR; PG8_MMA(0, 0, At, B0); PG8_MMA(0, 1, At, B1); PG8_BAR; PG8_SCHED;
;             PG8_LDA(At, 0, 1); PG8_STAGE(PG8_SB(0, 0), b2, voffB); PG8_STAGE(PG8_SB(0, 1), b2 + hB, voffB); PG8_STAGE(PG8_SA(0, 0), a2, voffA);
;             PG8_WAIT_V(8); PG8_WAIT_L(0); PG8_BAR; PG8_MMA(1, 0, At, B0); PG8_MMA(1, 1, At, B1); PG8_BAR; PG8_SCHED;
.LBB0_926:
	ds_read_b128 v[156:159], v150
	ds_read_b128 v[166:169], v150 offset:1024
	ds_read_b128 v[170:173], v150 offset:2048
	ds_read_b128 v[174:177], v150 offset:3072
	ds_read_b128 v[178:181], v151
	ds_read_b128 v[182:185], v151 offset:1024
	ds_read_b128 v[186:189], v151 offset:2048
	ds_read_b128 v[190:193], v151 offset:3072
	s_add_i32 s94, s62, 2
	s_add_u32 s18, s60, 0xf3a80080
	s_addc_u32 s19, s61, -1
	s_cmp_lg_u32 s68, s62
	s_cselect_b32 s18, s18, 0
	s_cselect_b32 s19, s19, 0
	s_add_u32 s64, s58, s18
	s_addc_u32 s65, s59, s19
	s_add_u32 s62, s56, s18
	s_addc_u32 s63, s57, s19
	s_mov_b32 m0, s44
	v_lshl_add_u64 v[160:161], v[146:147], 0, s[60:61]
	ds_read_b128 v[194:197], v152
	ds_read_b128 v[198:201], v152 offset:1024
	ds_read_b128 v[202:205], v152 offset:2048
	ds_read_b128 v[206:209], v152 offset:3072
	ds_read_b128 v[210:213], v152 offset:4096
	ds_read_b128 v[214:217], v152 offset:5120
	ds_read_b128 v[222:225], v152 offset:6144
	ds_read_b128 v[226:229], v152 offset:7168
	global_load_lds_dwordx4 v[160:161], off
	s_mov_b32 m0, s45
	v_lshl_add_u64 v[160:161], v[148:149], 0, s[60:61]
	global_load_lds_dwordx4 v[160:161], off
	s_waitcnt vmcnt(8) lgkmcnt(0)
	s_barrier
	v_mfma_f32_16x16x32_bf16 v[124:127], v[156:159], v[194:197], v[124:127]
	v_mfma_f32_16x16x32_bf16 v[120:123], v[170:173], v[194:197], v[120:123]
	v_mfma_f32_16x16x32_bf16 v[108:111], v[156:159], v[202:205], v[108:111]
	v_mfma_f32_16x16x32_bf16 v[104:107], v[170:173], v[202:205], v[104:107]
	v_mfma_f32_16x16x32_bf16 v[92:95], v[156:159], v[210:213], v[92:95]
	v_mfma_f32_16x16x32_bf16 v[88:91], v[170:173], v[210:213], v[88:91]
	v_mfma_f32_16x16x32_bf16 v[76:79], v[156:159], v[222:225], v[76:79]
	v_mfma_f32_16x16x32_bf16 v[72:75], v[170:173], v[222:225], v[72:75]
	v_mfma_f32_16x16x32_bf16 v[124:127], v[166:169], v[198:201], v[124:127]
	v_mfma_f32_16x16x32_bf16 v[120:123], v[174:177], v[198:201], v[120:123]
	v_mfma_f32_16x16x32_bf16 v[108:111], v[166:169], v[206:209], v[108:111]
	v_mfma_f32_16x16x32_bf16 v[104:107], v[174:177], v[206:209], v[104:107]
	v_mfma_f32_16x16x32_bf16 v[92:95], v[166:169], v[214:217], v[92:95]
	v_mfma_f32_16x16x32_bf16 v[88:91], v[174:177], v[214:217], v[88:91]
	v_mfma_f32_16x16x32_bf16 v[76:79], v[166:169], v[226:229], v[76:79]
	v_mfma_f32_16x16x32_bf16 v[72:75], v[174:177], v[226:229], v[72:75]
	v_mfma_f32_16x16x32_bf16 v[116:119], v[178:181], v[194:197], v[116:119]
	v_mfma_f32_16x16x32_bf16 v[112:115], v[186:189], v[194:197], v[112:115]
	v_mfma_f32_16x16x32_bf16 v[100:103], v[178:181], v[202:205], v[100:103]
	v_mfma_f32_16x16x32_bf16 v[96:99], v[186:189], v[202:205], v[96:99]
	v_mfma_f32_16x16x32_bf16 v[84:87], v[178:181], v[210:213], v[84:87]
	v_mfma_f32_16x16x32_bf16 v[80:83], v[186:189], v[210:213], v[80:83]
	v_mfma_f32_16x16x32_bf16 v[68:71], v[178:181], v[222:225], v[68:71]
	v_mfma_f32_16x16x32_bf16 v[64:67], v[186:189], v[222:225], v[64:67]
	v_mfma_f32_16x16x32_bf16 v[116:119], v[182:185], v[198:201], v[116:119]
	v_mfma_f32_16x16x32_bf16 v[112:115], v[190:193], v[198:201], v[112:115]
	v_mfma_f32_16x16x32_bf16 v[100:103], v[182:185], v[206:209], v[100:103]
	v_mfma_f32_16x16x32_bf16 v[96:99], v[190:193], v[206:209], v[96:99]
	v_mfma_f32_16x16x32_bf16 v[84:87], v[182:185], v[214:217], v[84:87]
	v_mfma_f32_16x16x32_bf16 v[80:83], v[190:193], v[214:217], v[80:83]
	v_mfma_f32_16x16x32_bf16 v[68:71], v[182:185], v[226:229], v[68:71]
	v_mfma_f32_16x16x32_bf16 v[64:67], v[190:193], v[226:229], v[64:67]
	s_barrier
	s_mov_b32 m0, s46
	v_lshl_add_u64 v[160:161], s[62:63], 0, v[130:131]
	s_add_u32 s18, s62, 0x80000
	ds_read_b128 v[194:197], v152 offset:16384
	ds_read_b128 v[198:201], v152 offset:17408
	ds_read_b128 v[202:205], v152 offset:18432
	ds_read_b128 v[206:209], v152 offset:19456
	ds_read_b128 v[210:213], v152 offset:20480
	ds_read_b128 v[214:217], v152 offset:21504
	ds_read_b128 v[222:225], v152 offset:22528
	ds_read_b128 v[226:229], v152 offset:23552
	global_load_lds_dwordx4 v[160:161], off
	v_lshl_add_u64 v[218:219], s[62:63], 0, v[134:135]
	s_mov_b32 m0, s47
	s_addc_u32 s19, s63, 0
	global_load_lds_dwordx4 v[218:219], off
	v_lshl_add_u64 v[230:231], s[18:19], 0, v[130:131]
	s_mov_b32 m0, s92
	v_lshl_add_u64 v[232:233], s[64:65], 0, v[132:133]
	global_load_lds_dwordx4 v[230:231], off
	s_mov_b32 m0, s93
	v_lshl_add_u64 v[230:231], s[18:19], 0, v[134:135]
	global_load_lds_dwordx4 v[230:231], off
	s_mov_b32 m0, s22
	v_lshl_add_u64 v[230:231], s[64:65], 0, v[128:129]
	global_load_lds_dwordx4 v[230:231], off
	s_mov_b32 m0, s87
	s_nop 0
	global_load_lds_dwordx4 v[232:233], off
	s_waitcnt vmcnt(8) lgkmcnt(0)
	s_barrier
; #define PG8_STAGE(bufoff, gbase, voff) do { _Pragma("unroll") for (int _i = 0; _i < 2; ++_i) \
;         __builtin_amdgcn_global_load_lds((const unsigned*)((const char*)(gbase) + (voff)[_i]), (LAS unsigned*)(lds + (bufoff) + ldsw + _i * 8192), 16, 0, 0); } while (0)
; #define PG8_LDA(dst, b, h) do { _Pragma("unroll") for (int m = 0; m < 4; ++m) _Pragma("unroll") for (int k = 0; k < 2; ++k) dst[m][k] = *(const LAS bf16x8*)(lds + PG8_SA(b, h) + aoff + m * 2048 + k * 1024); } while (0)
; #define PG8_LDB(dst, b, h) do { _Pragma("unroll") for (int n = 0; n < 2; ++n) _Pragma("unroll") for (int k = 0; k < 2; ++k) dst[n][k] = *(const LAS bf16x8*)(lds + PG8_SB(b, h) + boff + n * 2048 + k * 1024); } while (0)
; #define PG8_MMA(ai, bj, At, Bt) do { __builtin_amdgcn_s_setprio(1); _Pragma("unroll") for (int m = 0; m < 4; ++m) _Pragma("unroll") for (int n = 0; n < 2; ++n) _Pragma("unroll") for (int k = 0; k < 2; ++k) \
;         acc[ai][bj][m][n] = __builtin_amdgcn_mfma_f32_16x16x32_bf16(Bt[n][k], At[m][k], acc[ai][bj][m][n], 0, 0, 0); __builtin_amdgcn_s_setprio(0); } while (0)
; #define PG8_WAIT_V(n) asm volatile("s_waitcnt vmcnt(" #n ")" ::: "memory")
; #define PG8_WAIT_L(n) asm volatile("s_waitcnt lgkmcnt(" #n ")" ::: "memory")
; #define PG8_BAR __builtin_amdgcn_s_barrier()
; #define PG8_SCHED __builtin_amdgcn_sched_barrier(0)
; template <class Epi, class Sched, bool ALIGN_EPI>
; __device__ __forceinline__ void gemm_phase(LAS unsigned char* lds, const Gemm g, const Sched& S, const Epi& E) {
;     ...
;             PG8_WAIT_V(8); PG8_WAIT_L(0); PG8_BAR; PG8_MMA(1, 0, At, B0); PG8_MMA(1, 1, At, B1); PG8_BAR; PG8_SCHED;
;             PG8_LDB(B0, 1, 0); PG8_LDB(B1, 1, 1); PG8_SCHED; PG8_LDA(At, 1, 0); PG8_STAGE(PG8_SA(0, 1), a2 + hA, voffA);
;             PG8_WAIT_V(8); PG8_WAIT_L(0); PG8_BAR; PG8_MMA(0, 0, At, B0); PG8_MMA(0, 1, At, B1); PG8_BAR; PG8_SCHED;
	v_mfma_f32_16x16x32_bf16 v[60:63], v[156:159], v[194:197], v[60:63]
	v_mfma_f32_16x16x32_bf16 v[56:59], v[170:173], v[194:197], v[56:59]
	v_mfma_f32_16x16x32_bf16 v[44:47], v[156:159], v[202:205], v[44:47]
	v_mfma_f32_16x16x32_bf16 v[40:43], v[170:173], v[202:205], v[40:43]
	v_mfma_f32_16x16x32_bf16 v[28:31], v[156:159], v[210:213], v[28:31]
	v_mfma_f32_16x16x32_bf16 v[24:27], v[170:173], v[210:213], v[24:27]
	v_mfma_f32_16x16x32_bf16 v[12:15], v[156:159], v[222:225], v[12:15]
	v_mfma_f32_16x16x32_bf16 v[8:11], v[170:173], v[222:225], v[8:11]
	v_mfma_f32_16x16x32_bf16 v[60:63], v[166:169], v[198:201], v[60:63]
	v_mfma_f32_16x16x32_bf16 v[56:59], v[174:177], v[198:201], v[56:59]
	v_mfma_f32_16x16x32_bf16 v[44:47], v[166:169], v[206:209], v[44:47]
	v_mfma_f32_16x16x32_bf16 v[40:43], v[174:177], v[206:209], v[40:43]
	v_mfma_f32_16x16x32_bf16 v[28:31], v[166:169], v[214:217], v[28:31]
	v_mfma_f32_16x16x32_bf16 v[24:27], v[174:177], v[214:217], v[24:27]
	v_mfma_f32_16x16x32_bf16 v[12:15], v[166:169], v[226:229], v[12:15]
	v_mfma_f32_16x16x32_bf16 v[8:11], v[174:177], v[226:229], v[8:11]
	v_mfma_f32_16x16x32_bf16 v[52:55], v[178:181], v[194:197], v[52:55]
	v_mfma_f32_16x16x32_bf16 v[48:51], v[186:189], v[194:197], v[48:51]
	v_mfma_f32_16x16x32_bf16 v[36:39], v[178:181], v[202:205], v[36:39]
	v_mfma_f32_16x16x32_bf16 v[32:35], v[186:189], v[202:205], v[32:35]
	v_mfma_f32_16x16x32_bf16 v[20:23], v[178:181], v[210:213], v[20:23]
	v_mfma_f32_16x16x32_bf16 v[16:19], v[186:189], v[210:213], v[16:19]
	v_mfma_f32_16x16x32_bf16 v[4:7], v[178:181], v[222:225], v[4:7]
	v_mfma_f32_16x16x32_bf16 v[0:3], v[186:189], v[222:225], v[0:3]
	v_mfma_f32_16x16x32_bf16 v[52:55], v[182:185], v[198:201], v[52:55]
	v_mfma_f32_16x16x32_bf16 v[48:51], v[190:193], v[198:201], v[48:51]
	v_mfma_f32_16x16x32_bf16 v[36:39], v[182:185], v[206:209], v[36:39]
	v_mfma_f32_16x16x32_bf16 v[32:35], v[190:193], v[206:209], v[32:35]
	v_mfma_f32_16x16x32_bf16 v[20:23], v[182:185], v[214:217], v[20:23]
	v_mfma_f32_16x16x32_bf16 v[16:19], v[190:193], v[214:217], v[16:19]
	v_mfma_f32_16x16x32_bf16 v[4:7], v[182:185], v[226:229], v[4:7]
	v_mfma_f32_16x16x32_bf16 v[0:3], v[190:193], v[226:229], v[0:3]
	s_barrier
	ds_read_b128 v[156:159], v153
	ds_read_b128 v[166:169], v153 offset:1024
	ds_read_b128 v[170:173], v153 offset:2048
	ds_read_b128 v[174:177], v153 offset:3072
	ds_read_b128 v[178:181], v154
	ds_read_b128 v[182:185], v154 offset:1024
	ds_read_b128 v[186:189], v154 offset:2048
	ds_read_b128 v[190:193], v154 offset:3072
	s_add_u32 s18, s64, 0x80000
	s_addc_u32 s19, s65, 0
	s_mov_b32 m0, s88
	v_lshl_add_u64 v[234:235], s[18:19], 0, v[128:129]
	ds_read_b128 v[194:197], v152 offset:32768
	ds_read_b128 v[198:201], v152 offset:33792
	ds_read_b128 v[202:205], v152 offset:34816
	ds_read_b128 v[206:209], v152 offset:35840
	ds_read_b128 v[210:213], v152 offset:36864
	ds_read_b128 v[214:217], v152 offset:37888
	ds_read_b128 v[222:225], v152 offset:38912
	ds_read_b128 v[226:229], v152 offset:39936
	global_load_lds_dwordx4 v[234:235], off
	s_mov_b32 m0, s89
	v_lshl_add_u64 v[234:235], s[18:19], 0, v[132:133]
	global_load_lds_dwordx4 v[234:235], off
	s_waitcnt vmcnt(8) lgkmcnt(0)
	s_barrier
	v_mfma_f32_16x16x32_bf16 v[124:127], v[156:159], v[194:197], v[124:127]
	v_mfma_f32_16x16x32_bf16 v[120:123], v[170:173], v[194:197], v[120:123]
	v_mfma_f32_16x16x32_bf16 v[108:111], v[156:159], v[202:205], v[108:111]
	v_mfma_f32_16x16x32_bf16 v[104:107], v[170:173], v[202:205], v[104:107]
	v_mfma_f32_16x16x32_bf16 v[92:95], v[156:159], v[210:213], v[92:95]
	v_mfma_f32_16x16x32_bf16 v[88:91], v[170:173], v[210:213], v[88:91]
	v_mfma_f32_16x16x32_bf16 v[76:79], v[156:159], v[222:225], v[76:79]
	v_mfma_f32_16x16x32_bf16 v[72:75], v[170:173], v[222:225], v[72:75]
	v_mfma_f32_16x16x32_bf16 v[124:127], v[166:169], v[198:201], v[124:127]
	v_mfma_f32_16x16x32_bf16 v[120:123], v[174:177], v[198:201], v[120:123]
	v_mfma_f32_16x16x32_bf16 v[108:111], v[166:169], v[206:209], v[108:111]
	v_mfma_f32_16x16x32_bf16 v[104:107], v[174:177], v[206:209], v[104:107]
	v_mfma_f32_16x16x32_bf16 v[92:95], v[166:169], v[214:217], v[92:95]
	v_mfma_f32_16x16x32_bf16 v[88:91], v[174:177], v[214:217], v[88:91]
	v_mfma_f32_16x16x32_bf16 v[76:79], v[166:169], v[226:229], v[76:79]
	v_mfma_f32_16x16x32_bf16 v[72:75], v[174:177], v[226:229], v[72:75]
	v_mfma_f32_16x16x32_bf16 v[116:119], v[178:181], v[194:197], v[116:119]
	v_mfma_f32_16x16x32_bf16 v[112:115], v[186:189], v[194:197], v[112:115]
	v_mfma_f32_16x16x32_bf16 v[100:103], v[178:181], v[202:205], v[100:103]
	v_mfma_f32_16x16x32_bf16 v[96:99], v[186:189], v[202:205], v[96:99]
	v_mfma_f32_16x16x32_bf16 v[84:87], v[178:181], v[210:213], v[84:87]
	v_mfma_f32_16x16x32_bf16 v[80:83], v[186:189], v[210:213], v[80:83]
	v_mfma_f32_16x16x32_bf16 v[68:71], v[178:181], v[222:225], v[68:71]
	v_mfma_f32_16x16x32_bf16 v[64:67], v[186:189], v[222:225], v[64:67]
	v_mfma_f32_16x16x32_bf16 v[116:119], v[182:185], v[198:201], v[116:119]
	v_mfma_f32_16x16x32_bf16 v[112:115], v[190:193], v[198:201], v[112:115]
	v_mfma_f32_16x16x32_bf16 v[100:103], v[182:185], v[206:209], v[100:103]
	v_mfma_f32_16x16x32_bf16 v[96:99], v[190:193], v[206:209], v[96:99]
	v_mfma_f32_16x16x32_bf16 v[84:87], v[182:185], v[214:217], v[84:87]
	v_mfma_f32_16x16x32_bf16 v[80:83], v[190:193], v[214:217], v[80:83]
	v_mfma_f32_16x16x32_bf16 v[68:71], v[182:185], v[226:229], v[68:71]
	v_mfma_f32_16x16x32_bf16 v[64:67], v[190:193], v[226:229], v[64:67]
	s_barrier
; #define PG8_STAGE(bufoff, gbase, voff) do { _Pragma("unroll") for (int _i = 0; _i < 2; ++_i) \
;         __builtin_amdgcn_global_load_lds((const unsigned*)((const char*)(gbase) + (voff)[_i]), (LAS unsigned*)(lds + (bufoff) + ldsw + _i * 8192), 16, 0, 0); } while (0)
; #define PG8_LDA(dst, b, h) do { _Pragma("unroll") for (int m = 0; m < 4; ++m) _Pragma("unroll") for (int k = 0; k < 2; ++k) dst[m][k] = *(const LAS bf16x8*)(lds + PG8_SA(b, h) + aoff + m * 2048 + k * 1024); } while (0)
; #define PG8_MMA(ai, bj, At, Bt) do { __builtin_amdgcn_s_setprio(1); _Pragma("unroll") for (int m = 0; m < 4; ++m) _Pragma("unroll") for (int n = 0; n < 2; ++n) _Pragma("unroll") for (int k = 0; k < 2; ++k) \
;         acc[ai][bj][m][n] = __builtin_amdgcn_mfma_f32_16x16x32_bf16(Bt[n][k], At[m][k], acc[ai][bj][m][n], 0, 0, 0); __builtin_amdgcn_s_setprio(0); } while (0)
; #define PG8_WAIT_V(n) asm volatile("s_waitcnt vmcnt(" #n ")" ::: "memory")
; #define PG8_WAIT_L(n) asm volatile("s_waitcnt lgkmcnt(" #n ")" ::: "memory")
; #define PG8_BAR __builtin_amdgcn_s_barrier()
; #define PG8_SCHED __builtin_amdgcn_sched_barrier(0)
; template <class Epi, class Sched, bool ALIGN_EPI>
; __device__ __forceinline__ void gemm_phase(LAS unsigned char* lds, const Gemm g, const Sched& S, const Epi& E) {
;     ...
;             PG8_LDA(At, 1, 1); PG8_STAGE(PG8_SB(1, 0), b3, voffB); PG8_STAGE(PG8_SB(1, 1), b3 + hB, voffB); PG8_STAGE(PG8_SA(1, 0), a3, voffA);
;             PG8_WAIT_V(8); PG8_WAIT_L(0); PG8_BAR; PG8_MMA(1, 0, At, B0); PG8_MMA(1, 1, At, B1); PG8_BAR; PG8_SCHED;
;         }
	s_add_i32 s18, s74, s84
	v_lshl_add_u64 v[160:161], v[160:161], 0, s[24:25]
	s_mov_b32 m0, s18
	ds_read_b128 v[194:197], v152 offset:49152
	ds_read_b128 v[198:201], v152 offset:50176
	ds_read_b128 v[202:205], v152 offset:51200
	ds_read_b128 v[206:209], v152 offset:52224
	ds_read_b128 v[210:213], v152 offset:53248
	ds_read_b128 v[214:217], v152 offset:54272
	ds_read_b128 v[222:225], v152 offset:55296
	ds_read_b128 v[226:229], v152 offset:56320
	global_load_lds_dwordx4 v[160:161], off
	s_add_i32 m0, s18, 0x2000
	s_add_u32 s18, s62, 0x80080
	v_lshl_add_u64 v[160:161], v[218:219], 0, s[24:25]
	s_addc_u32 s19, s63, 0
	s_add_i32 s33, s75, s84
	global_load_lds_dwordx4 v[160:161], off
	s_mov_b32 m0, s33
	v_lshl_add_u64 v[160:161], s[18:19], 0, v[130:131]
	global_load_lds_dwordx4 v[160:161], off
	s_add_i32 m0, s33, 0x2000
	v_lshl_add_u64 v[160:161], s[18:19], 0, v[134:135]
	global_load_lds_dwordx4 v[160:161], off
	s_mov_b32 m0, s90
	v_lshl_add_u64 v[160:161], v[230:231], 0, s[24:25]
	global_load_lds_dwordx4 v[160:161], off
	s_mov_b32 m0, s91
	v_lshl_add_u64 v[160:161], v[232:233], 0, s[24:25]
	global_load_lds_dwordx4 v[160:161], off
	s_waitcnt vmcnt(8) lgkmcnt(0)
	s_barrier
	v_mfma_f32_16x16x32_bf16 v[60:63], v[156:159], v[194:197], v[60:63]
	v_mfma_f32_16x16x32_bf16 v[56:59], v[170:173], v[194:197], v[56:59]
	v_mfma_f32_16x16x32_bf16 v[44:47], v[156:159], v[202:205], v[44:47]
	v_mfma_f32_16x16x32_bf16 v[40:43], v[170:173], v[202:205], v[40:43]
	v_mfma_f32_16x16x32_bf16 v[28:31], v[156:159], v[210:213], v[28:31]
	v_mfma_f32_16x16x32_bf16 v[24:27], v[170:173], v[210:213], v[24:27]
	v_mfma_f32_16x16x32_bf16 v[12:15], v[156:159], v[222:225], v[12:15]
	v_mfma_f32_16x16x32_bf16 v[8:11], v[170:173], v[222:225], v[8:11]
	v_mfma_f32_16x16x32_bf16 v[60:63], v[166:169], v[198:201], v[60:63]
	v_mfma_f32_16x16x32_bf16 v[56:59], v[174:177], v[198:201], v[56:59]
	v_mfma_f32_16x16x32_bf16 v[44:47], v[166:169], v[206:209], v[44:47]
	v_mfma_f32_16x16x32_bf16 v[40:43], v[174:177], v[206:209], v[40:43]
	v_mfma_f32_16x16x32_bf16 v[28:31], v[166:169], v[214:217], v[28:31]
	v_mfma_f32_16x16x32_bf16 v[24:27], v[174:177], v[214:217], v[24:27]
	v_mfma_f32_16x16x32_bf16 v[12:15], v[166:169], v[226:229], v[12:15]
	v_mfma_f32_16x16x32_bf16 v[8:11], v[174:177], v[226:229], v[8:11]
	v_mfma_f32_16x16x32_bf16 v[52:55], v[178:181], v[194:197], v[52:55]
	v_mfma_f32_16x16x32_bf16 v[48:51], v[186:189], v[194:197], v[48:51]
	v_mfma_f32_16x16x32_bf16 v[36:39], v[178:181], v[202:205], v[36:39]
	v_mfma_f32_16x16x32_bf16 v[32:35], v[186:189], v[202:205], v[32:35]
	v_mfma_f32_16x16x32_bf16 v[20:23], v[178:181], v[210:213], v[20:23]
	v_mfma_f32_16x16x32_bf16 v[16:19], v[186:189], v[210:213], v[16:19]
	v_mfma_f32_16x16x32_bf16 v[4:7], v[178:181], v[222:225], v[4:7]
	v_mfma_f32_16x16x32_bf16 v[0:3], v[186:189], v[222:225], v[0:3]
	v_mfma_f32_16x16x32_bf16 v[52:55], v[182:185], v[198:201], v[52:55]
	v_mfma_f32_16x16x32_bf16 v[48:51], v[190:193], v[198:201], v[48:51]
	v_mfma_f32_16x16x32_bf16 v[36:39], v[182:185], v[206:209], v[36:39]
	v_mfma_f32_16x16x32_bf16 v[32:35], v[190:193], v[206:209], v[32:35]
	v_mfma_f32_16x16x32_bf16 v[20:23], v[182:185], v[214:217], v[20:23]
	v_mfma_f32_16x16x32_bf16 v[16:19], v[190:193], v[214:217], v[16:19]
	v_mfma_f32_16x16x32_bf16 v[4:7], v[182:185], v[226:229], v[4:7]
	v_mfma_f32_16x16x32_bf16 v[0:3], v[190:193], v[226:229], v[0:3]
	s_barrier
	s_add_u32 s60, s60, 0x100
	s_addc_u32 s61, s61, 0
	s_cmp_lt_i32 s94, s27
	s_mov_b32 s62, s94
	s_cbranch_scc1 .LBB0_926
	v_readlane_b32 s92, v254, 6
	v_readlane_b32 s93, v254, 7

; #define PG8_STAGE(bufoff, gbase, voff) do { _Pragma("unroll") for (int _i = 0; _i < 2; ++_i) \
;         __builtin_amdgcn_global_load_lds((const unsigned*)((const char*)(gbase) + (voff)[_i]), (LAS unsigned*)(lds + (bufoff) + ldsw + _i * 8192), 16, 0, 0); } while (0)
; #define PG8_LDA(dst, b, h) do { _Pragma("unroll") for (int m = 0; m < 4; ++m) _Pragma("unroll") for (int k = 0; k < 2; ++k) dst[m][k] = *(const LAS bf16x8*)(lds + PG8_SA(b, h) + aoff + m * 2048 + k * 1024); } while (0)
; #define PG8_LDB(dst, b, h) do { _Pragma("unroll") for (int n = 0; n < 2; ++n) _Pragma("unroll") for (int k = 0; k < 2; ++k) dst[n][k] = *(const LAS bf16x8*)(lds + PG8_SB(b, h) + boff + n * 2048 + k * 1024); } while (0)
; #define PG8_MMA(ai, bj, At, Bt) do { __builtin_amdgcn_s_setprio(1); _Pragma("unroll") for (int m = 0; m < 4; ++m) _Pragma("unroll") for (int n = 0; n < 2; ++n) _Pragma("unroll") for (int k = 0; k < 2; ++k) \
;         acc[ai][bj][m][n] = __builtin_amdgcn_mfma_f32_16x16x32_bf16(Bt[n][k], At[m][k], acc[ai][bj][m][n], 0, 0, 0); __builtin_amdgcn_s_setprio(0); } while (0)
; #define PG8_WAIT_V(n) asm volatile("s_waitcnt vmcnt(" #n ")" ::: "memory")
; #define PG8_WAIT_L(n) asm volatile("s_waitcnt lgkmcnt(" #n ")" ::: "memory")
; #define PG8_BAR __builtin_amdgcn_s_barrier()
; #define PG8_SCHED __builtin_amdgcn_sched_barrier(0)
; template <class Epi, class Sched, bool ALIGN_EPI>
; __device__ __forceinline__ void gemm_phase(LAS unsigned char* lds, const Gemm g, const Sched& S, const Epi& E) {
;     ...
;             const bool last = (t == nt - 2);
;             const char* a1 = cA + (size_t)(t + 1) * kstep;
;             const char* a2 = last ? nA : cA + (size_t)(t + 2) * kstep; const char* b2 = last ? nB : cB + (size_t)(t + 2) * kstep;
;             const char* a3 = a2 + kstep; const char* b3 = b2 + kstep;
;             PG8_LDB(B0, 0, 0); PG8_LDB(B1, 0, 1); PG8_SCHED; PG8_LDA(At, 0, 0); PG8_STAGE(PG8_SA(1, 1), a1 + hA, voffA);
;             PG8_WAIT_V(8); PG8_WAIT_L(0); PG8_BAR; PG8_MMA(0, 0, At, B0); PG8_MMA(0, 1, At, B1); PG8_BAR; PG8_SCHED;
;             PG8_LDA(At, 0, 1); PG8_STAGE(PG8_SB(0, 0), b2, voffB); PG8_STAGE(PG8_SB(0, 1), b2 + hB, voffB); PG8_STAGE(PG8_SA(0, 0), a2, voffA);
;             PG8_WAIT_V(8); PG8_WAIT_L(0); PG8_BAR; PG8_MMA(1, 0, At, B0); PG8_MMA(1, 1, At, B1); PG8_BAR; PG8_SCHED;
.LBB0_955:
	ds_read_b128 v[156:159], v152
	ds_read_b128 v[160:163], v152 offset:1024
	ds_read_b128 v[164:167], v152 offset:2048
	ds_read_b128 v[168:171], v152 offset:3072
	ds_read_b128 v[172:175], v153
	ds_read_b128 v[176:179], v153 offset:1024
	ds_read_b128 v[180:183], v153 offset:2048
	ds_read_b128 v[184:187], v153 offset:3072
	s_add_i32 s75, s40, 2
	s_add_u32 s18, s38, 0xf4b80080
	s_addc_u32 s19, s39, -1
	s_cmp_lg_u32 s57, s40
	s_cselect_b32 s18, s18, 0
	s_cselect_b32 s19, s19, 0
	s_add_u32 s42, s26, s18
	s_addc_u32 s43, s27, s19
	s_add_u32 s40, s24, s18
	s_addc_u32 s41, s25, s19
	s_mov_b32 m0, s4
	v_lshl_add_u64 v[222:223], v[142:143], 0, s[38:39]
	ds_read_b128 v[188:191], v151
	ds_read_b128 v[192:195], v151 offset:1024
	ds_read_b128 v[196:199], v151 offset:2048
	ds_read_b128 v[200:203], v151 offset:3072
	ds_read_b128 v[204:207], v151 offset:4096
	ds_read_b128 v[208:211], v151 offset:5120
	ds_read_b128 v[212:215], v151 offset:6144
	ds_read_b128 v[216:219], v151 offset:7168
	global_load_lds_dwordx4 v[222:223], off
	s_mov_b32 m0, s44
	v_lshl_add_u64 v[222:223], v[144:145], 0, s[38:39]
	global_load_lds_dwordx4 v[222:223], off
	s_waitcnt vmcnt(8) lgkmcnt(0)
	s_barrier
	v_mfma_f32_16x16x32_bf16 v[124:127], v[156:159], v[188:191], v[124:127]
	v_mfma_f32_16x16x32_bf16 v[120:123], v[164:167], v[188:191], v[120:123]
	v_mfma_f32_16x16x32_bf16 v[108:111], v[156:159], v[196:199], v[108:111]
	v_mfma_f32_16x16x32_bf16 v[104:107], v[164:167], v[196:199], v[104:107]
	v_mfma_f32_16x16x32_bf16 v[92:95], v[156:159], v[204:207], v[92:95]
	v_mfma_f32_16x16x32_bf16 v[88:91], v[164:167], v[204:207], v[88:91]
	v_mfma_f32_16x16x32_bf16 v[76:79], v[156:159], v[212:215], v[76:79]
	v_mfma_f32_16x16x32_bf16 v[72:75], v[164:167], v[212:215], v[72:75]
	v_mfma_f32_16x16x32_bf16 v[124:127], v[160:163], v[192:195], v[124:127]
	v_mfma_f32_16x16x32_bf16 v[120:123], v[168:171], v[192:195], v[120:123]
	v_mfma_f32_16x16x32_bf16 v[108:111], v[160:163], v[200:203], v[108:111]
	v_mfma_f32_16x16x32_bf16 v[104:107], v[168:171], v[200:203], v[104:107]
	v_mfma_f32_16x16x32_bf16 v[92:95], v[160:163], v[208:211], v[92:95]
	v_mfma_f32_16x16x32_bf16 v[88:91], v[168:171], v[208:211], v[88:91]
	v_mfma_f32_16x16x32_bf16 v[76:79], v[160:163], v[216:219], v[76:79]
	v_mfma_f32_16x16x32_bf16 v[72:75], v[168:171], v[216:219], v[72:75]
	v_mfma_f32_16x16x32_bf16 v[116:119], v[172:175], v[188:191], v[116:119]
	v_mfma_f32_16x16x32_bf16 v[112:115], v[180:183], v[188:191], v[112:115]
	v_mfma_f32_16x16x32_bf16 v[100:103], v[172:175], v[196:199], v[100:103]
	v_mfma_f32_16x16x32_bf16 v[96:99], v[180:183], v[196:199], v[96:99]
	v_mfma_f32_16x16x32_bf16 v[84:87], v[172:175], v[204:207], v[84:87]
	v_mfma_f32_16x16x32_bf16 v[80:83], v[180:183], v[204:207], v[80:83]
	v_mfma_f32_16x16x32_bf16 v[68:71], v[172:175], v[212:215], v[68:71]
	v_mfma_f32_16x16x32_bf16 v[64:67], v[180:183], v[212:215], v[64:67]
	v_mfma_f32_16x16x32_bf16 v[116:119], v[176:179], v[192:195], v[116:119]
	v_mfma_f32_16x16x32_bf16 v[112:115], v[184:187], v[192:195], v[112:115]
	v_mfma_f32_16x16x32_bf16 v[100:103], v[176:179], v[200:203], v[100:103]
	v_mfma_f32_16x16x32_bf16 v[96:99], v[184:187], v[200:203], v[96:99]
	v_mfma_f32_16x16x32_bf16 v[84:87], v[176:179], v[208:211], v[84:87]
	v_mfma_f32_16x16x32_bf16 v[80:83], v[184:187], v[208:211], v[80:83]
	v_mfma_f32_16x16x32_bf16 v[68:71], v[176:179], v[216:219], v[68:71]
	v_mfma_f32_16x16x32_bf16 v[64:67], v[184:187], v[216:219], v[64:67]
	s_barrier
	s_mov_b32 m0, s45
	v_lshl_add_u64 v[222:223], s[40:41], 0, v[130:131]
	s_add_u32 s18, s40, 0x100000
	ds_read_b128 v[188:191], v151 offset:16384
	ds_read_b128 v[192:195], v151 offset:17408
	ds_read_b128 v[196:199], v151 offset:18432
	ds_read_b128 v[200:203], v151 offset:19456
	ds_read_b128 v[204:207], v151 offset:20480
	ds_read_b128 v[208:211], v151 offset:21504
	ds_read_b128 v[212:215], v151 offset:22528
	ds_read_b128 v[216:219], v151 offset:23552
	global_load_lds_dwordx4 v[222:223], off
	v_lshl_add_u64 v[224:225], s[40:41], 0, v[134:135]
	s_mov_b32 m0, s46
	s_addc_u32 s19, s41, 0
	global_load_lds_dwordx4 v[224:225], off
	v_lshl_add_u64 v[226:227], s[18:19], 0, v[130:131]
	s_mov_b32 m0, s47
	v_lshl_add_u64 v[228:229], s[42:43], 0, v[132:133]
	global_load_lds_dwordx4 v[226:227], off
	s_mov_b32 m0, s74
	v_lshl_add_u64 v[226:227], s[18:19], 0, v[134:135]
	global_load_lds_dwordx4 v[226:227], off
	s_mov_b32 m0, s23
	v_lshl_add_u64 v[226:227], s[42:43], 0, v[128:129]
	global_load_lds_dwordx4 v[226:227], off
	s_mov_b32 m0, s67
	s_nop 0
	global_load_lds_dwordx4 v[228:229], off
	s_waitcnt vmcnt(8) lgkmcnt(0)
	s_barrier
; #define PG8_STAGE(bufoff, gbase, voff) do { _Pragma("unroll") for (int _i = 0; _i < 2; ++_i) \
;         __builtin_amdgcn_global_load_lds((const unsigned*)((const char*)(gbase) + (voff)[_i]), (LAS unsigned*)(lds + (bufoff) + ldsw + _i * 8192), 16, 0, 0); } while (0)
; #define PG8_LDA(dst, b, h) do { _Pragma("unroll") for (int m = 0; m < 4; ++m) _Pragma("unroll") for (int k = 0; k < 2; ++k) dst[m][k] = *(const LAS bf16x8*)(lds + PG8_SA(b, h) + aoff + m * 2048 + k * 1024); } while (0)
; #define PG8_LDB(dst, b, h) do { _Pragma("unroll") for (int n = 0; n < 2; ++n) _Pragma("unroll") for (int k = 0; k < 2; ++k) dst[n][k] = *(const LAS bf16x8*)(lds + PG8_SB(b, h) + boff + n * 2048 + k * 1024); } while (0)
; #define PG8_MMA(ai, bj, At, Bt) do { __builtin_amdgcn_s_setprio(1); _Pragma("unroll") for (int m = 0; m < 4; ++m) _Pragma("unroll") for (int n = 0; n < 2; ++n) _Pragma("unroll") for (int k = 0; k < 2; ++k) \
;         acc[ai][bj][m][n] = __builtin_amdgcn_mfma_f32_16x16x32_bf16(Bt[n][k], At[m][k], acc[ai][bj][m][n], 0, 0, 0); __builtin_amdgcn_s_setprio(0); } while (0)
; #define PG8_WAIT_V(n) asm volatile("s_waitcnt vmcnt(" #n ")" ::: "memory")
; #define PG8_WAIT_L(n) asm volatile("s_waitcnt lgkmcnt(" #n ")" ::: "memory")
; #define PG8_BAR __builtin_amdgcn_s_barrier()
; #define PG8_SCHED __builtin_amdgcn_sched_barrier(0)
; template <class Epi, class Sched, bool ALIGN_EPI>
; __device__ __forceinline__ void gemm_phase(LAS unsigned char* lds, const Gemm g, const Sched& S, const Epi& E) {
;     ...
;             PG8_WAIT_V(8); PG8_WAIT_L(0); PG8_BAR; PG8_MMA(1, 0, At, B0); PG8_MMA(1, 1, At, B1); PG8_BAR; PG8_SCHED;
;             PG8_LDB(B0, 1, 0); PG8_LDB(B1, 1, 1); PG8_SCHED; PG8_LDA(At, 1, 0); PG8_STAGE(PG8_SA(0, 1), a2 + hA, voffA);
;             PG8_WAIT_V(8); PG8_WAIT_L(0); PG8_BAR; PG8_MMA(0, 0, At, B0); PG8_MMA(0, 1, At, B1); PG8_BAR; PG8_SCHED;
	v_mfma_f32_16x16x32_bf16 v[60:63], v[156:159], v[188:191], v[60:63]
	v_mfma_f32_16x16x32_bf16 v[56:59], v[164:167], v[188:191], v[56:59]
	v_mfma_f32_16x16x32_bf16 v[44:47], v[156:159], v[196:199], v[44:47]
	v_mfma_f32_16x16x32_bf16 v[40:43], v[164:167], v[196:199], v[40:43]
	v_mfma_f32_16x16x32_bf16 v[28:31], v[156:159], v[204:207], v[28:31]
	v_mfma_f32_16x16x32_bf16 v[24:27], v[164:167], v[204:207], v[24:27]
	v_mfma_f32_16x16x32_bf16 v[12:15], v[156:159], v[212:215], v[12:15]
	v_mfma_f32_16x16x32_bf16 v[8:11], v[164:167], v[212:215], v[8:11]
	v_mfma_f32_16x16x32_bf16 v[60:63], v[160:163], v[192:195], v[60:63]
	v_mfma_f32_16x16x32_bf16 v[56:59], v[168:171], v[192:195], v[56:59]
	v_mfma_f32_16x16x32_bf16 v[44:47], v[160:163], v[200:203], v[44:47]
	v_mfma_f32_16x16x32_bf16 v[40:43], v[168:171], v[200:203], v[40:43]
	v_mfma_f32_16x16x32_bf16 v[28:31], v[160:163], v[208:211], v[28:31]
	v_mfma_f32_16x16x32_bf16 v[24:27], v[168:171], v[208:211], v[24:27]
	v_mfma_f32_16x16x32_bf16 v[12:15], v[160:163], v[216:219], v[12:15]
	v_mfma_f32_16x16x32_bf16 v[8:11], v[168:171], v[216:219], v[8:11]
	v_mfma_f32_16x16x32_bf16 v[52:55], v[172:175], v[188:191], v[52:55]
	v_mfma_f32_16x16x32_bf16 v[48:51], v[180:183], v[188:191], v[48:51]
	v_mfma_f32_16x16x32_bf16 v[36:39], v[172:175], v[196:199], v[36:39]
	v_mfma_f32_16x16x32_bf16 v[32:35], v[180:183], v[196:199], v[32:35]
	v_mfma_f32_16x16x32_bf16 v[20:23], v[172:175], v[204:207], v[20:23]
	v_mfma_f32_16x16x32_bf16 v[16:19], v[180:183], v[204:207], v[16:19]
	v_mfma_f32_16x16x32_bf16 v[4:7], v[172:175], v[212:215], v[4:7]
	v_mfma_f32_16x16x32_bf16 v[0:3], v[180:183], v[212:215], v[0:3]
	v_mfma_f32_16x16x32_bf16 v[52:55], v[176:179], v[192:195], v[52:55]
	v_mfma_f32_16x16x32_bf16 v[48:51], v[184:187], v[192:195], v[48:51]
	v_mfma_f32_16x16x32_bf16 v[36:39], v[176:179], v[200:203], v[36:39]
	v_mfma_f32_16x16x32_bf16 v[32:35], v[184:187], v[200:203], v[32:35]
	v_mfma_f32_16x16x32_bf16 v[20:23], v[176:179], v[208:211], v[20:23]
	v_mfma_f32_16x16x32_bf16 v[16:19], v[184:187], v[208:211], v[16:19]
	v_mfma_f32_16x16x32_bf16 v[4:7], v[176:179], v[216:219], v[4:7]
	v_mfma_f32_16x16x32_bf16 v[0:3], v[184:187], v[216:219], v[0:3]
	s_barrier
	s_add_i32 s33, 0, 0x1c000
	v_add_u32_e32 v155, s33, v150
	ds_read_b128 v[156:159], v154
	ds_read_b128 v[160:163], v154 offset:1024
	ds_read_b128 v[164:167], v154 offset:2048
	ds_read_b128 v[168:171], v154 offset:3072
	ds_read_b128 v[172:175], v155
	ds_read_b128 v[176:179], v155 offset:1024
	ds_read_b128 v[180:183], v155 offset:2048
	ds_read_b128 v[184:187], v155 offset:3072
	s_add_u32 s18, s42, 0x80000
	s_addc_u32 s19, s43, 0
	s_mov_b32 m0, s68
	v_lshl_add_u64 v[230:231], s[18:19], 0, v[128:129]
	ds_read_b128 v[188:191], v151 offset:32768
	ds_read_b128 v[192:195], v151 offset:33792
	ds_read_b128 v[196:199], v151 offset:34816
	ds_read_b128 v[200:203], v151 offset:35840
	ds_read_b128 v[204:207], v151 offset:36864
	ds_read_b128 v[208:211], v151 offset:37888
	ds_read_b128 v[212:215], v151 offset:38912
	ds_read_b128 v[216:219], v151 offset:39936
	global_load_lds_dwordx4 v[230:231], off
	s_mov_b32 m0, s69
	v_lshl_add_u64 v[230:231], s[18:19], 0, v[132:133]
	global_load_lds_dwordx4 v[230:231], off
	s_waitcnt vmcnt(8) lgkmcnt(0)
	s_barrier
	v_mfma_f32_16x16x32_bf16 v[124:127], v[156:159], v[188:191], v[124:127]
	v_mfma_f32_16x16x32_bf16 v[120:123], v[164:167], v[188:191], v[120:123]
	v_mfma_f32_16x16x32_bf16 v[108:111], v[156:159], v[196:199], v[108:111]
	v_mfma_f32_16x16x32_bf16 v[104:107], v[164:167], v[196:199], v[104:107]
	v_mfma_f32_16x16x32_bf16 v[92:95], v[156:159], v[204:207], v[92:95]
	v_mfma_f32_16x16x32_bf16 v[88:91], v[164:167], v[204:207], v[88:91]
	v_mfma_f32_16x16x32_bf16 v[76:79], v[156:159], v[212:215], v[76:79]
	v_mfma_f32_16x16x32_bf16 v[72:75], v[164:167], v[212:215], v[72:75]
	v_mfma_f32_16x16x32_bf16 v[124:127], v[160:163], v[192:195], v[124:127]
	v_mfma_f32_16x16x32_bf16 v[120:123], v[168:171], v[192:195], v[120:123]
	v_mfma_f32_16x16x32_bf16 v[108:111], v[160:163], v[200:203], v[108:111]
	v_mfma_f32_16x16x32_bf16 v[104:107], v[168:171], v[200:203], v[104:107]
	v_mfma_f32_16x16x32_bf16 v[92:95], v[160:163], v[208:211], v[92:95]
	v_mfma_f32_16x16x32_bf16 v[88:91], v[168:171], v[208:211], v[88:91]
	v_mfma_f32_16x16x32_bf16 v[76:79], v[160:163], v[216:219], v[76:79]
	v_mfma_f32_16x16x32_bf16 v[72:75], v[168:171], v[216:219], v[72:75]
	v_mfma_f32_16x16x32_bf16 v[116:119], v[172:175], v[188:191], v[116:119]
	v_mfma_f32_16x16x32_bf16 v[112:115], v[180:183], v[188:191], v[112:115]
	v_mfma_f32_16x16x32_bf16 v[100:103], v[172:175], v[196:199], v[100:103]
	v_mfma_f32_16x16x32_bf16 v[96:99], v[180:183], v[196:199], v[96:99]
	v_mfma_f32_16x16x32_bf16 v[84:87], v[172:175], v[204:207], v[84:87]
	v_mfma_f32_16x16x32_bf16 v[80:83], v[180:183], v[204:207], v[80:83]
	v_mfma_f32_16x16x32_bf16 v[68:71], v[172:175], v[212:215], v[68:71]
	v_mfma_f32_16x16x32_bf16 v[64:67], v[180:183], v[212:215], v[64:67]
	v_mfma_f32_16x16x32_bf16 v[116:119], v[176:179], v[192:195], v[116:119]
	v_mfma_f32_16x16x32_bf16 v[112:115], v[184:187], v[192:195], v[112:115]
	v_mfma_f32_16x16x32_bf16 v[100:103], v[176:179], v[200:203], v[100:103]
	v_mfma_f32_16x16x32_bf16 v[96:99], v[184:187], v[200:203], v[96:99]
	v_mfma_f32_16x16x32_bf16 v[84:87], v[176:179], v[208:211], v[84:87]
	v_mfma_f32_16x16x32_bf16 v[80:83], v[184:187], v[208:211], v[80:83]
	v_mfma_f32_16x16x32_bf16 v[68:71], v[176:179], v[216:219], v[68:71]
	v_mfma_f32_16x16x32_bf16 v[64:67], v[184:187], v[216:219], v[64:67]
	s_barrier
; #define PG8_STAGE(bufoff, gbase, voff) do { _Pragma("unroll") for (int _i = 0; _i < 2; ++_i) \
;         __builtin_amdgcn_global_load_lds((const unsigned*)((const char*)(gbase) + (voff)[_i]), (LAS unsigned*)(lds + (bufoff) + ldsw + _i * 8192), 16, 0, 0); } while (0)
; #define PG8_LDA(dst, b, h) do { _Pragma("unroll") for (int m = 0; m < 4; ++m) _Pragma("unroll") for (int k = 0; k < 2; ++k) dst[m][k] = *(const LAS bf16x8*)(lds + PG8_SA(b, h) + aoff + m * 2048 + k * 1024); } while (0)
; #define PG8_MMA(ai, bj, At, Bt) do { __builtin_amdgcn_s_setprio(1); _Pragma("unroll") for (int m = 0; m < 4; ++m) _Pragma("unroll") for (int n = 0; n < 2; ++n) _Pragma("unroll") for (int k = 0; k < 2; ++k) \
;         acc[ai][bj][m][n] = __builtin_amdgcn_mfma_f32_16x16x32_bf16(Bt[n][k], At[m][k], acc[ai][bj][m][n], 0, 0, 0); __builtin_amdgcn_s_setprio(0); } while (0)
; #define PG8_WAIT_V(n) asm volatile("s_waitcnt vmcnt(" #n ")" ::: "memory")
; #define PG8_WAIT_L(n) asm volatile("s_waitcnt lgkmcnt(" #n ")" ::: "memory")
; #define PG8_BAR __builtin_amdgcn_s_barrier()
; #define PG8_SCHED __builtin_amdgcn_sched_barrier(0)
; template <class Epi, class Sched, bool ALIGN_EPI>
; __device__ __forceinline__ void gemm_phase(LAS unsigned char* lds, const Gemm g, const Sched& S, const Epi& E) {
;     ...
;             PG8_LDA(At, 1, 1); PG8_STAGE(PG8_SB(1, 0), b3, voffB); PG8_STAGE(PG8_SB(1, 1), b3 + hB, voffB); PG8_STAGE(PG8_SA(1, 0), a3, voffA);
;             PG8_WAIT_V(8); PG8_WAIT_L(0); PG8_BAR; PG8_MMA(1, 0, At, B0); PG8_MMA(1, 1, At, B1); PG8_BAR; PG8_SCHED;
;         }
	s_add_i32 s18, s61, s11
	v_lshl_add_u64 v[222:223], v[222:223], 0, s[6:7]
	s_mov_b32 m0, s18
	ds_read_b128 v[188:191], v151 offset:49152
	ds_read_b128 v[192:195], v151 offset:50176
	ds_read_b128 v[196:199], v151 offset:51200
	ds_read_b128 v[200:203], v151 offset:52224
	ds_read_b128 v[204:207], v151 offset:53248
	ds_read_b128 v[208:211], v151 offset:54272
	ds_read_b128 v[212:215], v151 offset:55296
	ds_read_b128 v[216:219], v151 offset:56320
	global_load_lds_dwordx4 v[222:223], off
	s_add_i32 m0, s18, 0x2000
	s_add_u32 s18, s40, 0x100080
	v_lshl_add_u64 v[222:223], v[224:225], 0, s[6:7]
	s_addc_u32 s19, s41, 0
	s_add_i32 s33, s33, s11
	global_load_lds_dwordx4 v[222:223], off
	s_mov_b32 m0, s33
	v_lshl_add_u64 v[222:223], s[18:19], 0, v[130:131]
	global_load_lds_dwordx4 v[222:223], off
	s_add_i32 m0, s33, 0x2000
	v_lshl_add_u64 v[222:223], s[18:19], 0, v[134:135]
	global_load_lds_dwordx4 v[222:223], off
	s_mov_b32 m0, s70
	v_lshl_add_u64 v[222:223], v[226:227], 0, s[6:7]
	global_load_lds_dwordx4 v[222:223], off
	s_mov_b32 m0, s71
	v_lshl_add_u64 v[222:223], v[228:229], 0, s[6:7]
	global_load_lds_dwordx4 v[222:223], off
	s_waitcnt vmcnt(8) lgkmcnt(0)
	s_barrier
	v_mfma_f32_16x16x32_bf16 v[60:63], v[156:159], v[188:191], v[60:63]
	v_mfma_f32_16x16x32_bf16 v[56:59], v[164:167], v[188:191], v[56:59]
	v_mfma_f32_16x16x32_bf16 v[44:47], v[156:159], v[196:199], v[44:47]
	v_mfma_f32_16x16x32_bf16 v[40:43], v[164:167], v[196:199], v[40:43]
	v_mfma_f32_16x16x32_bf16 v[28:31], v[156:159], v[204:207], v[28:31]
	v_mfma_f32_16x16x32_bf16 v[24:27], v[164:167], v[204:207], v[24:27]
	v_mfma_f32_16x16x32_bf16 v[12:15], v[156:159], v[212:215], v[12:15]
	v_mfma_f32_16x16x32_bf16 v[8:11], v[164:167], v[212:215], v[8:11]
	v_mfma_f32_16x16x32_bf16 v[60:63], v[160:163], v[192:195], v[60:63]
	v_mfma_f32_16x16x32_bf16 v[56:59], v[168:171], v[192:195], v[56:59]
	v_mfma_f32_16x16x32_bf16 v[44:47], v[160:163], v[200:203], v[44:47]
	v_mfma_f32_16x16x32_bf16 v[40:43], v[168:171], v[200:203], v[40:43]
	v_mfma_f32_16x16x32_bf16 v[28:31], v[160:163], v[208:211], v[28:31]
	v_mfma_f32_16x16x32_bf16 v[24:27], v[168:171], v[208:211], v[24:27]
	v_mfma_f32_16x16x32_bf16 v[12:15], v[160:163], v[216:219], v[12:15]
	v_mfma_f32_16x16x32_bf16 v[8:11], v[168:171], v[216:219], v[8:11]
	v_mfma_f32_16x16x32_bf16 v[52:55], v[172:175], v[188:191], v[52:55]
	v_mfma_f32_16x16x32_bf16 v[48:51], v[180:183], v[188:191], v[48:51]
	v_mfma_f32_16x16x32_bf16 v[36:39], v[172:175], v[196:199], v[36:39]
	v_mfma_f32_16x16x32_bf16 v[32:35], v[180:183], v[196:199], v[32:35]
	v_mfma_f32_16x16x32_bf16 v[20:23], v[172:175], v[204:207], v[20:23]
	v_mfma_f32_16x16x32_bf16 v[16:19], v[180:183], v[204:207], v[16:19]
	v_mfma_f32_16x16x32_bf16 v[4:7], v[172:175], v[212:215], v[4:7]
	v_mfma_f32_16x16x32_bf16 v[0:3], v[180:183], v[212:215], v[0:3]
	v_mfma_f32_16x16x32_bf16 v[52:55], v[176:179], v[192:195], v[52:55]
	v_mfma_f32_16x16x32_bf16 v[48:51], v[184:187], v[192:195], v[48:51]
	v_mfma_f32_16x16x32_bf16 v[36:39], v[176:179], v[200:203], v[36:39]
	v_mfma_f32_16x16x32_bf16 v[32:35], v[184:187], v[200:203], v[32:35]
	v_mfma_f32_16x16x32_bf16 v[20:23], v[176:179], v[208:211], v[20:23]
	v_mfma_f32_16x16x32_bf16 v[16:19], v[184:187], v[208:211], v[16:19]
	v_mfma_f32_16x16x32_bf16 v[4:7], v[176:179], v[216:219], v[4:7]
	v_mfma_f32_16x16x32_bf16 v[0:3], v[184:187], v[216:219], v[0:3]
	s_barrier
	s_add_u32 s38, s38, 0x100
	s_addc_u32 s39, s39, 0
	s_cmp_ge_i32 s75, s56
	s_mov_b32 s40, s75
	s_cbranch_scc0 .LBB0_955

; #define PG8_STAGE(bufoff, gbase, voff) do { _Pragma("unroll") for (int _i = 0; _i < 2; ++_i) \
;         __builtin_amdgcn_global_load_lds((const unsigned*)((const char*)(gbase) + (voff)[_i]), (LAS unsigned*)(lds + (bufoff) + ldsw + _i * 8192), 16, 0, 0); } while (0)
; #define PG8_LDA(dst, b, h) do { _Pragma("unroll") for (int m = 0; m < 4; ++m) _Pragma("unroll") for (int k = 0; k < 2; ++k) dst[m][k] = *(const LAS bf16x8*)(lds + PG8_SA(b, h) + aoff + m * 2048 + k * 1024); } while (0)
; #define PG8_LDB(dst, b, h) do { _Pragma("unroll") for (int n = 0; n < 2; ++n) _Pragma("unroll") for (int k = 0; k < 2; ++k) dst[n][k] = *(const LAS bf16x8*)(lds + PG8_SB(b, h) + boff + n * 2048 + k * 1024); } while (0)
; #define PG8_MMA(ai, bj, At, Bt) do { __builtin_amdgcn_s_setprio(1); _Pragma("unroll") for (int m = 0; m < 4; ++m) _Pragma("unroll") for (int n = 0; n < 2; ++n) _Pragma("unroll") for (int k = 0; k < 2; ++k) \
;         acc[ai][bj][m][n] = __builtin_amdgcn_mfma_f32_16x16x32_bf16(Bt[n][k], At[m][k], acc[ai][bj][m][n], 0, 0, 0); __builtin_amdgcn_s_setprio(0); } while (0)
; #define PG8_WAIT_V(n) asm volatile("s_waitcnt vmcnt(" #n ")" ::: "memory")
; #define PG8_WAIT_L(n) asm volatile("s_waitcnt lgkmcnt(" #n ")" ::: "memory")
; #define PG8_BAR __builtin_amdgcn_s_barrier()
; #define PG8_SCHED __builtin_amdgcn_sched_barrier(0)
; template <class Epi, class Sched, bool ALIGN_EPI>
; __device__ __forceinline__ void gemm_phase(LAS unsigned char* lds, const Gemm g, const Sched& S, const Epi& E) {
;     ...
;             const bool last = (t == nt - 2);
;             const char* a1 = cA + (size_t)(t + 1) * kstep;
;             const char* a2 = last ? nA : cA + (size_t)(t + 2) * kstep; const char* b2 = last ? nB : cB + (size_t)(t + 2) * kstep;
;             const char* a3 = a2 + kstep; const char* b3 = b2 + kstep;
;             PG8_LDB(B0, 0, 0); PG8_LDB(B1, 0, 1); PG8_SCHED; PG8_LDA(At, 0, 0); PG8_STAGE(PG8_SA(1, 1), a1 + hA, voffA);
;             PG8_WAIT_V(8); PG8_WAIT_L(0); PG8_BAR; PG8_MMA(0, 0, At, B0); PG8_MMA(0, 1, At, B1); PG8_BAR; PG8_SCHED;
;             PG8_LDA(At, 0, 1); PG8_STAGE(PG8_SB(0, 0), b2, voffB); PG8_STAGE(PG8_SB(0, 1), b2 + hB, voffB); PG8_STAGE(PG8_SA(0, 0), a2, voffA);
;             PG8_WAIT_V(8); PG8_WAIT_L(0); PG8_BAR; PG8_MMA(1, 0, At, B0); PG8_MMA(1, 1, At, B1); PG8_BAR; PG8_SCHED;
.LBB0_1065:
	ds_read_b128 v[144:147], v151
	ds_read_b128 v[156:159], v151 offset:1024
	ds_read_b128 v[160:163], v151 offset:2048
	ds_read_b128 v[164:167], v151 offset:3072
	ds_read_b128 v[168:171], v152
	ds_read_b128 v[172:175], v152 offset:1024
	ds_read_b128 v[176:179], v152 offset:2048
	ds_read_b128 v[180:183], v152 offset:3072
	s_add_i32 s47, s46, 2
	s_add_u32 s18, s52, 0xfffc0080
	s_addc_u32 s19, s53, -1
	s_cmp_eq_u32 s68, s46
	s_cselect_b32 s57, s11, s19
	s_cselect_b32 s56, s39, s18
	s_cselect_b32 s55, s80, s45
	s_cselect_b32 s54, s81, s44
	v_lshl_add_u64 v[216:217], s[52:53], 0, v[136:137]
	s_add_i32 m0, s60, 0xc000
	ds_read_b128 v[184:187], v153
	ds_read_b128 v[188:191], v153 offset:1024
	ds_read_b128 v[192:195], v153 offset:2048
	ds_read_b128 v[196:199], v153 offset:3072
	ds_read_b128 v[200:203], v153 offset:4096
	ds_read_b128 v[204:207], v153 offset:5120
	ds_read_b128 v[208:211], v153 offset:6144
	ds_read_b128 v[212:215], v153 offset:7168
	global_load_lds_dwordx4 v[216:217], off
	s_add_i32 m0, s60, 0xe000
	v_lshl_add_u64 v[216:217], s[52:53], 0, v[138:139]
	global_load_lds_dwordx4 v[216:217], off
	s_waitcnt vmcnt(8) lgkmcnt(0)
	s_barrier
	v_mfma_f32_16x16x32_bf16 v[124:127], v[144:147], v[184:187], v[124:127]
	v_mfma_f32_16x16x32_bf16 v[120:123], v[160:163], v[184:187], v[120:123]
	v_mfma_f32_16x16x32_bf16 v[108:111], v[144:147], v[192:195], v[108:111]
	v_mfma_f32_16x16x32_bf16 v[104:107], v[160:163], v[192:195], v[104:107]
	v_mfma_f32_16x16x32_bf16 v[92:95], v[144:147], v[200:203], v[92:95]
	v_mfma_f32_16x16x32_bf16 v[88:91], v[160:163], v[200:203], v[88:91]
	v_mfma_f32_16x16x32_bf16 v[76:79], v[144:147], v[208:211], v[76:79]
	v_mfma_f32_16x16x32_bf16 v[72:75], v[160:163], v[208:211], v[72:75]
	v_mfma_f32_16x16x32_bf16 v[124:127], v[156:159], v[188:191], v[124:127]
	v_mfma_f32_16x16x32_bf16 v[120:123], v[164:167], v[188:191], v[120:123]
	v_mfma_f32_16x16x32_bf16 v[108:111], v[156:159], v[196:199], v[108:111]
	v_mfma_f32_16x16x32_bf16 v[104:107], v[164:167], v[196:199], v[104:107]
	v_mfma_f32_16x16x32_bf16 v[92:95], v[156:159], v[204:207], v[92:95]
	v_mfma_f32_16x16x32_bf16 v[88:91], v[164:167], v[204:207], v[88:91]
	v_mfma_f32_16x16x32_bf16 v[76:79], v[156:159], v[212:215], v[76:79]
	v_mfma_f32_16x16x32_bf16 v[72:75], v[164:167], v[212:215], v[72:75]
	v_mfma_f32_16x16x32_bf16 v[116:119], v[168:171], v[184:187], v[116:119]
	v_mfma_f32_16x16x32_bf16 v[112:115], v[176:179], v[184:187], v[112:115]
	v_mfma_f32_16x16x32_bf16 v[100:103], v[168:171], v[192:195], v[100:103]
	v_mfma_f32_16x16x32_bf16 v[96:99], v[176:179], v[192:195], v[96:99]
	v_mfma_f32_16x16x32_bf16 v[84:87], v[168:171], v[200:203], v[84:87]
	v_mfma_f32_16x16x32_bf16 v[80:83], v[176:179], v[200:203], v[80:83]
	v_mfma_f32_16x16x32_bf16 v[68:71], v[168:171], v[208:211], v[68:71]
	v_mfma_f32_16x16x32_bf16 v[64:67], v[176:179], v[208:211], v[64:67]
	v_mfma_f32_16x16x32_bf16 v[116:119], v[172:175], v[188:191], v[116:119]
	v_mfma_f32_16x16x32_bf16 v[112:115], v[180:183], v[188:191], v[112:115]
	v_mfma_f32_16x16x32_bf16 v[100:103], v[172:175], v[196:199], v[100:103]
	v_mfma_f32_16x16x32_bf16 v[96:99], v[180:183], v[196:199], v[96:99]
	v_mfma_f32_16x16x32_bf16 v[84:87], v[172:175], v[204:207], v[84:87]
	v_mfma_f32_16x16x32_bf16 v[80:83], v[180:183], v[204:207], v[80:83]
	v_mfma_f32_16x16x32_bf16 v[68:71], v[172:175], v[212:215], v[68:71]
	v_mfma_f32_16x16x32_bf16 v[64:67], v[180:183], v[212:215], v[64:67]
	s_barrier
	s_add_i32 s18, s74, s59
	v_lshl_add_u64 v[216:217], s[54:55], 0, v[130:131]
	s_mov_b32 m0, s18
	ds_read_b128 v[184:187], v153 offset:16384
	ds_read_b128 v[188:191], v153 offset:17408
	ds_read_b128 v[192:195], v153 offset:18432
	ds_read_b128 v[196:199], v153 offset:19456
	ds_read_b128 v[200:203], v153 offset:20480
	ds_read_b128 v[204:207], v153 offset:21504
	ds_read_b128 v[208:211], v153 offset:22528
	ds_read_b128 v[212:215], v153 offset:23552
	global_load_lds_dwordx4 v[216:217], off
	s_add_i32 m0, s18, 0x2000
	s_add_u32 s18, s54, 0x40000
	v_lshl_add_u64 v[218:219], s[54:55], 0, v[134:135]
	s_addc_u32 s19, s55, 0
	s_add_i32 s33, s75, s59
	global_load_lds_dwordx4 v[218:219], off
	v_lshl_add_u64 v[222:223], s[18:19], 0, v[130:131]
	s_mov_b32 m0, s33
	v_lshl_add_u64 v[224:225], s[56:57], 0, v[132:133]
	global_load_lds_dwordx4 v[222:223], off
	s_add_i32 m0, s33, 0x2000
	v_lshl_add_u64 v[222:223], s[18:19], 0, v[134:135]
	global_load_lds_dwordx4 v[222:223], off
	s_mov_b32 m0, s60
	v_lshl_add_u64 v[222:223], s[56:57], 0, v[128:129]
	global_load_lds_dwordx4 v[222:223], off
	s_mov_b32 m0, s61
	s_nop 0
	global_load_lds_dwordx4 v[224:225], off
	s_waitcnt vmcnt(8) lgkmcnt(0)
	s_barrier
; #define PG8_STAGE(bufoff, gbase, voff) do { _Pragma("unroll") for (int _i = 0; _i < 2; ++_i) \
;         __builtin_amdgcn_global_load_lds((const unsigned*)((const char*)(gbase) + (voff)[_i]), (LAS unsigned*)(lds + (bufoff) + ldsw + _i * 8192), 16, 0, 0); } while (0)
; #define PG8_LDA(dst, b, h) do { _Pragma("unroll") for (int m = 0; m < 4; ++m) _Pragma("unroll") for (int k = 0; k < 2; ++k) dst[m][k] = *(const LAS bf16x8*)(lds + PG8_SA(b, h) + aoff + m * 2048 + k * 1024); } while (0)
; #define PG8_LDB(dst, b, h) do { _Pragma("unroll") for (int n = 0; n < 2; ++n) _Pragma("unroll") for (int k = 0; k < 2; ++k) dst[n][k] = *(const LAS bf16x8*)(lds + PG8_SB(b, h) + boff + n * 2048 + k * 1024); } while (0)
; #define PG8_MMA(ai, bj, At, Bt) do { __builtin_amdgcn_s_setprio(1); _Pragma("unroll") for (int m = 0; m < 4; ++m) _Pragma("unroll") for (int n = 0; n < 2; ++n) _Pragma("unroll") for (int k = 0; k < 2; ++k) \
;         acc[ai][bj][m][n] = __builtin_amdgcn_mfma_f32_16x16x32_bf16(Bt[n][k], At[m][k], acc[ai][bj][m][n], 0, 0, 0); __builtin_amdgcn_s_setprio(0); } while (0)
; #define PG8_WAIT_V(n) asm volatile("s_waitcnt vmcnt(" #n ")" ::: "memory")
; #define PG8_WAIT_L(n) asm volatile("s_waitcnt lgkmcnt(" #n ")" ::: "memory")
; #define PG8_BAR __builtin_amdgcn_s_barrier()
; #define PG8_SCHED __builtin_amdgcn_sched_barrier(0)
; template <class Epi, class Sched, bool ALIGN_EPI>
; __device__ __forceinline__ void gemm_phase(LAS unsigned char* lds, const Gemm g, const Sched& S, const Epi& E) {
;     ...
;             PG8_WAIT_V(8); PG8_WAIT_L(0); PG8_BAR; PG8_MMA(1, 0, At, B0); PG8_MMA(1, 1, At, B1); PG8_BAR; PG8_SCHED;
;             PG8_LDB(B0, 1, 0); PG8_LDB(B1, 1, 1); PG8_SCHED; PG8_LDA(At, 1, 0); PG8_STAGE(PG8_SA(0, 1), a2 + hA, voffA);
;             PG8_WAIT_V(8); PG8_WAIT_L(0); PG8_BAR; PG8_MMA(0, 0, At, B0); PG8_MMA(0, 1, At, B1); PG8_BAR; PG8_SCHED;
	v_mfma_f32_16x16x32_bf16 v[60:63], v[144:147], v[184:187], v[60:63]
	v_mfma_f32_16x16x32_bf16 v[56:59], v[160:163], v[184:187], v[56:59]
	v_mfma_f32_16x16x32_bf16 v[44:47], v[144:147], v[192:195], v[44:47]
	v_mfma_f32_16x16x32_bf16 v[40:43], v[160:163], v[192:195], v[40:43]
	v_mfma_f32_16x16x32_bf16 v[28:31], v[144:147], v[200:203], v[28:31]
	v_mfma_f32_16x16x32_bf16 v[24:27], v[160:163], v[200:203], v[24:27]
	v_mfma_f32_16x16x32_bf16 v[12:15], v[144:147], v[208:211], v[12:15]
	v_mfma_f32_16x16x32_bf16 v[8:11], v[160:163], v[208:211], v[8:11]
	v_mfma_f32_16x16x32_bf16 v[60:63], v[156:159], v[188:191], v[60:63]
	v_mfma_f32_16x16x32_bf16 v[56:59], v[164:167], v[188:191], v[56:59]
	v_mfma_f32_16x16x32_bf16 v[44:47], v[156:159], v[196:199], v[44:47]
	v_mfma_f32_16x16x32_bf16 v[40:43], v[164:167], v[196:199], v[40:43]
	v_mfma_f32_16x16x32_bf16 v[28:31], v[156:159], v[204:207], v[28:31]
	v_mfma_f32_16x16x32_bf16 v[24:27], v[164:167], v[204:207], v[24:27]
	v_mfma_f32_16x16x32_bf16 v[12:15], v[156:159], v[212:215], v[12:15]
	v_mfma_f32_16x16x32_bf16 v[8:11], v[164:167], v[212:215], v[8:11]
	v_mfma_f32_16x16x32_bf16 v[52:55], v[168:171], v[184:187], v[52:55]
	v_mfma_f32_16x16x32_bf16 v[48:51], v[176:179], v[184:187], v[48:51]
	v_mfma_f32_16x16x32_bf16 v[36:39], v[168:171], v[192:195], v[36:39]
	v_mfma_f32_16x16x32_bf16 v[32:35], v[176:179], v[192:195], v[32:35]
	v_mfma_f32_16x16x32_bf16 v[20:23], v[168:171], v[200:203], v[20:23]
	v_mfma_f32_16x16x32_bf16 v[16:19], v[176:179], v[200:203], v[16:19]
	v_mfma_f32_16x16x32_bf16 v[4:7], v[168:171], v[208:211], v[4:7]
	v_mfma_f32_16x16x32_bf16 v[0:3], v[176:179], v[208:211], v[0:3]
	v_mfma_f32_16x16x32_bf16 v[52:55], v[172:175], v[188:191], v[52:55]
	v_mfma_f32_16x16x32_bf16 v[48:51], v[180:183], v[188:191], v[48:51]
	v_mfma_f32_16x16x32_bf16 v[36:39], v[172:175], v[196:199], v[36:39]
	v_mfma_f32_16x16x32_bf16 v[32:35], v[180:183], v[196:199], v[32:35]
	v_mfma_f32_16x16x32_bf16 v[20:23], v[172:175], v[204:207], v[20:23]
	v_mfma_f32_16x16x32_bf16 v[16:19], v[180:183], v[204:207], v[16:19]
	v_mfma_f32_16x16x32_bf16 v[4:7], v[172:175], v[212:215], v[4:7]
	v_mfma_f32_16x16x32_bf16 v[0:3], v[180:183], v[212:215], v[0:3]
	s_barrier
	s_add_i32 s33, 0, 0x18000
	v_add_u32_e32 v155, s33, v149
	s_add_i32 s46, 0, 0x1c000
	ds_read_b128 v[144:147], v155
	ds_read_b128 v[156:159], v155 offset:1024
	ds_read_b128 v[160:163], v155 offset:2048
	ds_read_b128 v[164:167], v155 offset:3072
	v_add_u32_e32 v155, s46, v149
	ds_read_b128 v[168:171], v155
	ds_read_b128 v[172:175], v155 offset:1024
	ds_read_b128 v[176:179], v155 offset:2048
	ds_read_b128 v[180:183], v155 offset:3072
	s_add_u32 s18, s56, 0x40000
	s_addc_u32 s19, s57, 0
	s_mov_b32 m0, s62
	v_lshl_add_u64 v[226:227], s[18:19], 0, v[128:129]
	ds_read_b128 v[184:187], v153 offset:32768
	ds_read_b128 v[188:191], v153 offset:33792
	ds_read_b128 v[192:195], v153 offset:34816
	ds_read_b128 v[196:199], v153 offset:35840
	ds_read_b128 v[200:203], v153 offset:36864
	ds_read_b128 v[204:207], v153 offset:37888
	ds_read_b128 v[208:211], v153 offset:38912
	ds_read_b128 v[212:215], v153 offset:39936
	global_load_lds_dwordx4 v[226:227], off
	s_mov_b32 m0, s63
	v_lshl_add_u64 v[226:227], s[18:19], 0, v[132:133]
	global_load_lds_dwordx4 v[226:227], off
	s_waitcnt vmcnt(8) lgkmcnt(0)
	s_barrier
	v_mfma_f32_16x16x32_bf16 v[124:127], v[144:147], v[184:187], v[124:127]
	v_mfma_f32_16x16x32_bf16 v[120:123], v[160:163], v[184:187], v[120:123]
	v_mfma_f32_16x16x32_bf16 v[108:111], v[144:147], v[192:195], v[108:111]
	v_mfma_f32_16x16x32_bf16 v[104:107], v[160:163], v[192:195], v[104:107]
	v_mfma_f32_16x16x32_bf16 v[92:95], v[144:147], v[200:203], v[92:95]
	v_mfma_f32_16x16x32_bf16 v[88:91], v[160:163], v[200:203], v[88:91]
	v_mfma_f32_16x16x32_bf16 v[76:79], v[144:147], v[208:211], v[76:79]
	v_mfma_f32_16x16x32_bf16 v[72:75], v[160:163], v[208:211], v[72:75]
	v_mfma_f32_16x16x32_bf16 v[124:127], v[156:159], v[188:191], v[124:127]
	v_mfma_f32_16x16x32_bf16 v[120:123], v[164:167], v[188:191], v[120:123]
	v_mfma_f32_16x16x32_bf16 v[108:111], v[156:159], v[196:199], v[108:111]
	v_mfma_f32_16x16x32_bf16 v[104:107], v[164:167], v[196:199], v[104:107]
	v_mfma_f32_16x16x32_bf16 v[92:95], v[156:159], v[204:207], v[92:95]
	v_mfma_f32_16x16x32_bf16 v[88:91], v[164:167], v[204:207], v[88:91]
	v_mfma_f32_16x16x32_bf16 v[76:79], v[156:159], v[212:215], v[76:79]
	v_mfma_f32_16x16x32_bf16 v[72:75], v[164:167], v[212:215], v[72:75]
	v_mfma_f32_16x16x32_bf16 v[116:119], v[168:171], v[184:187], v[116:119]
	v_mfma_f32_16x16x32_bf16 v[112:115], v[176:179], v[184:187], v[112:115]
	v_mfma_f32_16x16x32_bf16 v[100:103], v[168:171], v[192:195], v[100:103]
	v_mfma_f32_16x16x32_bf16 v[96:99], v[176:179], v[192:195], v[96:99]
	v_mfma_f32_16x16x32_bf16 v[84:87], v[168:171], v[200:203], v[84:87]
	v_mfma_f32_16x16x32_bf16 v[80:83], v[176:179], v[200:203], v[80:83]
	v_mfma_f32_16x16x32_bf16 v[68:71], v[168:171], v[208:211], v[68:71]
	v_mfma_f32_16x16x32_bf16 v[64:67], v[176:179], v[208:211], v[64:67]
	v_mfma_f32_16x16x32_bf16 v[116:119], v[172:175], v[188:191], v[116:119]
	v_mfma_f32_16x16x32_bf16 v[112:115], v[180:183], v[188:191], v[112:115]
	v_mfma_f32_16x16x32_bf16 v[100:103], v[172:175], v[196:199], v[100:103]
	v_mfma_f32_16x16x32_bf16 v[96:99], v[180:183], v[196:199], v[96:99]
	v_mfma_f32_16x16x32_bf16 v[84:87], v[172:175], v[204:207], v[84:87]
	v_mfma_f32_16x16x32_bf16 v[80:83], v[180:183], v[204:207], v[80:83]
	v_mfma_f32_16x16x32_bf16 v[68:71], v[172:175], v[212:215], v[68:71]
	v_mfma_f32_16x16x32_bf16 v[64:67], v[180:183], v[212:215], v[64:67]
	s_barrier
; #define PG8_STAGE(bufoff, gbase, voff) do { _Pragma("unroll") for (int _i = 0; _i < 2; ++_i) \
;         __builtin_amdgcn_global_load_lds((const unsigned*)((const char*)(gbase) + (voff)[_i]), (LAS unsigned*)(lds + (bufoff) + ldsw + _i * 8192), 16, 0, 0); } while (0)
; #define PG8_LDA(dst, b, h) do { _Pragma("unroll") for (int m = 0; m < 4; ++m) _Pragma("unroll") for (int k = 0; k < 2; ++k) dst[m][k] = *(const LAS bf16x8*)(lds + PG8_SA(b, h) + aoff + m * 2048 + k * 1024); } while (0)
; #define PG8_MMA(ai, bj, At, Bt) do { __builtin_amdgcn_s_setprio(1); _Pragma("unroll") for (int m = 0; m < 4; ++m) _Pragma("unroll") for (int n = 0; n < 2; ++n) _Pragma("unroll") for (int k = 0; k < 2; ++k) \
;         acc[ai][bj][m][n] = __builtin_amdgcn_mfma_f32_16x16x32_bf16(Bt[n][k], At[m][k], acc[ai][bj][m][n], 0, 0, 0); __builtin_amdgcn_s_setprio(0); } while (0)
; #define PG8_WAIT_V(n) asm volatile("s_waitcnt vmcnt(" #n ")" ::: "memory")
; #define PG8_WAIT_L(n) asm volatile("s_waitcnt lgkmcnt(" #n ")" ::: "memory")
; #define PG8_BAR __builtin_amdgcn_s_barrier()
; #define PG8_SCHED __builtin_amdgcn_sched_barrier(0)
; template <class Epi, class Sched, bool ALIGN_EPI>
; __device__ __forceinline__ void gemm_phase(LAS unsigned char* lds, const Gemm g, const Sched& S, const Epi& E) {
;     ...
;             PG8_LDA(At, 1, 1); PG8_STAGE(PG8_SB(1, 0), b3, voffB); PG8_STAGE(PG8_SB(1, 1), b3 + hB, voffB); PG8_STAGE(PG8_SA(1, 0), a3, voffA);
;             PG8_WAIT_V(8); PG8_WAIT_L(0); PG8_BAR; PG8_MMA(1, 0, At, B0); PG8_MMA(1, 1, At, B1); PG8_BAR; PG8_SCHED;
;         }
	s_add_i32 s18, s33, s59
	v_lshl_add_u64 v[216:217], v[216:217], 0, s[24:25]
	s_mov_b32 m0, s18
	ds_read_b128 v[184:187], v153 offset:49152
	ds_read_b128 v[188:191], v153 offset:50176
	ds_read_b128 v[192:195], v153 offset:51200
	ds_read_b128 v[196:199], v153 offset:52224
	ds_read_b128 v[200:203], v153 offset:53248
	ds_read_b128 v[204:207], v153 offset:54272
	ds_read_b128 v[208:211], v153 offset:55296
	ds_read_b128 v[212:215], v153 offset:56320
	global_load_lds_dwordx4 v[216:217], off
	s_add_i32 m0, s18, 0x2000
	s_add_u32 s18, s54, 0x40080
	v_lshl_add_u64 v[216:217], v[218:219], 0, s[24:25]
	s_addc_u32 s19, s55, 0
	s_add_i32 s33, s46, s59
	global_load_lds_dwordx4 v[216:217], off
	s_mov_b32 m0, s33
	v_lshl_add_u64 v[216:217], s[18:19], 0, v[130:131]
	global_load_lds_dwordx4 v[216:217], off
	s_add_i32 m0, s33, 0x2000
	v_lshl_add_u64 v[216:217], s[18:19], 0, v[134:135]
	global_load_lds_dwordx4 v[216:217], off
	s_mov_b32 m0, s66
	v_lshl_add_u64 v[216:217], v[222:223], 0, s[24:25]
	global_load_lds_dwordx4 v[216:217], off
	s_mov_b32 m0, s67
	v_lshl_add_u64 v[216:217], v[224:225], 0, s[24:25]
	global_load_lds_dwordx4 v[216:217], off
	s_waitcnt vmcnt(8) lgkmcnt(0)
	s_barrier
	v_mfma_f32_16x16x32_bf16 v[60:63], v[144:147], v[184:187], v[60:63]
	v_mfma_f32_16x16x32_bf16 v[56:59], v[160:163], v[184:187], v[56:59]
	v_mfma_f32_16x16x32_bf16 v[44:47], v[144:147], v[192:195], v[44:47]
	v_mfma_f32_16x16x32_bf16 v[40:43], v[160:163], v[192:195], v[40:43]
	v_mfma_f32_16x16x32_bf16 v[28:31], v[144:147], v[200:203], v[28:31]
	v_mfma_f32_16x16x32_bf16 v[24:27], v[160:163], v[200:203], v[24:27]
	v_mfma_f32_16x16x32_bf16 v[12:15], v[144:147], v[208:211], v[12:15]
	v_mfma_f32_16x16x32_bf16 v[8:11], v[160:163], v[208:211], v[8:11]
	v_mfma_f32_16x16x32_bf16 v[60:63], v[156:159], v[188:191], v[60:63]
	v_mfma_f32_16x16x32_bf16 v[56:59], v[164:167], v[188:191], v[56:59]
	v_mfma_f32_16x16x32_bf16 v[44:47], v[156:159], v[196:199], v[44:47]
	v_mfma_f32_16x16x32_bf16 v[40:43], v[164:167], v[196:199], v[40:43]
	v_mfma_f32_16x16x32_bf16 v[28:31], v[156:159], v[204:207], v[28:31]
	v_mfma_f32_16x16x32_bf16 v[24:27], v[164:167], v[204:207], v[24:27]
	v_mfma_f32_16x16x32_bf16 v[12:15], v[156:159], v[212:215], v[12:15]
	v_mfma_f32_16x16x32_bf16 v[8:11], v[164:167], v[212:215], v[8:11]
	v_mfma_f32_16x16x32_bf16 v[52:55], v[168:171], v[184:187], v[52:55]
	v_mfma_f32_16x16x32_bf16 v[48:51], v[176:179], v[184:187], v[48:51]
	v_mfma_f32_16x16x32_bf16 v[36:39], v[168:171], v[192:195], v[36:39]
	v_mfma_f32_16x16x32_bf16 v[32:35], v[176:179], v[192:195], v[32:35]
	v_mfma_f32_16x16x32_bf16 v[20:23], v[168:171], v[200:203], v[20:23]
	v_mfma_f32_16x16x32_bf16 v[16:19], v[176:179], v[200:203], v[16:19]
	v_mfma_f32_16x16x32_bf16 v[4:7], v[168:171], v[208:211], v[4:7]
	v_mfma_f32_16x16x32_bf16 v[0:3], v[176:179], v[208:211], v[0:3]
	v_mfma_f32_16x16x32_bf16 v[52:55], v[172:175], v[188:191], v[52:55]
	v_mfma_f32_16x16x32_bf16 v[48:51], v[180:183], v[188:191], v[48:51]
	v_mfma_f32_16x16x32_bf16 v[36:39], v[172:175], v[196:199], v[36:39]
	v_mfma_f32_16x16x32_bf16 v[32:35], v[180:183], v[196:199], v[32:35]
	v_mfma_f32_16x16x32_bf16 v[20:23], v[172:175], v[204:207], v[20:23]
	v_mfma_f32_16x16x32_bf16 v[16:19], v[180:183], v[204:207], v[16:19]
	v_mfma_f32_16x16x32_bf16 v[4:7], v[172:175], v[212:215], v[4:7]
	v_mfma_f32_16x16x32_bf16 v[0:3], v[180:183], v[212:215], v[0:3]
	s_barrier
	s_add_u32 s52, s52, 0x100
	s_addc_u32 s53, s53, 0
	s_add_u32 s44, s44, 0x100
	s_addc_u32 s45, s45, 0
	s_cmp_ge_i32 s47, s65
	s_mov_b32 s46, s47
	s_cbranch_scc0 .LBB0_1065

; #define PG8_STAGE(bufoff, gbase, voff) do { _Pragma("unroll") for (int _i = 0; _i < 2; ++_i) \
;         __builtin_amdgcn_global_load_lds((const unsigned*)((const char*)(gbase) + (voff)[_i]), (LAS unsigned*)(lds + (bufoff) + ldsw + _i * 8192), 16, 0, 0); } while (0)
; #define PG8_LDA(dst, b, h) do { _Pragma("unroll") for (int m = 0; m < 4; ++m) _Pragma("unroll") for (int k = 0; k < 2; ++k) dst[m][k] = *(const LAS bf16x8*)(lds + PG8_SA(b, h) + aoff + m * 2048 + k * 1024); } while (0)
; #define PG8_LDB(dst, b, h) do { _Pragma("unroll") for (int n = 0; n < 2; ++n) _Pragma("unroll") for (int k = 0; k < 2; ++k) dst[n][k] = *(const LAS bf16x8*)(lds + PG8_SB(b, h) + boff + n * 2048 + k * 1024); } while (0)
; #define PG8_MMA(ai, bj, At, Bt) do { __builtin_amdgcn_s_setprio(1); _Pragma("unroll") for (int m = 0; m < 4; ++m) _Pragma("unroll") for (int n = 0; n < 2; ++n) _Pragma("unroll") for (int k = 0; k < 2; ++k) \
;         acc[ai][bj][m][n] = __builtin_amdgcn_mfma_f32_16x16x32_bf16(Bt[n][k], At[m][k], acc[ai][bj][m][n], 0, 0, 0); __builtin_amdgcn_s_setprio(0); } while (0)
; #define PG8_WAIT_V(n) asm volatile("s_waitcnt vmcnt(" #n ")" ::: "memory")
; #define PG8_WAIT_L(n) asm volatile("s_waitcnt lgkmcnt(" #n ")" ::: "memory")
; #define PG8_BAR __builtin_amdgcn_s_barrier()
; #define PG8_SCHED __builtin_amdgcn_sched_barrier(0)
; template <class Epi, class Sched, bool ALIGN_EPI>
; __device__ __forceinline__ void gemm_phase(LAS unsigned char* lds, const Gemm g, const Sched& S, const Epi& E) {
;     ...
;         for (int t = 0; t < nt; t += 2) {
;             const bool last = (t == nt - 2);
;             const char* a1 = cA + (size_t)(t + 1) * kstep;
;             const char* a2 = last ? nA : cA + (size_t)(t + 2) * kstep; const char* b2 = last ? nB : cB + (size_t)(t + 2) * kstep;
;             const char* a3 = a2 + kstep; const char* b3 = b2 + kstep;
;             PG8_LDB(B0, 0, 0); PG8_LDB(B1, 0, 1); PG8_SCHED; PG8_LDA(At, 0, 0); PG8_STAGE(PG8_SA(1, 1), a1 + hA, voffA);
;             PG8_WAIT_V(8); PG8_WAIT_L(0); PG8_BAR; PG8_MMA(0, 0, At, B0); PG8_MMA(0, 1, At, B1); PG8_BAR; PG8_SCHED;
;             PG8_LDA(At, 0, 1); PG8_STAGE(PG8_SB(0, 0), b2, voffB); PG8_STAGE(PG8_SB(0, 1), b2 + hB, voffB); PG8_STAGE(PG8_SA(0, 0), a2, voffA);
;             PG8_WAIT_V(8); PG8_WAIT_L(0); PG8_BAR; PG8_MMA(1, 0, At, B0); PG8_MMA(1, 1, At, B1); PG8_BAR; PG8_SCHED;
.LBB0_1148:
	ds_read_b128 v[128:131], v184
	ds_read_b128 v[132:135], v184 offset:1024
	ds_read_b128 v[136:139], v184 offset:2048
	ds_read_b128 v[140:143], v184 offset:3072
	ds_read_b128 v[162:165], v185
	ds_read_b128 v[166:169], v185 offset:1024
	ds_read_b128 v[170:173], v185 offset:2048
	ds_read_b128 v[174:177], v185 offset:3072
	s_add_u32 s6, s4, 0xfff80080
	s_addc_u32 s7, s5, -1
	s_cmp_eq_u32 s46, 28
	s_cselect_b32 s55, s74, s7
	s_cselect_b32 s54, s75, s6
	s_cselect_b32 s7, s41, s45
	s_cselect_b32 s6, s76, s44
	v_lshl_add_u64 v[178:179], s[4:5], 0, v[154:155]
	s_add_i32 m0, s58, 0xc000
	ds_read_b128 v[188:191], v186
	ds_read_b128 v[192:195], v186 offset:1024
	ds_read_b128 v[196:199], v186 offset:2048
	ds_read_b128 v[200:203], v186 offset:3072
	ds_read_b128 v[204:207], v186 offset:4096
	ds_read_b128 v[208:211], v186 offset:5120
	ds_read_b128 v[212:215], v186 offset:6144
	ds_read_b128 v[216:219], v186 offset:7168
	global_load_lds_dwordx4 v[178:179], off
	s_add_i32 m0, s58, 0xe000
	v_lshl_add_u64 v[178:179], s[4:5], 0, v[156:157]
	global_load_lds_dwordx4 v[178:179], off
	s_waitcnt vmcnt(8) lgkmcnt(0)
	s_barrier
	v_mfma_f32_16x16x32_bf16 v[124:127], v[128:131], v[188:191], v[124:127]
	v_mfma_f32_16x16x32_bf16 v[116:119], v[136:139], v[188:191], v[116:119]
	v_mfma_f32_16x16x32_bf16 v[108:111], v[128:131], v[196:199], v[108:111]
	v_mfma_f32_16x16x32_bf16 v[100:103], v[136:139], v[196:199], v[100:103]
	v_mfma_f32_16x16x32_bf16 v[92:95], v[128:131], v[204:207], v[92:95]
	v_mfma_f32_16x16x32_bf16 v[84:87], v[136:139], v[204:207], v[84:87]
	v_mfma_f32_16x16x32_bf16 v[76:79], v[128:131], v[212:215], v[76:79]
	v_mfma_f32_16x16x32_bf16 v[68:71], v[136:139], v[212:215], v[68:71]
	v_mfma_f32_16x16x32_bf16 v[124:127], v[132:135], v[192:195], v[124:127]
	v_mfma_f32_16x16x32_bf16 v[116:119], v[140:143], v[192:195], v[116:119]
	v_mfma_f32_16x16x32_bf16 v[108:111], v[132:135], v[200:203], v[108:111]
	v_mfma_f32_16x16x32_bf16 v[100:103], v[140:143], v[200:203], v[100:103]
	v_mfma_f32_16x16x32_bf16 v[92:95], v[132:135], v[208:211], v[92:95]
	v_mfma_f32_16x16x32_bf16 v[84:87], v[140:143], v[208:211], v[84:87]
	v_mfma_f32_16x16x32_bf16 v[76:79], v[132:135], v[216:219], v[76:79]
	v_mfma_f32_16x16x32_bf16 v[68:71], v[140:143], v[216:219], v[68:71]
	v_mfma_f32_16x16x32_bf16 v[120:123], v[162:165], v[188:191], v[120:123]
	v_mfma_f32_16x16x32_bf16 v[112:115], v[170:173], v[188:191], v[112:115]
	v_mfma_f32_16x16x32_bf16 v[104:107], v[162:165], v[196:199], v[104:107]
	v_mfma_f32_16x16x32_bf16 v[96:99], v[170:173], v[196:199], v[96:99]
	v_mfma_f32_16x16x32_bf16 v[88:91], v[162:165], v[204:207], v[88:91]
	v_mfma_f32_16x16x32_bf16 v[80:83], v[170:173], v[204:207], v[80:83]
	v_mfma_f32_16x16x32_bf16 v[72:75], v[162:165], v[212:215], v[72:75]
	v_mfma_f32_16x16x32_bf16 v[64:67], v[170:173], v[212:215], v[64:67]
	v_mfma_f32_16x16x32_bf16 v[120:123], v[166:169], v[192:195], v[120:123]
	v_mfma_f32_16x16x32_bf16 v[112:115], v[174:177], v[192:195], v[112:115]
	v_mfma_f32_16x16x32_bf16 v[104:107], v[166:169], v[200:203], v[104:107]
	v_mfma_f32_16x16x32_bf16 v[96:99], v[174:177], v[200:203], v[96:99]
	v_mfma_f32_16x16x32_bf16 v[88:91], v[166:169], v[208:211], v[88:91]
	v_mfma_f32_16x16x32_bf16 v[80:83], v[174:177], v[208:211], v[80:83]
	v_mfma_f32_16x16x32_bf16 v[72:75], v[166:169], v[216:219], v[72:75]
	v_mfma_f32_16x16x32_bf16 v[64:67], v[174:177], v[216:219], v[64:67]
	s_barrier
	s_add_i32 s18, s66, s39
	v_lshl_add_u64 v[178:179], s[6:7], 0, v[148:149]
	s_mov_b32 m0, s18
	ds_read_b128 v[188:191], v186 offset:16384
	ds_read_b128 v[192:195], v186 offset:17408
	ds_read_b128 v[196:199], v186 offset:18432
	ds_read_b128 v[200:203], v186 offset:19456
	ds_read_b128 v[204:207], v186 offset:20480
	ds_read_b128 v[208:211], v186 offset:21504
	ds_read_b128 v[212:215], v186 offset:22528
	ds_read_b128 v[216:219], v186 offset:23552
	global_load_lds_dwordx4 v[178:179], off
	s_add_i32 m0, s18, 0x2000
	s_add_u32 s18, s6, 0x80000
	v_lshl_add_u64 v[222:223], s[6:7], 0, v[144:145]
	s_addc_u32 s19, s7, 0
	s_add_i32 s33, s67, s39
	global_load_lds_dwordx4 v[222:223], off
	v_lshl_add_u64 v[224:225], s[18:19], 0, v[148:149]
	s_mov_b32 m0, s33
	v_lshl_add_u64 v[226:227], s[54:55], 0, v[146:147]
	global_load_lds_dwordx4 v[224:225], off
	s_add_i32 m0, s33, 0x2000
	v_lshl_add_u64 v[224:225], s[18:19], 0, v[144:145]
	global_load_lds_dwordx4 v[224:225], off
	s_mov_b32 m0, s58
	v_lshl_add_u64 v[224:225], s[54:55], 0, v[150:151]
	global_load_lds_dwordx4 v[224:225], off
	s_mov_b32 m0, s59
	s_nop 0
	global_load_lds_dwordx4 v[226:227], off
	s_waitcnt vmcnt(8) lgkmcnt(0)
	s_barrier
; #define PG8_STAGE(bufoff, gbase, voff) do { _Pragma("unroll") for (int _i = 0; _i < 2; ++_i) \
;         __builtin_amdgcn_global_load_lds((const unsigned*)((const char*)(gbase) + (voff)[_i]), (LAS unsigned*)(lds + (bufoff) + ldsw + _i * 8192), 16, 0, 0); } while (0)
; #define PG8_LDA(dst, b, h) do { _Pragma("unroll") for (int m = 0; m < 4; ++m) _Pragma("unroll") for (int k = 0; k < 2; ++k) dst[m][k] = *(const LAS bf16x8*)(lds + PG8_SA(b, h) + aoff + m * 2048 + k * 1024); } while (0)
; #define PG8_LDB(dst, b, h) do { _Pragma("unroll") for (int n = 0; n < 2; ++n) _Pragma("unroll") for (int k = 0; k < 2; ++k) dst[n][k] = *(const LAS bf16x8*)(lds + PG8_SB(b, h) + boff + n * 2048 + k * 1024); } while (0)
; #define PG8_MMA(ai, bj, At, Bt) do { __builtin_amdgcn_s_setprio(1); _Pragma("unroll") for (int m = 0; m < 4; ++m) _Pragma("unroll") for (int n = 0; n < 2; ++n) _Pragma("unroll") for (int k = 0; k < 2; ++k) \
;         acc[ai][bj][m][n] = __builtin_amdgcn_mfma_f32_16x16x32_bf16(Bt[n][k], At[m][k], acc[ai][bj][m][n], 0, 0, 0); __builtin_amdgcn_s_setprio(0); } while (0)
; #define PG8_WAIT_V(n) asm volatile("s_waitcnt vmcnt(" #n ")" ::: "memory")
; #define PG8_WAIT_L(n) asm volatile("s_waitcnt lgkmcnt(" #n ")" ::: "memory")
; #define PG8_BAR __builtin_amdgcn_s_barrier()
; #define PG8_SCHED __builtin_amdgcn_sched_barrier(0)
; template <class Epi, class Sched, bool ALIGN_EPI>
; __device__ __forceinline__ void gemm_phase(LAS unsigned char* lds, const Gemm g, const Sched& S, const Epi& E) {
;     ...
;             PG8_WAIT_V(8); PG8_WAIT_L(0); PG8_BAR; PG8_MMA(1, 0, At, B0); PG8_MMA(1, 1, At, B1); PG8_BAR; PG8_SCHED;
;             PG8_LDB(B0, 1, 0); PG8_LDB(B1, 1, 1); PG8_SCHED; PG8_LDA(At, 1, 0); PG8_STAGE(PG8_SA(0, 1), a2 + hA, voffA);
;             PG8_WAIT_V(8); PG8_WAIT_L(0); PG8_BAR; PG8_MMA(0, 0, At, B0); PG8_MMA(0, 1, At, B1); PG8_BAR; PG8_SCHED;
;             PG8_LDA(At, 1, 1); PG8_STAGE(PG8_SB(1, 0), b3, voffB); PG8_STAGE(PG8_SB(1, 1), b3 + hB, voffB); PG8_STAGE(PG8_SA(1, 0), a3, voffA);
	v_mfma_f32_16x16x32_bf16 v[60:63], v[128:131], v[188:191], v[60:63]
	v_mfma_f32_16x16x32_bf16 v[52:55], v[136:139], v[188:191], v[52:55]
	v_mfma_f32_16x16x32_bf16 v[44:47], v[128:131], v[196:199], v[44:47]
	v_mfma_f32_16x16x32_bf16 v[36:39], v[136:139], v[196:199], v[36:39]
	v_mfma_f32_16x16x32_bf16 v[28:31], v[128:131], v[204:207], v[28:31]
	v_mfma_f32_16x16x32_bf16 v[20:23], v[136:139], v[204:207], v[20:23]
	v_mfma_f32_16x16x32_bf16 v[12:15], v[128:131], v[212:215], v[12:15]
	v_mfma_f32_16x16x32_bf16 v[4:7], v[136:139], v[212:215], v[4:7]
	v_mfma_f32_16x16x32_bf16 v[60:63], v[132:135], v[192:195], v[60:63]
	v_mfma_f32_16x16x32_bf16 v[52:55], v[140:143], v[192:195], v[52:55]
	v_mfma_f32_16x16x32_bf16 v[44:47], v[132:135], v[200:203], v[44:47]
	v_mfma_f32_16x16x32_bf16 v[36:39], v[140:143], v[200:203], v[36:39]
	v_mfma_f32_16x16x32_bf16 v[28:31], v[132:135], v[208:211], v[28:31]
	v_mfma_f32_16x16x32_bf16 v[20:23], v[140:143], v[208:211], v[20:23]
	v_mfma_f32_16x16x32_bf16 v[12:15], v[132:135], v[216:219], v[12:15]
	v_mfma_f32_16x16x32_bf16 v[4:7], v[140:143], v[216:219], v[4:7]
	v_mfma_f32_16x16x32_bf16 v[56:59], v[162:165], v[188:191], v[56:59]
	v_mfma_f32_16x16x32_bf16 v[48:51], v[170:173], v[188:191], v[48:51]
	v_mfma_f32_16x16x32_bf16 v[40:43], v[162:165], v[196:199], v[40:43]
	v_mfma_f32_16x16x32_bf16 v[32:35], v[170:173], v[196:199], v[32:35]
	v_mfma_f32_16x16x32_bf16 v[24:27], v[162:165], v[204:207], v[24:27]
	v_mfma_f32_16x16x32_bf16 v[16:19], v[170:173], v[204:207], v[16:19]
	v_mfma_f32_16x16x32_bf16 v[8:11], v[162:165], v[212:215], v[8:11]
	v_mfma_f32_16x16x32_bf16 v[0:3], v[170:173], v[212:215], v[0:3]
	v_mfma_f32_16x16x32_bf16 v[56:59], v[166:169], v[192:195], v[56:59]
	v_mfma_f32_16x16x32_bf16 v[48:51], v[174:177], v[192:195], v[48:51]
	v_mfma_f32_16x16x32_bf16 v[40:43], v[166:169], v[200:203], v[40:43]
	v_mfma_f32_16x16x32_bf16 v[32:35], v[174:177], v[200:203], v[32:35]
	v_mfma_f32_16x16x32_bf16 v[24:27], v[166:169], v[208:211], v[24:27]
	v_mfma_f32_16x16x32_bf16 v[16:19], v[174:177], v[208:211], v[16:19]
	v_mfma_f32_16x16x32_bf16 v[8:11], v[166:169], v[216:219], v[8:11]
	v_mfma_f32_16x16x32_bf16 v[0:3], v[174:177], v[216:219], v[0:3]
	s_barrier
	s_add_i32 s33, 0, 0x18000
	s_add_i32 s47, 0, 0x1c000
	v_add_u32_e32 v140, s33, v182
	v_add_u32_e32 v174, s47, v182
	ds_read_b128 v[128:131], v140
	ds_read_b128 v[132:135], v140 offset:1024
	ds_read_b128 v[136:139], v140 offset:2048
	ds_read_b128 v[140:143], v140 offset:3072
	ds_read_b128 v[162:165], v174
	ds_read_b128 v[166:169], v174 offset:1024
	ds_read_b128 v[170:173], v174 offset:2048
	ds_read_b128 v[174:177], v174 offset:3072
	s_add_u32 s18, s54, 0x80000
	s_addc_u32 s19, s55, 0
	s_mov_b32 m0, s60
	v_lshl_add_u64 v[228:229], s[18:19], 0, v[150:151]
	ds_read_b128 v[188:191], v186 offset:32768
	ds_read_b128 v[192:195], v186 offset:33792
	ds_read_b128 v[196:199], v186 offset:34816
	ds_read_b128 v[200:203], v186 offset:35840
	ds_read_b128 v[204:207], v186 offset:36864
	ds_read_b128 v[208:211], v186 offset:37888
	ds_read_b128 v[212:215], v186 offset:38912
	ds_read_b128 v[216:219], v186 offset:39936
	global_load_lds_dwordx4 v[228:229], off
	s_mov_b32 m0, s61
	v_lshl_add_u64 v[228:229], s[18:19], 0, v[146:147]
	global_load_lds_dwordx4 v[228:229], off
	s_waitcnt vmcnt(8) lgkmcnt(0)
	s_barrier
	v_mfma_f32_16x16x32_bf16 v[124:127], v[128:131], v[188:191], v[124:127]
	v_mfma_f32_16x16x32_bf16 v[116:119], v[136:139], v[188:191], v[116:119]
	v_mfma_f32_16x16x32_bf16 v[108:111], v[128:131], v[196:199], v[108:111]
	v_mfma_f32_16x16x32_bf16 v[100:103], v[136:139], v[196:199], v[100:103]
	v_mfma_f32_16x16x32_bf16 v[92:95], v[128:131], v[204:207], v[92:95]
	v_mfma_f32_16x16x32_bf16 v[84:87], v[136:139], v[204:207], v[84:87]
	v_mfma_f32_16x16x32_bf16 v[76:79], v[128:131], v[212:215], v[76:79]
	v_mfma_f32_16x16x32_bf16 v[68:71], v[136:139], v[212:215], v[68:71]
	v_mfma_f32_16x16x32_bf16 v[124:127], v[132:135], v[192:195], v[124:127]
	v_mfma_f32_16x16x32_bf16 v[116:119], v[140:143], v[192:195], v[116:119]
	v_mfma_f32_16x16x32_bf16 v[108:111], v[132:135], v[200:203], v[108:111]
	v_mfma_f32_16x16x32_bf16 v[100:103], v[140:143], v[200:203], v[100:103]
	v_mfma_f32_16x16x32_bf16 v[92:95], v[132:135], v[208:211], v[92:95]
	v_mfma_f32_16x16x32_bf16 v[84:87], v[140:143], v[208:211], v[84:87]
	v_mfma_f32_16x16x32_bf16 v[76:79], v[132:135], v[216:219], v[76:79]
	v_mfma_f32_16x16x32_bf16 v[68:71], v[140:143], v[216:219], v[68:71]
	v_mfma_f32_16x16x32_bf16 v[120:123], v[162:165], v[188:191], v[120:123]
	v_mfma_f32_16x16x32_bf16 v[112:115], v[170:173], v[188:191], v[112:115]
	v_mfma_f32_16x16x32_bf16 v[104:107], v[162:165], v[196:199], v[104:107]
	v_mfma_f32_16x16x32_bf16 v[96:99], v[170:173], v[196:199], v[96:99]
	v_mfma_f32_16x16x32_bf16 v[88:91], v[162:165], v[204:207], v[88:91]
	v_mfma_f32_16x16x32_bf16 v[80:83], v[170:173], v[204:207], v[80:83]
	v_mfma_f32_16x16x32_bf16 v[72:75], v[162:165], v[212:215], v[72:75]
	v_mfma_f32_16x16x32_bf16 v[64:67], v[170:173], v[212:215], v[64:67]
	v_mfma_f32_16x16x32_bf16 v[120:123], v[166:169], v[192:195], v[120:123]
	v_mfma_f32_16x16x32_bf16 v[112:115], v[174:177], v[192:195], v[112:115]
	v_mfma_f32_16x16x32_bf16 v[104:107], v[166:169], v[200:203], v[104:107]
	v_mfma_f32_16x16x32_bf16 v[96:99], v[174:177], v[200:203], v[96:99]
	v_mfma_f32_16x16x32_bf16 v[88:91], v[166:169], v[208:211], v[88:91]
	v_mfma_f32_16x16x32_bf16 v[80:83], v[174:177], v[208:211], v[80:83]
	v_mfma_f32_16x16x32_bf16 v[72:75], v[166:169], v[216:219], v[72:75]
	v_mfma_f32_16x16x32_bf16 v[64:67], v[174:177], v[216:219], v[64:67]
	s_barrier
; #define PG8_STAGE(bufoff, gbase, voff) do { _Pragma("unroll") for (int _i = 0; _i < 2; ++_i) \
;         __builtin_amdgcn_global_load_lds((const unsigned*)((const char*)(gbase) + (voff)[_i]), (LAS unsigned*)(lds + (bufoff) + ldsw + _i * 8192), 16, 0, 0); } while (0)
; #define PG8_LDA(dst, b, h) do { _Pragma("unroll") for (int m = 0; m < 4; ++m) _Pragma("unroll") for (int k = 0; k < 2; ++k) dst[m][k] = *(const LAS bf16x8*)(lds + PG8_SA(b, h) + aoff + m * 2048 + k * 1024); } while (0)
; #define PG8_MMA(ai, bj, At, Bt) do { __builtin_amdgcn_s_setprio(1); _Pragma("unroll") for (int m = 0; m < 4; ++m) _Pragma("unroll") for (int n = 0; n < 2; ++n) _Pragma("unroll") for (int k = 0; k < 2; ++k) \
;         acc[ai][bj][m][n] = __builtin_amdgcn_mfma_f32_16x16x32_bf16(Bt[n][k], At[m][k], acc[ai][bj][m][n], 0, 0, 0); __builtin_amdgcn_s_setprio(0); } while (0)
; #define PG8_WAIT_V(n) asm volatile("s_waitcnt vmcnt(" #n ")" ::: "memory")
; #define PG8_WAIT_L(n) asm volatile("s_waitcnt lgkmcnt(" #n ")" ::: "memory")
; #define PG8_BAR __builtin_amdgcn_s_barrier()
; #define PG8_SCHED __builtin_amdgcn_sched_barrier(0)
; template <class Epi, class Sched, bool ALIGN_EPI>
; __device__ __forceinline__ void gemm_phase(LAS unsigned char* lds, const Gemm g, const Sched& S, const Epi& E) {
;     ...
;             PG8_LDA(At, 1, 1); PG8_STAGE(PG8_SB(1, 0), b3, voffB); PG8_STAGE(PG8_SB(1, 1), b3 + hB, voffB); PG8_STAGE(PG8_SA(1, 0), a3, voffA);
;             PG8_WAIT_V(8); PG8_WAIT_L(0); PG8_BAR; PG8_MMA(1, 0, At, B0); PG8_MMA(1, 1, At, B1); PG8_BAR; PG8_SCHED;
;         }
	s_add_i32 s18, s33, s39
	v_lshl_add_u64 v[178:179], v[178:179], 0, s[26:27]
	s_mov_b32 m0, s18
	ds_read_b128 v[188:191], v186 offset:49152
	ds_read_b128 v[192:195], v186 offset:50176
	ds_read_b128 v[196:199], v186 offset:51200
	ds_read_b128 v[200:203], v186 offset:52224
	ds_read_b128 v[204:207], v186 offset:53248
	ds_read_b128 v[208:211], v186 offset:54272
	ds_read_b128 v[212:215], v186 offset:55296
	ds_read_b128 v[216:219], v186 offset:56320
	global_load_lds_dwordx4 v[178:179], off
	s_add_i32 m0, s18, 0x2000
	s_add_u32 s6, s6, 0x80080
	v_lshl_add_u64 v[178:179], v[222:223], 0, s[26:27]
	s_addc_u32 s7, s7, 0
	s_add_i32 s18, s47, s39
	global_load_lds_dwordx4 v[178:179], off
	s_mov_b32 m0, s18
	v_lshl_add_u64 v[178:179], s[6:7], 0, v[148:149]
	global_load_lds_dwordx4 v[178:179], off
	s_add_i32 m0, s18, 0x2000
	v_lshl_add_u64 v[178:179], s[6:7], 0, v[144:145]
	global_load_lds_dwordx4 v[178:179], off
	s_mov_b32 m0, s62
	v_lshl_add_u64 v[178:179], v[224:225], 0, s[26:27]
	global_load_lds_dwordx4 v[178:179], off
	s_mov_b32 m0, s63
	v_lshl_add_u64 v[178:179], v[226:227], 0, s[26:27]
	global_load_lds_dwordx4 v[178:179], off
	s_waitcnt vmcnt(8) lgkmcnt(0)
	s_barrier
	v_mfma_f32_16x16x32_bf16 v[60:63], v[128:131], v[188:191], v[60:63]
	v_mfma_f32_16x16x32_bf16 v[52:55], v[136:139], v[188:191], v[52:55]
	v_mfma_f32_16x16x32_bf16 v[44:47], v[128:131], v[196:199], v[44:47]
	v_mfma_f32_16x16x32_bf16 v[36:39], v[136:139], v[196:199], v[36:39]
	v_mfma_f32_16x16x32_bf16 v[28:31], v[128:131], v[204:207], v[28:31]
	v_mfma_f32_16x16x32_bf16 v[20:23], v[136:139], v[204:207], v[20:23]
	v_mfma_f32_16x16x32_bf16 v[12:15], v[128:131], v[212:215], v[12:15]
	v_mfma_f32_16x16x32_bf16 v[4:7], v[136:139], v[212:215], v[4:7]
	v_mfma_f32_16x16x32_bf16 v[60:63], v[132:135], v[192:195], v[60:63]
	v_mfma_f32_16x16x32_bf16 v[52:55], v[140:143], v[192:195], v[52:55]
	v_mfma_f32_16x16x32_bf16 v[44:47], v[132:135], v[200:203], v[44:47]
	v_mfma_f32_16x16x32_bf16 v[36:39], v[140:143], v[200:203], v[36:39]
	v_mfma_f32_16x16x32_bf16 v[28:31], v[132:135], v[208:211], v[28:31]
	v_mfma_f32_16x16x32_bf16 v[20:23], v[140:143], v[208:211], v[20:23]
	v_mfma_f32_16x16x32_bf16 v[12:15], v[132:135], v[216:219], v[12:15]
	v_mfma_f32_16x16x32_bf16 v[4:7], v[140:143], v[216:219], v[4:7]
	v_mfma_f32_16x16x32_bf16 v[56:59], v[162:165], v[188:191], v[56:59]
	v_mfma_f32_16x16x32_bf16 v[48:51], v[170:173], v[188:191], v[48:51]
	v_mfma_f32_16x16x32_bf16 v[40:43], v[162:165], v[196:199], v[40:43]
	v_mfma_f32_16x16x32_bf16 v[32:35], v[170:173], v[196:199], v[32:35]
	v_mfma_f32_16x16x32_bf16 v[24:27], v[162:165], v[204:207], v[24:27]
	v_mfma_f32_16x16x32_bf16 v[16:19], v[170:173], v[204:207], v[16:19]
	v_mfma_f32_16x16x32_bf16 v[8:11], v[162:165], v[212:215], v[8:11]
	v_mfma_f32_16x16x32_bf16 v[0:3], v[170:173], v[212:215], v[0:3]
	v_mfma_f32_16x16x32_bf16 v[56:59], v[166:169], v[192:195], v[56:59]
	v_mfma_f32_16x16x32_bf16 v[48:51], v[174:177], v[192:195], v[48:51]
	v_mfma_f32_16x16x32_bf16 v[40:43], v[166:169], v[200:203], v[40:43]
	v_mfma_f32_16x16x32_bf16 v[32:35], v[174:177], v[200:203], v[32:35]
	v_mfma_f32_16x16x32_bf16 v[24:27], v[166:169], v[208:211], v[24:27]
	v_mfma_f32_16x16x32_bf16 v[16:19], v[174:177], v[208:211], v[16:19]
	v_mfma_f32_16x16x32_bf16 v[8:11], v[166:169], v[216:219], v[8:11]
	v_mfma_f32_16x16x32_bf16 v[0:3], v[174:177], v[216:219], v[0:3]
	s_barrier
	s_add_i32 s46, s46, 2
	s_add_u32 s4, s4, 0x100
	s_addc_u32 s5, s5, 0
	s_add_u32 s44, s44, 0x100
	s_addc_u32 s45, s45, 0
	s_cmp_gt_u32 s46, 29
	s_cbranch_scc0 .LBB0_1148
	s_and_b64 vcc, exec, s[30:31]
	s_cbranch_vccz .LBB0_1151
	s_barrier

; #define PG8_STAGE(bufoff, gbase, voff) do { _Pragma("unroll") for (int _i = 0; _i < 2; ++_i) \
;         __builtin_amdgcn_global_load_lds((const unsigned*)((const char*)(gbase) + (voff)[_i]), (LAS unsigned*)(lds + (bufoff) + ldsw + _i * 8192), 16, 0, 0); } while (0)
; #define PG8_LDA(dst, b, h) do { _Pragma("unroll") for (int m = 0; m < 4; ++m) _Pragma("unroll") for (int k = 0; k < 2; ++k) dst[m][k] = *(const LAS bf16x8*)(lds + PG8_SA(b, h) + aoff + m * 2048 + k * 1024); } while (0)
; #define PG8_LDB(dst, b, h) do { _Pragma("unroll") for (int n = 0; n < 2; ++n) _Pragma("unroll") for (int k = 0; k < 2; ++k) dst[n][k] = *(const LAS bf16x8*)(lds + PG8_SB(b, h) + boff + n * 2048 + k * 1024); } while (0)
; #define PG8_MMA(ai, bj, At, Bt) do { __builtin_amdgcn_s_setprio(1); _Pragma("unroll") for (int m = 0; m < 4; ++m) _Pragma("unroll") for (int n = 0; n < 2; ++n) _Pragma("unroll") for (int k = 0; k < 2; ++k) \
;         acc[ai][bj][m][n] = __builtin_amdgcn_mfma_f32_16x16x32_bf16(Bt[n][k], At[m][k], acc[ai][bj][m][n], 0, 0, 0); __builtin_amdgcn_s_setprio(0); } while (0)
; #define PG8_WAIT_V(n) asm volatile("s_waitcnt vmcnt(" #n ")" ::: "memory")
; #define PG8_WAIT_L(n) asm volatile("s_waitcnt lgkmcnt(" #n ")" ::: "memory")
; #define PG8_BAR __builtin_amdgcn_s_barrier()
; #define PG8_SCHED __builtin_amdgcn_sched_barrier(0)
; template <class Epi, class Sched, bool ALIGN_EPI>
; __device__ __forceinline__ void gemm_phase(LAS unsigned char* lds, const Gemm g, const Sched& S, const Epi& E) {
;     ...
;         for (int t = 0; t < nt; t += 2) {
;             const bool last = (t == nt - 2);
;             const char* a1 = cA + (size_t)(t + 1) * kstep;
;             const char* a2 = last ? nA : cA + (size_t)(t + 2) * kstep; const char* b2 = last ? nB : cB + (size_t)(t + 2) * kstep;
;             const char* a3 = a2 + kstep; const char* b3 = b2 + kstep;
;             PG8_LDB(B0, 0, 0); PG8_LDB(B1, 0, 1); PG8_SCHED; PG8_LDA(At, 0, 0); PG8_STAGE(PG8_SA(1, 1), a1 + hA, voffA);
;             PG8_WAIT_V(8); PG8_WAIT_L(0); PG8_BAR; PG8_MMA(0, 0, At, B0); PG8_MMA(0, 1, At, B1); PG8_BAR; PG8_SCHED;
;             PG8_LDA(At, 0, 1); PG8_STAGE(PG8_SB(0, 0), b2, voffB); PG8_STAGE(PG8_SB(0, 1), b2 + hB, voffB); PG8_STAGE(PG8_SA(0, 0), a2, voffA);
;             PG8_WAIT_V(8); PG8_WAIT_L(0); PG8_BAR; PG8_MMA(1, 0, At, B0); PG8_MMA(1, 1, At, B1); PG8_BAR; PG8_SCHED;
.LBB0_1234:
	ds_read_b128 v[144:147], v151
	ds_read_b128 v[156:159], v151 offset:1024
	ds_read_b128 v[160:163], v151 offset:2048
	ds_read_b128 v[164:167], v151 offset:3072
	ds_read_b128 v[168:171], v152
	ds_read_b128 v[172:175], v152 offset:1024
	ds_read_b128 v[176:179], v152 offset:2048
	ds_read_b128 v[180:183], v152 offset:3072
	s_add_u32 s18, s38, 0xffea0080
	s_addc_u32 s19, s39, -1
	s_cmpk_eq_i32 s46, 0x54
	s_cselect_b32 s43, s70, s19
	s_cselect_b32 s42, s71, s18
	s_cselect_b32 s41, s27, s45
	s_cselect_b32 s40, s72, s44
	v_lshl_add_u64 v[216:217], s[38:39], 0, v[136:137]
	s_add_i32 m0, s55, 0xc000
	ds_read_b128 v[184:187], v153
	ds_read_b128 v[188:191], v153 offset:1024
	ds_read_b128 v[192:195], v153 offset:2048
	ds_read_b128 v[196:199], v153 offset:3072
	ds_read_b128 v[200:203], v153 offset:4096
	ds_read_b128 v[204:207], v153 offset:5120
	ds_read_b128 v[208:211], v153 offset:6144
	ds_read_b128 v[212:215], v153 offset:7168
	global_load_lds_dwordx4 v[216:217], off
	s_add_i32 m0, s55, 0xe000
	v_lshl_add_u64 v[216:217], s[38:39], 0, v[138:139]
	global_load_lds_dwordx4 v[216:217], off
	s_waitcnt vmcnt(8) lgkmcnt(0)
	s_barrier
	v_mfma_f32_16x16x32_bf16 v[124:127], v[144:147], v[184:187], v[124:127]
	v_mfma_f32_16x16x32_bf16 v[120:123], v[160:163], v[184:187], v[120:123]
	v_mfma_f32_16x16x32_bf16 v[108:111], v[144:147], v[192:195], v[108:111]
	v_mfma_f32_16x16x32_bf16 v[104:107], v[160:163], v[192:195], v[104:107]
	v_mfma_f32_16x16x32_bf16 v[92:95], v[144:147], v[200:203], v[92:95]
	v_mfma_f32_16x16x32_bf16 v[88:91], v[160:163], v[200:203], v[88:91]
	v_mfma_f32_16x16x32_bf16 v[76:79], v[144:147], v[208:211], v[76:79]
	v_mfma_f32_16x16x32_bf16 v[72:75], v[160:163], v[208:211], v[72:75]
	v_mfma_f32_16x16x32_bf16 v[124:127], v[156:159], v[188:191], v[124:127]
	v_mfma_f32_16x16x32_bf16 v[120:123], v[164:167], v[188:191], v[120:123]
	v_mfma_f32_16x16x32_bf16 v[108:111], v[156:159], v[196:199], v[108:111]
	v_mfma_f32_16x16x32_bf16 v[104:107], v[164:167], v[196:199], v[104:107]
	v_mfma_f32_16x16x32_bf16 v[92:95], v[156:159], v[204:207], v[92:95]
	v_mfma_f32_16x16x32_bf16 v[88:91], v[164:167], v[204:207], v[88:91]
	v_mfma_f32_16x16x32_bf16 v[76:79], v[156:159], v[212:215], v[76:79]
	v_mfma_f32_16x16x32_bf16 v[72:75], v[164:167], v[212:215], v[72:75]
	v_mfma_f32_16x16x32_bf16 v[116:119], v[168:171], v[184:187], v[116:119]
	v_mfma_f32_16x16x32_bf16 v[112:115], v[176:179], v[184:187], v[112:115]
	v_mfma_f32_16x16x32_bf16 v[100:103], v[168:171], v[192:195], v[100:103]
	v_mfma_f32_16x16x32_bf16 v[96:99], v[176:179], v[192:195], v[96:99]
	v_mfma_f32_16x16x32_bf16 v[84:87], v[168:171], v[200:203], v[84:87]
	v_mfma_f32_16x16x32_bf16 v[80:83], v[176:179], v[200:203], v[80:83]
	v_mfma_f32_16x16x32_bf16 v[68:71], v[168:171], v[208:211], v[68:71]
	v_mfma_f32_16x16x32_bf16 v[64:67], v[176:179], v[208:211], v[64:67]
	v_mfma_f32_16x16x32_bf16 v[116:119], v[172:175], v[188:191], v[116:119]
	v_mfma_f32_16x16x32_bf16 v[112:115], v[180:183], v[188:191], v[112:115]
	v_mfma_f32_16x16x32_bf16 v[100:103], v[172:175], v[196:199], v[100:103]
	v_mfma_f32_16x16x32_bf16 v[96:99], v[180:183], v[196:199], v[96:99]
	v_mfma_f32_16x16x32_bf16 v[84:87], v[172:175], v[204:207], v[84:87]
	v_mfma_f32_16x16x32_bf16 v[80:83], v[180:183], v[204:207], v[80:83]
	v_mfma_f32_16x16x32_bf16 v[68:71], v[172:175], v[212:215], v[68:71]
	v_mfma_f32_16x16x32_bf16 v[64:67], v[180:183], v[212:215], v[64:67]
	s_barrier
	s_add_i32 s18, s65, s54
	v_lshl_add_u64 v[216:217], s[40:41], 0, v[130:131]
	s_mov_b32 m0, s18
	ds_read_b128 v[184:187], v153 offset:16384
	ds_read_b128 v[188:191], v153 offset:17408
	ds_read_b128 v[192:195], v153 offset:18432
	ds_read_b128 v[196:199], v153 offset:19456
	ds_read_b128 v[200:203], v153 offset:20480
	ds_read_b128 v[204:207], v153 offset:21504
	ds_read_b128 v[208:211], v153 offset:22528
	ds_read_b128 v[212:215], v153 offset:23552
	global_load_lds_dwordx4 v[216:217], off
	s_add_i32 m0, s18, 0x2000
	s_add_u32 s18, s40, 0x160000
	v_lshl_add_u64 v[218:219], s[40:41], 0, v[134:135]
	s_addc_u32 s19, s41, 0
	s_add_i32 s33, s66, s54
	global_load_lds_dwordx4 v[218:219], off
	v_lshl_add_u64 v[222:223], s[18:19], 0, v[130:131]
	s_mov_b32 m0, s33
	v_lshl_add_u64 v[224:225], s[42:43], 0, v[132:133]
	global_load_lds_dwordx4 v[222:223], off
	s_add_i32 m0, s33, 0x2000
	v_lshl_add_u64 v[222:223], s[18:19], 0, v[134:135]
	global_load_lds_dwordx4 v[222:223], off
	s_mov_b32 m0, s55
	v_lshl_add_u64 v[222:223], s[42:43], 0, v[128:129]
	global_load_lds_dwordx4 v[222:223], off
	s_mov_b32 m0, s56
	s_nop 0
	global_load_lds_dwordx4 v[224:225], off
	s_waitcnt vmcnt(8) lgkmcnt(0)
	s_barrier
; #define PG8_STAGE(bufoff, gbase, voff) do { _Pragma("unroll") for (int _i = 0; _i < 2; ++_i) \
;         __builtin_amdgcn_global_load_lds((const unsigned*)((const char*)(gbase) + (voff)[_i]), (LAS unsigned*)(lds + (bufoff) + ldsw + _i * 8192), 16, 0, 0); } while (0)
; #define PG8_LDA(dst, b, h) do { _Pragma("unroll") for (int m = 0; m < 4; ++m) _Pragma("unroll") for (int k = 0; k < 2; ++k) dst[m][k] = *(const LAS bf16x8*)(lds + PG8_SA(b, h) + aoff + m * 2048 + k * 1024); } while (0)
; #define PG8_LDB(dst, b, h) do { _Pragma("unroll") for (int n = 0; n < 2; ++n) _Pragma("unroll") for (int k = 0; k < 2; ++k) dst[n][k] = *(const LAS bf16x8*)(lds + PG8_SB(b, h) + boff + n * 2048 + k * 1024); } while (0)
; #define PG8_MMA(ai, bj, At, Bt) do { __builtin_amdgcn_s_setprio(1); _Pragma("unroll") for (int m = 0; m < 4; ++m) _Pragma("unroll") for (int n = 0; n < 2; ++n) _Pragma("unroll") for (int k = 0; k < 2; ++k) \
;         acc[ai][bj][m][n] = __builtin_amdgcn_mfma_f32_16x16x32_bf16(Bt[n][k], At[m][k], acc[ai][bj][m][n], 0, 0, 0); __builtin_amdgcn_s_setprio(0); } while (0)
; #define PG8_WAIT_V(n) asm volatile("s_waitcnt vmcnt(" #n ")" ::: "memory")
; #define PG8_WAIT_L(n) asm volatile("s_waitcnt lgkmcnt(" #n ")" ::: "memory")
; #define PG8_BAR __builtin_amdgcn_s_barrier()
; #define PG8_SCHED __builtin_amdgcn_sched_barrier(0)
; template <class Epi, class Sched, bool ALIGN_EPI>
; __device__ __forceinline__ void gemm_phase(LAS unsigned char* lds, const Gemm g, const Sched& S, const Epi& E) {
;     ...
;             PG8_WAIT_V(8); PG8_WAIT_L(0); PG8_BAR; PG8_MMA(1, 0, At, B0); PG8_MMA(1, 1, At, B1); PG8_BAR; PG8_SCHED;
;             PG8_LDB(B0, 1, 0); PG8_LDB(B1, 1, 1); PG8_SCHED; PG8_LDA(At, 1, 0); PG8_STAGE(PG8_SA(0, 1), a2 + hA, voffA);
;             PG8_WAIT_V(8); PG8_WAIT_L(0); PG8_BAR; PG8_MMA(0, 0, At, B0); PG8_MMA(0, 1, At, B1); PG8_BAR; PG8_SCHED;
;             PG8_LDA(At, 1, 1); PG8_STAGE(PG8_SB(1, 0), b3, voffB); PG8_STAGE(PG8_SB(1, 1), b3 + hB, voffB); PG8_STAGE(PG8_SA(1, 0), a3, voffA);
	v_mfma_f32_16x16x32_bf16 v[60:63], v[144:147], v[184:187], v[60:63]
	v_mfma_f32_16x16x32_bf16 v[56:59], v[160:163], v[184:187], v[56:59]
	v_mfma_f32_16x16x32_bf16 v[44:47], v[144:147], v[192:195], v[44:47]
	v_mfma_f32_16x16x32_bf16 v[40:43], v[160:163], v[192:195], v[40:43]
	v_mfma_f32_16x16x32_bf16 v[28:31], v[144:147], v[200:203], v[28:31]
	v_mfma_f32_16x16x32_bf16 v[24:27], v[160:163], v[200:203], v[24:27]
	v_mfma_f32_16x16x32_bf16 v[12:15], v[144:147], v[208:211], v[12:15]
	v_mfma_f32_16x16x32_bf16 v[8:11], v[160:163], v[208:211], v[8:11]
	v_mfma_f32_16x16x32_bf16 v[60:63], v[156:159], v[188:191], v[60:63]
	v_mfma_f32_16x16x32_bf16 v[56:59], v[164:167], v[188:191], v[56:59]
	v_mfma_f32_16x16x32_bf16 v[44:47], v[156:159], v[196:199], v[44:47]
	v_mfma_f32_16x16x32_bf16 v[40:43], v[164:167], v[196:199], v[40:43]
	v_mfma_f32_16x16x32_bf16 v[28:31], v[156:159], v[204:207], v[28:31]
	v_mfma_f32_16x16x32_bf16 v[24:27], v[164:167], v[204:207], v[24:27]
	v_mfma_f32_16x16x32_bf16 v[12:15], v[156:159], v[212:215], v[12:15]
	v_mfma_f32_16x16x32_bf16 v[8:11], v[164:167], v[212:215], v[8:11]
	v_mfma_f32_16x16x32_bf16 v[52:55], v[168:171], v[184:187], v[52:55]
	v_mfma_f32_16x16x32_bf16 v[48:51], v[176:179], v[184:187], v[48:51]
	v_mfma_f32_16x16x32_bf16 v[36:39], v[168:171], v[192:195], v[36:39]
	v_mfma_f32_16x16x32_bf16 v[32:35], v[176:179], v[192:195], v[32:35]
	v_mfma_f32_16x16x32_bf16 v[20:23], v[168:171], v[200:203], v[20:23]
	v_mfma_f32_16x16x32_bf16 v[16:19], v[176:179], v[200:203], v[16:19]
	v_mfma_f32_16x16x32_bf16 v[4:7], v[168:171], v[208:211], v[4:7]
	v_mfma_f32_16x16x32_bf16 v[0:3], v[176:179], v[208:211], v[0:3]
	v_mfma_f32_16x16x32_bf16 v[52:55], v[172:175], v[188:191], v[52:55]
	v_mfma_f32_16x16x32_bf16 v[48:51], v[180:183], v[188:191], v[48:51]
	v_mfma_f32_16x16x32_bf16 v[36:39], v[172:175], v[196:199], v[36:39]
	v_mfma_f32_16x16x32_bf16 v[32:35], v[180:183], v[196:199], v[32:35]
	v_mfma_f32_16x16x32_bf16 v[20:23], v[172:175], v[204:207], v[20:23]
	v_mfma_f32_16x16x32_bf16 v[16:19], v[180:183], v[204:207], v[16:19]
	v_mfma_f32_16x16x32_bf16 v[4:7], v[172:175], v[212:215], v[4:7]
	v_mfma_f32_16x16x32_bf16 v[0:3], v[180:183], v[212:215], v[0:3]
	s_barrier
	s_add_i32 s33, 0, 0x18000
	v_add_u32_e32 v155, s33, v149
	s_add_i32 s47, 0, 0x1c000
	ds_read_b128 v[144:147], v155
	ds_read_b128 v[156:159], v155 offset:1024
	ds_read_b128 v[160:163], v155 offset:2048
	ds_read_b128 v[164:167], v155 offset:3072
	v_add_u32_e32 v155, s47, v149
	ds_read_b128 v[168:171], v155
	ds_read_b128 v[172:175], v155 offset:1024
	ds_read_b128 v[176:179], v155 offset:2048
	ds_read_b128 v[180:183], v155 offset:3072
	s_add_u32 s18, s42, 0x160000
	s_addc_u32 s19, s43, 0
	s_mov_b32 m0, s57
	v_lshl_add_u64 v[226:227], s[18:19], 0, v[128:129]
	ds_read_b128 v[184:187], v153 offset:32768
	ds_read_b128 v[188:191], v153 offset:33792
	ds_read_b128 v[192:195], v153 offset:34816
	ds_read_b128 v[196:199], v153 offset:35840
	ds_read_b128 v[200:203], v153 offset:36864
	ds_read_b128 v[204:207], v153 offset:37888
	ds_read_b128 v[208:211], v153 offset:38912
	ds_read_b128 v[212:215], v153 offset:39936
	global_load_lds_dwordx4 v[226:227], off
	s_mov_b32 m0, s58
	v_lshl_add_u64 v[226:227], s[18:19], 0, v[132:133]
	global_load_lds_dwordx4 v[226:227], off
	s_waitcnt vmcnt(8) lgkmcnt(0)
	s_barrier
	v_mfma_f32_16x16x32_bf16 v[124:127], v[144:147], v[184:187], v[124:127]
	v_mfma_f32_16x16x32_bf16 v[120:123], v[160:163], v[184:187], v[120:123]
	v_mfma_f32_16x16x32_bf16 v[108:111], v[144:147], v[192:195], v[108:111]
	v_mfma_f32_16x16x32_bf16 v[104:107], v[160:163], v[192:195], v[104:107]
	v_mfma_f32_16x16x32_bf16 v[92:95], v[144:147], v[200:203], v[92:95]
	v_mfma_f32_16x16x32_bf16 v[88:91], v[160:163], v[200:203], v[88:91]
	v_mfma_f32_16x16x32_bf16 v[76:79], v[144:147], v[208:211], v[76:79]
	v_mfma_f32_16x16x32_bf16 v[72:75], v[160:163], v[208:211], v[72:75]
	v_mfma_f32_16x16x32_bf16 v[124:127], v[156:159], v[188:191], v[124:127]
	v_mfma_f32_16x16x32_bf16 v[120:123], v[164:167], v[188:191], v[120:123]
	v_mfma_f32_16x16x32_bf16 v[108:111], v[156:159], v[196:199], v[108:111]
	v_mfma_f32_16x16x32_bf16 v[104:107], v[164:167], v[196:199], v[104:107]
	v_mfma_f32_16x16x32_bf16 v[92:95], v[156:159], v[204:207], v[92:95]
	v_mfma_f32_16x16x32_bf16 v[88:91], v[164:167], v[204:207], v[88:91]
	v_mfma_f32_16x16x32_bf16 v[76:79], v[156:159], v[212:215], v[76:79]
	v_mfma_f32_16x16x32_bf16 v[72:75], v[164:167], v[212:215], v[72:75]
	v_mfma_f32_16x16x32_bf16 v[116:119], v[168:171], v[184:187], v[116:119]
	v_mfma_f32_16x16x32_bf16 v[112:115], v[176:179], v[184:187], v[112:115]
	v_mfma_f32_16x16x32_bf16 v[100:103], v[168:171], v[192:195], v[100:103]
	v_mfma_f32_16x16x32_bf16 v[96:99], v[176:179], v[192:195], v[96:99]
	v_mfma_f32_16x16x32_bf16 v[84:87], v[168:171], v[200:203], v[84:87]
	v_mfma_f32_16x16x32_bf16 v[80:83], v[176:179], v[200:203], v[80:83]
	v_mfma_f32_16x16x32_bf16 v[68:71], v[168:171], v[208:211], v[68:71]
	v_mfma_f32_16x16x32_bf16 v[64:67], v[176:179], v[208:211], v[64:67]
	v_mfma_f32_16x16x32_bf16 v[116:119], v[172:175], v[188:191], v[116:119]
	v_mfma_f32_16x16x32_bf16 v[112:115], v[180:183], v[188:191], v[112:115]
	v_mfma_f32_16x16x32_bf16 v[100:103], v[172:175], v[196:199], v[100:103]
	v_mfma_f32_16x16x32_bf16 v[96:99], v[180:183], v[196:199], v[96:99]
	v_mfma_f32_16x16x32_bf16 v[84:87], v[172:175], v[204:207], v[84:87]
	v_mfma_f32_16x16x32_bf16 v[80:83], v[180:183], v[204:207], v[80:83]
	v_mfma_f32_16x16x32_bf16 v[68:71], v[172:175], v[212:215], v[68:71]
	v_mfma_f32_16x16x32_bf16 v[64:67], v[180:183], v[212:215], v[64:67]
	s_barrier
; #define PG8_STAGE(bufoff, gbase, voff) do { _Pragma("unroll") for (int _i = 0; _i < 2; ++_i) \
;         __builtin_amdgcn_global_load_lds((const unsigned*)((const char*)(gbase) + (voff)[_i]), (LAS unsigned*)(lds + (bufoff) + ldsw + _i * 8192), 16, 0, 0); } while (0)
; #define PG8_LDA(dst, b, h) do { _Pragma("unroll") for (int m = 0; m < 4; ++m) _Pragma("unroll") for (int k = 0; k < 2; ++k) dst[m][k] = *(const LAS bf16x8*)(lds + PG8_SA(b, h) + aoff + m * 2048 + k * 1024); } while (0)
; #define PG8_MMA(ai, bj, At, Bt) do { __builtin_amdgcn_s_setprio(1); _Pragma("unroll") for (int m = 0; m < 4; ++m) _Pragma("unroll") for (int n = 0; n < 2; ++n) _Pragma("unroll") for (int k = 0; k < 2; ++k) \
;         acc[ai][bj][m][n] = __builtin_amdgcn_mfma_f32_16x16x32_bf16(Bt[n][k], At[m][k], acc[ai][bj][m][n], 0, 0, 0); __builtin_amdgcn_s_setprio(0); } while (0)
; #define PG8_WAIT_V(n) asm volatile("s_waitcnt vmcnt(" #n ")" ::: "memory")
; #define PG8_WAIT_L(n) asm volatile("s_waitcnt lgkmcnt(" #n ")" ::: "memory")
; #define PG8_BAR __builtin_amdgcn_s_barrier()
; #define PG8_SCHED __builtin_amdgcn_sched_barrier(0)
; template <class Epi, class Sched, bool ALIGN_EPI>
; __device__ __forceinline__ void gemm_phase(LAS unsigned char* lds, const Gemm g, const Sched& S, const Epi& E) {
;     ...
;             PG8_LDA(At, 1, 1); PG8_STAGE(PG8_SB(1, 0), b3, voffB); PG8_STAGE(PG8_SB(1, 1), b3 + hB, voffB); PG8_STAGE(PG8_SA(1, 0), a3, voffA);
;             PG8_WAIT_V(8); PG8_WAIT_L(0); PG8_BAR; PG8_MMA(1, 0, At, B0); PG8_MMA(1, 1, At, B1); PG8_BAR; PG8_SCHED;
;         }
	s_add_i32 s18, s33, s54
	v_lshl_add_u64 v[216:217], v[216:217], 0, s[22:23]
	s_mov_b32 m0, s18
	ds_read_b128 v[184:187], v153 offset:49152
	ds_read_b128 v[188:191], v153 offset:50176
	ds_read_b128 v[192:195], v153 offset:51200
	ds_read_b128 v[196:199], v153 offset:52224
	ds_read_b128 v[200:203], v153 offset:53248
	ds_read_b128 v[204:207], v153 offset:54272
	ds_read_b128 v[208:211], v153 offset:55296
	ds_read_b128 v[212:215], v153 offset:56320
	global_load_lds_dwordx4 v[216:217], off
	s_add_i32 m0, s18, 0x2000
	s_add_u32 s18, s40, 0x160080
	v_lshl_add_u64 v[216:217], v[218:219], 0, s[22:23]
	s_addc_u32 s19, s41, 0
	s_add_i32 s33, s47, s54
	global_load_lds_dwordx4 v[216:217], off
	s_mov_b32 m0, s33
	v_lshl_add_u64 v[216:217], s[18:19], 0, v[130:131]
	global_load_lds_dwordx4 v[216:217], off
	s_add_i32 m0, s33, 0x2000
	v_lshl_add_u64 v[216:217], s[18:19], 0, v[134:135]
	global_load_lds_dwordx4 v[216:217], off
	s_mov_b32 m0, s60
	v_lshl_add_u64 v[216:217], v[222:223], 0, s[22:23]
	global_load_lds_dwordx4 v[216:217], off
	s_mov_b32 m0, s61
	v_lshl_add_u64 v[216:217], v[224:225], 0, s[22:23]
	global_load_lds_dwordx4 v[216:217], off
	s_waitcnt vmcnt(8) lgkmcnt(0)
	s_barrier
	v_mfma_f32_16x16x32_bf16 v[60:63], v[144:147], v[184:187], v[60:63]
	v_mfma_f32_16x16x32_bf16 v[56:59], v[160:163], v[184:187], v[56:59]
	v_mfma_f32_16x16x32_bf16 v[44:47], v[144:147], v[192:195], v[44:47]
	v_mfma_f32_16x16x32_bf16 v[40:43], v[160:163], v[192:195], v[40:43]
	v_mfma_f32_16x16x32_bf16 v[28:31], v[144:147], v[200:203], v[28:31]
	v_mfma_f32_16x16x32_bf16 v[24:27], v[160:163], v[200:203], v[24:27]
	v_mfma_f32_16x16x32_bf16 v[12:15], v[144:147], v[208:211], v[12:15]
	v_mfma_f32_16x16x32_bf16 v[8:11], v[160:163], v[208:211], v[8:11]
	v_mfma_f32_16x16x32_bf16 v[60:63], v[156:159], v[188:191], v[60:63]
	v_mfma_f32_16x16x32_bf16 v[56:59], v[164:167], v[188:191], v[56:59]
	v_mfma_f32_16x16x32_bf16 v[44:47], v[156:159], v[196:199], v[44:47]
	v_mfma_f32_16x16x32_bf16 v[40:43], v[164:167], v[196:199], v[40:43]
	v_mfma_f32_16x16x32_bf16 v[28:31], v[156:159], v[204:207], v[28:31]
	v_mfma_f32_16x16x32_bf16 v[24:27], v[164:167], v[204:207], v[24:27]
	v_mfma_f32_16x16x32_bf16 v[12:15], v[156:159], v[212:215], v[12:15]
	v_mfma_f32_16x16x32_bf16 v[8:11], v[164:167], v[212:215], v[8:11]
	v_mfma_f32_16x16x32_bf16 v[52:55], v[168:171], v[184:187], v[52:55]
	v_mfma_f32_16x16x32_bf16 v[48:51], v[176:179], v[184:187], v[48:51]
	v_mfma_f32_16x16x32_bf16 v[36:39], v[168:171], v[192:195], v[36:39]
	v_mfma_f32_16x16x32_bf16 v[32:35], v[176:179], v[192:195], v[32:35]
	v_mfma_f32_16x16x32_bf16 v[20:23], v[168:171], v[200:203], v[20:23]
	v_mfma_f32_16x16x32_bf16 v[16:19], v[176:179], v[200:203], v[16:19]
	v_mfma_f32_16x16x32_bf16 v[4:7], v[168:171], v[208:211], v[4:7]
	v_mfma_f32_16x16x32_bf16 v[0:3], v[176:179], v[208:211], v[0:3]
	v_mfma_f32_16x16x32_bf16 v[52:55], v[172:175], v[188:191], v[52:55]
	v_mfma_f32_16x16x32_bf16 v[48:51], v[180:183], v[188:191], v[48:51]
	v_mfma_f32_16x16x32_bf16 v[36:39], v[172:175], v[196:199], v[36:39]
	v_mfma_f32_16x16x32_bf16 v[32:35], v[180:183], v[196:199], v[32:35]
	v_mfma_f32_16x16x32_bf16 v[20:23], v[172:175], v[204:207], v[20:23]
	v_mfma_f32_16x16x32_bf16 v[16:19], v[180:183], v[204:207], v[16:19]
	v_mfma_f32_16x16x32_bf16 v[4:7], v[172:175], v[212:215], v[4:7]
	v_mfma_f32_16x16x32_bf16 v[0:3], v[180:183], v[212:215], v[0:3]
	s_barrier
	s_add_i32 s46, s46, 2
	s_add_u32 s38, s38, 0x100
	s_addc_u32 s39, s39, 0
	s_add_u32 s44, s44, 0x100
	s_addc_u32 s45, s45, 0
	s_cmpk_gt_u32 s46, 0x55
	s_cbranch_scc0 .LBB0_1234
	s_and_b64 vcc, exec, s[24:25]
	s_cbranch_vccz .LBB0_1237
	s_barrier

; #define PG8_STAGE(bufoff, gbase, voff) do { _Pragma("unroll") for (int _i = 0; _i < 2; ++_i) \
;         __builtin_amdgcn_global_load_lds((const unsigned*)((const char*)(gbase) + (voff)[_i]), (LAS unsigned*)(lds + (bufoff) + ldsw + _i * 8192), 16, 0, 0); } while (0)
; #define PG8_LDA(dst, b, h) do { _Pragma("unroll") for (int m = 0; m < 4; ++m) _Pragma("unroll") for (int k = 0; k < 2; ++k) dst[m][k] = *(const LAS bf16x8*)(lds + PG8_SA(b, h) + aoff + m * 2048 + k * 1024); } while (0)
; #define PG8_LDB(dst, b, h) do { _Pragma("unroll") for (int n = 0; n < 2; ++n) _Pragma("unroll") for (int k = 0; k < 2; ++k) dst[n][k] = *(const LAS bf16x8*)(lds + PG8_SB(b, h) + boff + n * 2048 + k * 1024); } while (0)
; #define PG8_MMA(ai, bj, At, Bt) do { __builtin_amdgcn_s_setprio(1); _Pragma("unroll") for (int m = 0; m < 4; ++m) _Pragma("unroll") for (int n = 0; n < 2; ++n) _Pragma("unroll") for (int k = 0; k < 2; ++k) \
;         acc[ai][bj][m][n] = __builtin_amdgcn_mfma_f32_16x16x32_bf16(Bt[n][k], At[m][k], acc[ai][bj][m][n], 0, 0, 0); __builtin_amdgcn_s_setprio(0); } while (0)
; #define PG8_WAIT_V(n) asm volatile("s_waitcnt vmcnt(" #n ")" ::: "memory")
; #define PG8_WAIT_L(n) asm volatile("s_waitcnt lgkmcnt(" #n ")" ::: "memory")
; #define PG8_BAR __builtin_amdgcn_s_barrier()
; #define PG8_SCHED __builtin_amdgcn_sched_barrier(0)
; template <class Epi, class Sched, bool ALIGN_EPI>
; __device__ __forceinline__ void gemm_phase(LAS unsigned char* lds, const Gemm g, const Sched& S, const Epi& E) {
;     ...
;         for (int t = 0; t < nt; t += 2) {
;             const bool last = (t == nt - 2);
;             const char* a1 = cA + (size_t)(t + 1) * kstep;
;             const char* a2 = last ? nA : cA + (size_t)(t + 2) * kstep; const char* b2 = last ? nB : cB + (size_t)(t + 2) * kstep;
;             const char* a3 = a2 + kstep; const char* b3 = b2 + kstep;
;             PG8_LDB(B0, 0, 0); PG8_LDB(B1, 0, 1); PG8_SCHED; PG8_LDA(At, 0, 0); PG8_STAGE(PG8_SA(1, 1), a1 + hA, voffA);
;             PG8_WAIT_V(8); PG8_WAIT_L(0); PG8_BAR; PG8_MMA(0, 0, At, B0); PG8_MMA(0, 1, At, B1); PG8_BAR; PG8_SCHED;
;             PG8_LDA(At, 0, 1); PG8_STAGE(PG8_SB(0, 0), b2, voffB); PG8_STAGE(PG8_SB(0, 1), b2 + hB, voffB); PG8_STAGE(PG8_SA(0, 0), a2, voffA);
;             PG8_WAIT_V(8); PG8_WAIT_L(0); PG8_BAR; PG8_MMA(1, 0, At, B0); PG8_MMA(1, 1, At, B1); PG8_BAR; PG8_SCHED;
.LBB0_1278:
	ds_read_b128 v[146:149], v186
	ds_read_b128 v[150:153], v186 offset:1024
	ds_read_b128 v[154:157], v186 offset:2048
	ds_read_b128 v[192:195], v186 offset:3072
	ds_read_b128 v[196:199], v187
	ds_read_b128 v[200:203], v187 offset:1024
	ds_read_b128 v[204:207], v187 offset:2048
	ds_read_b128 v[208:211], v187 offset:3072
	s_add_u32 s18, s54, 0xffea0080
	s_addc_u32 s19, s55, -1
	s_cmpk_eq_i32 s46, 0x54
	s_cselect_b32 s59, s11, s19
	s_cselect_b32 s58, s39, s18
	s_cselect_b32 s57, s41, s45
	s_cselect_b32 s56, s78, s44
	v_lshl_add_u64 v[158:159], s[54:55], 0, v[138:139]
	s_add_i32 m0, s61, 0xc000
	ds_read_b128 v[212:215], v188
	ds_read_b128 v[216:219], v188 offset:1024
	ds_read_b128 v[222:225], v188 offset:2048
	ds_read_b128 v[226:229], v188 offset:3072
	ds_read_b128 v[230:233], v188 offset:4096
	ds_read_b128 v[234:237], v188 offset:5120
	ds_read_b128 v[238:241], v188 offset:6144
	ds_read_b128 v[242:245], v188 offset:7168
	global_load_lds_dwordx4 v[158:159], off
	s_add_i32 m0, s61, 0xe000
	v_lshl_add_u64 v[158:159], s[54:55], 0, v[140:141]
	global_load_lds_dwordx4 v[158:159], off
	s_waitcnt vmcnt(8) lgkmcnt(0)
	s_barrier
	v_mfma_f32_16x16x32_bf16 v[124:127], v[146:149], v[212:215], v[124:127]
	v_mfma_f32_16x16x32_bf16 v[120:123], v[154:157], v[212:215], v[120:123]
	v_mfma_f32_16x16x32_bf16 v[108:111], v[146:149], v[222:225], v[108:111]
	v_mfma_f32_16x16x32_bf16 v[104:107], v[154:157], v[222:225], v[104:107]
	v_mfma_f32_16x16x32_bf16 v[92:95], v[146:149], v[230:233], v[92:95]
	v_mfma_f32_16x16x32_bf16 v[88:91], v[154:157], v[230:233], v[88:91]
	v_mfma_f32_16x16x32_bf16 v[76:79], v[146:149], v[238:241], v[76:79]
	v_mfma_f32_16x16x32_bf16 v[72:75], v[154:157], v[238:241], v[72:75]
	v_mfma_f32_16x16x32_bf16 v[124:127], v[150:153], v[216:219], v[124:127]
	v_mfma_f32_16x16x32_bf16 v[120:123], v[192:195], v[216:219], v[120:123]
	v_mfma_f32_16x16x32_bf16 v[108:111], v[150:153], v[226:229], v[108:111]
	v_mfma_f32_16x16x32_bf16 v[104:107], v[192:195], v[226:229], v[104:107]
	v_mfma_f32_16x16x32_bf16 v[92:95], v[150:153], v[234:237], v[92:95]
	v_mfma_f32_16x16x32_bf16 v[88:91], v[192:195], v[234:237], v[88:91]
	v_mfma_f32_16x16x32_bf16 v[76:79], v[150:153], v[242:245], v[76:79]
	v_mfma_f32_16x16x32_bf16 v[72:75], v[192:195], v[242:245], v[72:75]
	v_mfma_f32_16x16x32_bf16 v[116:119], v[196:199], v[212:215], v[116:119]
	v_mfma_f32_16x16x32_bf16 v[112:115], v[204:207], v[212:215], v[112:115]
	v_mfma_f32_16x16x32_bf16 v[100:103], v[196:199], v[222:225], v[100:103]
	v_mfma_f32_16x16x32_bf16 v[96:99], v[204:207], v[222:225], v[96:99]
	v_mfma_f32_16x16x32_bf16 v[84:87], v[196:199], v[230:233], v[84:87]
	v_mfma_f32_16x16x32_bf16 v[80:83], v[204:207], v[230:233], v[80:83]
	v_mfma_f32_16x16x32_bf16 v[68:71], v[196:199], v[238:241], v[68:71]
	v_mfma_f32_16x16x32_bf16 v[64:67], v[204:207], v[238:241], v[64:67]
	v_mfma_f32_16x16x32_bf16 v[116:119], v[200:203], v[216:219], v[116:119]
	v_mfma_f32_16x16x32_bf16 v[112:115], v[208:211], v[216:219], v[112:115]
	v_mfma_f32_16x16x32_bf16 v[100:103], v[200:203], v[226:229], v[100:103]
	v_mfma_f32_16x16x32_bf16 v[96:99], v[208:211], v[226:229], v[96:99]
	v_mfma_f32_16x16x32_bf16 v[84:87], v[200:203], v[234:237], v[84:87]
	v_mfma_f32_16x16x32_bf16 v[80:83], v[208:211], v[234:237], v[80:83]
	v_mfma_f32_16x16x32_bf16 v[68:71], v[200:203], v[242:245], v[68:71]
	v_mfma_f32_16x16x32_bf16 v[64:67], v[208:211], v[242:245], v[64:67]
	s_barrier
	s_add_i32 s18, s71, s60
	v_lshl_add_u64 v[158:159], s[56:57], 0, v[130:131]
	s_mov_b32 m0, s18
	ds_read_b128 v[212:215], v188 offset:16384
	ds_read_b128 v[216:219], v188 offset:17408
	ds_read_b128 v[222:225], v188 offset:18432
	ds_read_b128 v[226:229], v188 offset:19456
	ds_read_b128 v[230:233], v188 offset:20480
	ds_read_b128 v[234:237], v188 offset:21504
	ds_read_b128 v[238:241], v188 offset:22528
	ds_read_b128 v[242:245], v188 offset:23552
	global_load_lds_dwordx4 v[158:159], off
	s_add_i32 m0, s18, 0x2000
	s_add_u32 s18, s56, 0x160000
	v_lshl_add_u64 v[246:247], s[56:57], 0, v[134:135]
	s_addc_u32 s19, s57, 0
	s_add_i32 s33, s72, s60
	global_load_lds_dwordx4 v[246:247], off
	v_lshl_add_u64 v[248:249], s[18:19], 0, v[130:131]
	s_mov_b32 m0, s33
	v_lshl_add_u64 v[250:251], s[58:59], 0, v[132:133]
	global_load_lds_dwordx4 v[248:249], off
	s_add_i32 m0, s33, 0x2000
	v_lshl_add_u64 v[248:249], s[18:19], 0, v[134:135]
	global_load_lds_dwordx4 v[248:249], off
	s_mov_b32 m0, s61
	v_lshl_add_u64 v[248:249], s[58:59], 0, v[128:129]
	global_load_lds_dwordx4 v[248:249], off
	s_mov_b32 m0, s62
	s_nop 0
	global_load_lds_dwordx4 v[250:251], off
	s_waitcnt vmcnt(8) lgkmcnt(0)
	s_barrier
; #define PG8_STAGE(bufoff, gbase, voff) do { _Pragma("unroll") for (int _i = 0; _i < 2; ++_i) \
;         __builtin_amdgcn_global_load_lds((const unsigned*)((const char*)(gbase) + (voff)[_i]), (LAS unsigned*)(lds + (bufoff) + ldsw + _i * 8192), 16, 0, 0); } while (0)
; #define PG8_LDA(dst, b, h) do { _Pragma("unroll") for (int m = 0; m < 4; ++m) _Pragma("unroll") for (int k = 0; k < 2; ++k) dst[m][k] = *(const LAS bf16x8*)(lds + PG8_SA(b, h) + aoff + m * 2048 + k * 1024); } while (0)
; #define PG8_LDB(dst, b, h) do { _Pragma("unroll") for (int n = 0; n < 2; ++n) _Pragma("unroll") for (int k = 0; k < 2; ++k) dst[n][k] = *(const LAS bf16x8*)(lds + PG8_SB(b, h) + boff + n * 2048 + k * 1024); } while (0)
; #define PG8_MMA(ai, bj, At, Bt) do { __builtin_amdgcn_s_setprio(1); _Pragma("unroll") for (int m = 0; m < 4; ++m) _Pragma("unroll") for (int n = 0; n < 2; ++n) _Pragma("unroll") for (int k = 0; k < 2; ++k) \
;         acc[ai][bj][m][n] = __builtin_amdgcn_mfma_f32_16x16x32_bf16(Bt[n][k], At[m][k], acc[ai][bj][m][n], 0, 0, 0); __builtin_amdgcn_s_setprio(0); } while (0)
; #define PG8_WAIT_V(n) asm volatile("s_waitcnt vmcnt(" #n ")" ::: "memory")
; #define PG8_WAIT_L(n) asm volatile("s_waitcnt lgkmcnt(" #n ")" ::: "memory")
; #define PG8_BAR __builtin_amdgcn_s_barrier()
; #define PG8_SCHED __builtin_amdgcn_sched_barrier(0)
; template <class Epi, class Sched, bool ALIGN_EPI>
; __device__ __forceinline__ void gemm_phase(LAS unsigned char* lds, const Gemm g, const Sched& S, const Epi& E) {
;     ...
;             PG8_WAIT_V(8); PG8_WAIT_L(0); PG8_BAR; PG8_MMA(1, 0, At, B0); PG8_MMA(1, 1, At, B1); PG8_BAR; PG8_SCHED;
;             PG8_LDB(B0, 1, 0); PG8_LDB(B1, 1, 1); PG8_SCHED; PG8_LDA(At, 1, 0); PG8_STAGE(PG8_SA(0, 1), a2 + hA, voffA);
;             PG8_WAIT_V(8); PG8_WAIT_L(0); PG8_BAR; PG8_MMA(0, 0, At, B0); PG8_MMA(0, 1, At, B1); PG8_BAR; PG8_SCHED;
;             PG8_LDA(At, 1, 1); PG8_STAGE(PG8_SB(1, 0), b3, voffB); PG8_STAGE(PG8_SB(1, 1), b3 + hB, voffB); PG8_STAGE(PG8_SA(1, 0), a3, voffA);
	v_mfma_f32_16x16x32_bf16 v[60:63], v[146:149], v[212:215], v[60:63]
	v_mfma_f32_16x16x32_bf16 v[56:59], v[154:157], v[212:215], v[56:59]
	v_mfma_f32_16x16x32_bf16 v[44:47], v[146:149], v[222:225], v[44:47]
	v_mfma_f32_16x16x32_bf16 v[40:43], v[154:157], v[222:225], v[40:43]
	v_mfma_f32_16x16x32_bf16 v[28:31], v[146:149], v[230:233], v[28:31]
	v_mfma_f32_16x16x32_bf16 v[24:27], v[154:157], v[230:233], v[24:27]
	v_mfma_f32_16x16x32_bf16 v[12:15], v[146:149], v[238:241], v[12:15]
	v_mfma_f32_16x16x32_bf16 v[8:11], v[154:157], v[238:241], v[8:11]
	v_mfma_f32_16x16x32_bf16 v[60:63], v[150:153], v[216:219], v[60:63]
	v_mfma_f32_16x16x32_bf16 v[56:59], v[192:195], v[216:219], v[56:59]
	v_mfma_f32_16x16x32_bf16 v[44:47], v[150:153], v[226:229], v[44:47]
	v_mfma_f32_16x16x32_bf16 v[40:43], v[192:195], v[226:229], v[40:43]
	v_mfma_f32_16x16x32_bf16 v[28:31], v[150:153], v[234:237], v[28:31]
	v_mfma_f32_16x16x32_bf16 v[24:27], v[192:195], v[234:237], v[24:27]
	v_mfma_f32_16x16x32_bf16 v[12:15], v[150:153], v[242:245], v[12:15]
	v_mfma_f32_16x16x32_bf16 v[8:11], v[192:195], v[242:245], v[8:11]
	v_mfma_f32_16x16x32_bf16 v[52:55], v[196:199], v[212:215], v[52:55]
	v_mfma_f32_16x16x32_bf16 v[48:51], v[204:207], v[212:215], v[48:51]
	v_mfma_f32_16x16x32_bf16 v[36:39], v[196:199], v[222:225], v[36:39]
	v_mfma_f32_16x16x32_bf16 v[32:35], v[204:207], v[222:225], v[32:35]
	v_mfma_f32_16x16x32_bf16 v[20:23], v[196:199], v[230:233], v[20:23]
	v_mfma_f32_16x16x32_bf16 v[16:19], v[204:207], v[230:233], v[16:19]
	v_mfma_f32_16x16x32_bf16 v[4:7], v[196:199], v[238:241], v[4:7]
	v_mfma_f32_16x16x32_bf16 v[0:3], v[204:207], v[238:241], v[0:3]
	v_mfma_f32_16x16x32_bf16 v[52:55], v[200:203], v[216:219], v[52:55]
	v_mfma_f32_16x16x32_bf16 v[48:51], v[208:211], v[216:219], v[48:51]
	v_mfma_f32_16x16x32_bf16 v[36:39], v[200:203], v[226:229], v[36:39]
	v_mfma_f32_16x16x32_bf16 v[32:35], v[208:211], v[226:229], v[32:35]
	v_mfma_f32_16x16x32_bf16 v[20:23], v[200:203], v[234:237], v[20:23]
	v_mfma_f32_16x16x32_bf16 v[16:19], v[208:211], v[234:237], v[16:19]
	v_mfma_f32_16x16x32_bf16 v[4:7], v[200:203], v[242:245], v[4:7]
	v_mfma_f32_16x16x32_bf16 v[0:3], v[208:211], v[242:245], v[0:3]
	s_barrier
	s_add_i32 s33, 0, 0x18000
	v_add_u32_e32 v136, s33, v163
	s_add_i32 s47, 0, 0x1c000
	ds_read_b128 v[146:149], v136
	ds_read_b128 v[150:153], v136 offset:1024
	ds_read_b128 v[154:157], v136 offset:2048
	ds_read_b128 v[192:195], v136 offset:3072
	v_add_u32_e32 v136, s47, v163
	ds_read_b128 v[196:199], v136
	ds_read_b128 v[200:203], v136 offset:1024
	ds_read_b128 v[204:207], v136 offset:2048
	ds_read_b128 v[208:211], v136 offset:3072
	s_add_u32 s18, s58, 0x160000
	s_addc_u32 s19, s59, 0
	s_mov_b32 m0, s63
	v_lshl_add_u64 v[252:253], s[18:19], 0, v[128:129]
	ds_read_b128 v[212:215], v188 offset:32768
	ds_read_b128 v[216:219], v188 offset:33792
	ds_read_b128 v[222:225], v188 offset:34816
	ds_read_b128 v[226:229], v188 offset:35840
	ds_read_b128 v[230:233], v188 offset:36864
	ds_read_b128 v[234:237], v188 offset:37888
	ds_read_b128 v[238:241], v188 offset:38912
	ds_read_b128 v[242:245], v188 offset:39936
	global_load_lds_dwordx4 v[252:253], off
	s_mov_b32 m0, s64
	v_lshl_add_u64 v[252:253], s[18:19], 0, v[132:133]
	global_load_lds_dwordx4 v[252:253], off
	s_waitcnt vmcnt(8) lgkmcnt(0)
	s_barrier
	v_mfma_f32_16x16x32_bf16 v[124:127], v[146:149], v[212:215], v[124:127]
	v_mfma_f32_16x16x32_bf16 v[120:123], v[154:157], v[212:215], v[120:123]
	v_mfma_f32_16x16x32_bf16 v[108:111], v[146:149], v[222:225], v[108:111]
	v_mfma_f32_16x16x32_bf16 v[104:107], v[154:157], v[222:225], v[104:107]
	v_mfma_f32_16x16x32_bf16 v[92:95], v[146:149], v[230:233], v[92:95]
	v_mfma_f32_16x16x32_bf16 v[88:91], v[154:157], v[230:233], v[88:91]
	v_mfma_f32_16x16x32_bf16 v[76:79], v[146:149], v[238:241], v[76:79]
	v_mfma_f32_16x16x32_bf16 v[72:75], v[154:157], v[238:241], v[72:75]
	v_mfma_f32_16x16x32_bf16 v[124:127], v[150:153], v[216:219], v[124:127]
	v_mfma_f32_16x16x32_bf16 v[120:123], v[192:195], v[216:219], v[120:123]
	v_mfma_f32_16x16x32_bf16 v[108:111], v[150:153], v[226:229], v[108:111]
	v_mfma_f32_16x16x32_bf16 v[104:107], v[192:195], v[226:229], v[104:107]
	v_mfma_f32_16x16x32_bf16 v[92:95], v[150:153], v[234:237], v[92:95]
	v_mfma_f32_16x16x32_bf16 v[88:91], v[192:195], v[234:237], v[88:91]
	v_mfma_f32_16x16x32_bf16 v[76:79], v[150:153], v[242:245], v[76:79]
	v_mfma_f32_16x16x32_bf16 v[72:75], v[192:195], v[242:245], v[72:75]
	v_mfma_f32_16x16x32_bf16 v[116:119], v[196:199], v[212:215], v[116:119]
	v_mfma_f32_16x16x32_bf16 v[112:115], v[204:207], v[212:215], v[112:115]
	v_mfma_f32_16x16x32_bf16 v[100:103], v[196:199], v[222:225], v[100:103]
	v_mfma_f32_16x16x32_bf16 v[96:99], v[204:207], v[222:225], v[96:99]
	v_mfma_f32_16x16x32_bf16 v[84:87], v[196:199], v[230:233], v[84:87]
	v_mfma_f32_16x16x32_bf16 v[80:83], v[204:207], v[230:233], v[80:83]
	v_mfma_f32_16x16x32_bf16 v[68:71], v[196:199], v[238:241], v[68:71]
	v_mfma_f32_16x16x32_bf16 v[64:67], v[204:207], v[238:241], v[64:67]
	v_mfma_f32_16x16x32_bf16 v[116:119], v[200:203], v[216:219], v[116:119]
	v_mfma_f32_16x16x32_bf16 v[112:115], v[208:211], v[216:219], v[112:115]
	v_mfma_f32_16x16x32_bf16 v[100:103], v[200:203], v[226:229], v[100:103]
	v_mfma_f32_16x16x32_bf16 v[96:99], v[208:211], v[226:229], v[96:99]
	v_mfma_f32_16x16x32_bf16 v[84:87], v[200:203], v[234:237], v[84:87]
	v_mfma_f32_16x16x32_bf16 v[80:83], v[208:211], v[234:237], v[80:83]
	v_mfma_f32_16x16x32_bf16 v[68:71], v[200:203], v[242:245], v[68:71]
	v_mfma_f32_16x16x32_bf16 v[64:67], v[208:211], v[242:245], v[64:67]
	s_barrier
; #define PG8_STAGE(bufoff, gbase, voff) do { _Pragma("unroll") for (int _i = 0; _i < 2; ++_i) \
;         __builtin_amdgcn_global_load_lds((const unsigned*)((const char*)(gbase) + (voff)[_i]), (LAS unsigned*)(lds + (bufoff) + ldsw + _i * 8192), 16, 0, 0); } while (0)
; #define PG8_LDA(dst, b, h) do { _Pragma("unroll") for (int m = 0; m < 4; ++m) _Pragma("unroll") for (int k = 0; k < 2; ++k) dst[m][k] = *(const LAS bf16x8*)(lds + PG8_SA(b, h) + aoff + m * 2048 + k * 1024); } while (0)
; #define PG8_MMA(ai, bj, At, Bt) do { __builtin_amdgcn_s_setprio(1); _Pragma("unroll") for (int m = 0; m < 4; ++m) _Pragma("unroll") for (int n = 0; n < 2; ++n) _Pragma("unroll") for (int k = 0; k < 2; ++k) \
;         acc[ai][bj][m][n] = __builtin_amdgcn_mfma_f32_16x16x32_bf16(Bt[n][k], At[m][k], acc[ai][bj][m][n], 0, 0, 0); __builtin_amdgcn_s_setprio(0); } while (0)
; #define PG8_WAIT_V(n) asm volatile("s_waitcnt vmcnt(" #n ")" ::: "memory")
; #define PG8_WAIT_L(n) asm volatile("s_waitcnt lgkmcnt(" #n ")" ::: "memory")
; #define PG8_BAR __builtin_amdgcn_s_barrier()
; #define PG8_SCHED __builtin_amdgcn_sched_barrier(0)
; template <class Epi, class Sched, bool ALIGN_EPI>
; __device__ __forceinline__ void gemm_phase(LAS unsigned char* lds, const Gemm g, const Sched& S, const Epi& E) {
;     ...
;             PG8_LDA(At, 1, 1); PG8_STAGE(PG8_SB(1, 0), b3, voffB); PG8_STAGE(PG8_SB(1, 1), b3 + hB, voffB); PG8_STAGE(PG8_SA(1, 0), a3, voffA);
;             PG8_WAIT_V(8); PG8_WAIT_L(0); PG8_BAR; PG8_MMA(1, 0, At, B0); PG8_MMA(1, 1, At, B1); PG8_BAR; PG8_SCHED;
;         }
	s_add_i32 s18, s33, s60
	v_lshl_add_u64 v[158:159], v[158:159], 0, s[30:31]
	s_mov_b32 m0, s18
	ds_read_b128 v[212:215], v188 offset:49152
	ds_read_b128 v[216:219], v188 offset:50176
	ds_read_b128 v[222:225], v188 offset:51200
	ds_read_b128 v[226:229], v188 offset:52224
	ds_read_b128 v[230:233], v188 offset:53248
	ds_read_b128 v[234:237], v188 offset:54272
	ds_read_b128 v[238:241], v188 offset:55296
	ds_read_b128 v[242:245], v188 offset:56320
	global_load_lds_dwordx4 v[158:159], off
	s_add_i32 m0, s18, 0x2000
	s_add_u32 s18, s56, 0x160080
	v_lshl_add_u64 v[158:159], v[246:247], 0, s[30:31]
	s_addc_u32 s19, s57, 0
	s_add_i32 s33, s47, s60
	global_load_lds_dwordx4 v[158:159], off
	s_mov_b32 m0, s33
	v_lshl_add_u64 v[158:159], s[18:19], 0, v[130:131]
	global_load_lds_dwordx4 v[158:159], off
	s_add_i32 m0, s33, 0x2000
	v_lshl_add_u64 v[158:159], s[18:19], 0, v[134:135]
	global_load_lds_dwordx4 v[158:159], off
	s_mov_b32 m0, s68
	v_lshl_add_u64 v[158:159], v[248:249], 0, s[30:31]
	global_load_lds_dwordx4 v[158:159], off
	s_mov_b32 m0, s69
	v_lshl_add_u64 v[158:159], v[250:251], 0, s[30:31]
	global_load_lds_dwordx4 v[158:159], off
	s_waitcnt vmcnt(8) lgkmcnt(0)
	s_barrier
	v_mfma_f32_16x16x32_bf16 v[60:63], v[146:149], v[212:215], v[60:63]
	v_mfma_f32_16x16x32_bf16 v[56:59], v[154:157], v[212:215], v[56:59]
	v_mfma_f32_16x16x32_bf16 v[44:47], v[146:149], v[222:225], v[44:47]
	v_mfma_f32_16x16x32_bf16 v[40:43], v[154:157], v[222:225], v[40:43]
	v_mfma_f32_16x16x32_bf16 v[28:31], v[146:149], v[230:233], v[28:31]
	v_mfma_f32_16x16x32_bf16 v[24:27], v[154:157], v[230:233], v[24:27]
	v_mfma_f32_16x16x32_bf16 v[12:15], v[146:149], v[238:241], v[12:15]
	v_mfma_f32_16x16x32_bf16 v[8:11], v[154:157], v[238:241], v[8:11]
	v_mfma_f32_16x16x32_bf16 v[60:63], v[150:153], v[216:219], v[60:63]
	v_mfma_f32_16x16x32_bf16 v[56:59], v[192:195], v[216:219], v[56:59]
	v_mfma_f32_16x16x32_bf16 v[44:47], v[150:153], v[226:229], v[44:47]
	v_mfma_f32_16x16x32_bf16 v[40:43], v[192:195], v[226:229], v[40:43]
	v_mfma_f32_16x16x32_bf16 v[28:31], v[150:153], v[234:237], v[28:31]
	v_mfma_f32_16x16x32_bf16 v[24:27], v[192:195], v[234:237], v[24:27]
	v_mfma_f32_16x16x32_bf16 v[12:15], v[150:153], v[242:245], v[12:15]
	v_mfma_f32_16x16x32_bf16 v[8:11], v[192:195], v[242:245], v[8:11]
	v_mfma_f32_16x16x32_bf16 v[52:55], v[196:199], v[212:215], v[52:55]
	v_mfma_f32_16x16x32_bf16 v[48:51], v[204:207], v[212:215], v[48:51]
	v_mfma_f32_16x16x32_bf16 v[36:39], v[196:199], v[222:225], v[36:39]
	v_mfma_f32_16x16x32_bf16 v[32:35], v[204:207], v[222:225], v[32:35]
	v_mfma_f32_16x16x32_bf16 v[20:23], v[196:199], v[230:233], v[20:23]
	v_mfma_f32_16x16x32_bf16 v[16:19], v[204:207], v[230:233], v[16:19]
	v_mfma_f32_16x16x32_bf16 v[4:7], v[196:199], v[238:241], v[4:7]
	v_mfma_f32_16x16x32_bf16 v[0:3], v[204:207], v[238:241], v[0:3]
	v_mfma_f32_16x16x32_bf16 v[52:55], v[200:203], v[216:219], v[52:55]
	v_mfma_f32_16x16x32_bf16 v[48:51], v[208:211], v[216:219], v[48:51]
	v_mfma_f32_16x16x32_bf16 v[36:39], v[200:203], v[226:229], v[36:39]
	v_mfma_f32_16x16x32_bf16 v[32:35], v[208:211], v[226:229], v[32:35]
	v_mfma_f32_16x16x32_bf16 v[20:23], v[200:203], v[234:237], v[20:23]
	v_mfma_f32_16x16x32_bf16 v[16:19], v[208:211], v[234:237], v[16:19]
	v_mfma_f32_16x16x32_bf16 v[4:7], v[200:203], v[242:245], v[4:7]
	v_mfma_f32_16x16x32_bf16 v[0:3], v[208:211], v[242:245], v[0:3]
	s_barrier
	s_add_i32 s46, s46, 2
	s_add_u32 s54, s54, 0x100
	s_addc_u32 s55, s55, 0
	s_add_u32 s44, s44, 0x100
	s_addc_u32 s45, s45, 0
	s_cmpk_gt_u32 s46, 0x55
	s_cbranch_scc0 .LBB0_1278
	s_and_b64 vcc, exec, s[36:37]
	s_cbranch_vccz .LBB0_1281
	s_barrier
